# v6 + one static s_setprio 1 for waves 4-7 per GEMM phase instead of per-MMA-block priority flips
# speedup vs baseline: 1.0154x; 1.0147x over previous
; #define PG8_STAGE(bufoff, gbase, voff) do { _Pragma("unroll") for (int _i = 0; _i < 2; ++_i) \
;         __builtin_amdgcn_global_load_lds((const unsigned*)((const char*)(gbase) + (voff)[_i]), (LAS unsigned*)(lds + (bufoff) + ldsw + _i * 8192), 16, 0, 0); } while (0)
; #define PG8_WAIT_V(n) asm volatile("s_waitcnt vmcnt(" #n ")" ::: "memory")
; #define PG8_BAR __builtin_amdgcn_s_barrier()
; template <class Epi, class Ptrs>
; __device__ __forceinline__ void gemm_phase(LAS unsigned char* lds, const int K, const StaticOrder& S, const Ptrs& P, const Epi& E) {
;     const int tid = threadIdx.x, wid = __builtin_amdgcn_readfirstlane(tid >> 6), lane = tid & 63, wr = wid >> 2, wc = wid & 3, fr = lane & 15, fq = lane >> 4;
;     const int nt = K / BK;
;     unsigned voffA[2], voffB[2];
; #pragma unroll
;     for (int i = 0; i < 2; ++i) { int R, C; stage_rc(tid * 16 + i * 8192, R, C); const int Rb = (R & ~31) + perm32(R & 31);
;         voffA[i] = (unsigned)(R * K + C) * 2u; voffB[i] = (unsigned)(Rb * K + C) * 2u; }
;     const size_t kstep = (size_t)(BK * 2);
;     const size_t hstep = (size_t)HALF * K * 2;
;     const unsigned ldsw = (unsigned)wid * 1024u;
;     const int aoff = lds_byte(wr * 64 + fr, fq * 8), boff = lds_byte(wc * 32 + fr, fq * 8);
;     ...
;     PG8_STAGE(PG8_SB(0, 0), cB, voffB); PG8_STAGE(PG8_SA(0, 0), cA, voffA); PG8_STAGE(PG8_SB(0, 1), cB + hstep, voffB); PG8_STAGE(PG8_SA(0, 1), cA + hstep, voffA);
;     if (wr == 1) PG8_BAR;
;     PG8_WAIT_V(4); PG8_BAR;
;     PG8_STAGE(PG8_SB(1, 0), cB + kstep, voffB); PG8_STAGE(PG8_SA(1, 0), cA + kstep, voffA); PG8_STAGE(PG8_SB(1, 1), cB + hstep + kstep, voffB);
;     PG8_WAIT_V(6); PG8_BAR;
.LBB0_120:
	s_add_u32 s4, s28, 0x35000000
	s_addc_u32 s5, s29, 0
	s_mov_b64 s[58:59], 0x80
	v_writelane_b32 v254, s4, 0
	v_lshl_add_u64 v[6:7], v[6:7], 0, s[58:59]
	s_waitcnt vmcnt(4)
	s_barrier
	v_writelane_b32 v254, s5, 1
	s_add_u32 s4, s28, 0x26000000
	s_addc_u32 s5, s29, 0
	s_add_u32 s42, s28, 0x32000000
	s_addc_u32 s43, s29, 0
	s_add_u32 s44, s28, 0x2000000
	s_addc_u32 s45, s29, 0
	s_add_u32 s48, s26, 0xc000000
	s_addc_u32 s49, s27, 0
	s_add_u32 s54, s28, 0x3e000000
	s_addc_u32 s55, s29, 0
	s_add_u32 s56, s28, 0xe000000
	s_addc_u32 s57, s29, 0
	s_lshl_b32 s1, s1, 5
	s_and_b32 s88, s1, 0x60
	s_add_i32 m0, s67, 0x18000
	v_writelane_b32 v254, s4, 2
	s_ashr_i32 s86, s3, 31
	s_ashr_i32 s87, s2, 31
	s_lshl_b32 s20, s0, 13
	s_lshl_b32 s1, s88, 7
	global_load_lds_dwordx4 v[6:7], off
	v_lshl_add_u64 v[4:5], v[4:5], 0, s[58:59]
	s_add_i32 m0, s67, 0x1a000
	s_add_i32 s89, s67, 0x8000
	s_add_i32 s90, s67, 0xa000
	v_writelane_b32 v254, s5, 3
	global_load_lds_dwordx4 v[4:5], off
	v_lshl_add_u64 v[2:3], v[2:3], 0, s[58:59]
	s_mov_b32 m0, s89
	s_add_u32 s4, s78, 0x40080
	global_load_lds_dwordx4 v[2:3], off
	v_lshl_add_u64 v[0:1], v[0:1], 0, s[58:59]
	s_mov_b32 m0, s90
	s_addc_u32 s5, s79, 0
	global_load_lds_dwordx4 v[0:1], off
	s_add_i32 m0, s67, 0x1c000
	v_lshl_add_u64 v[0:1], s[4:5], 0, v[134:135]
	global_load_lds_dwordx4 v[0:1], off
	v_lshl_add_u64 v[0:1], s[4:5], 0, v[138:139]
	s_add_i32 m0, s67, 0x1e000
	v_lshlrev_b32_e32 v2, 6, v208
	global_load_lds_dwordx4 v[0:1], off
	v_and_b32_e32 v0, 15, v208
	v_lshlrev_b32_e32 v1, 1, v130
	s_movk_i32 s4, 0x3c0
	v_lshlrev_b32_e32 v3, 2, v208
	v_and_or_b32 v2, v2, s4, v1
	v_and_b32_e32 v3, 32, v3
	v_cmp_eq_u32_e64 s[10:11], 0, v0
	v_lshl_or_b32 v129, s0, 6, v0
	v_lshl_or_b32 v0, v0, 6, v1
	v_lshlrev_b32_e32 v1, 8, v208
	v_bitop3_b32 v131, s1, v2, v3 bitop3:0xf6
	v_and_b32_e32 v1, 0x38000, v1
	v_lshlrev_b32_e32 v2, 11, v10
	v_or3_b32 v1, v8, v1, v2
	v_add_u32_e32 v142, v1, v9
	v_lshlrev_b32_e32 v1, 4, v11
	s_waitcnt vmcnt(6)
	v_and_b32_e32 v1, 0x78000, v1
	v_bitop3_b32 v0, v0, s20, v3 bitop3:0xde
	v_or3_b32 v1, v8, v1, v2
	s_add_i32 s91, 0, 0x10000
	s_add_i32 s92, 0, 0x14000
	v_or_b32_e32 v204, s88, v130
	v_mov_b32_e32 v143, v141
	v_add_u32_e32 v144, v1, v9
	v_mov_b32_e32 v145, v141
	v_mov_b64_e32 v[146:147], 0x2100
	v_mov_b64_e32 v[148:149], 0x20ff
	v_add_u32_e32 v205, s91, v131
	v_add_u32_e32 v206, 0, v0
	v_add_u32_e32 v207, s92, v131
	s_mov_b32 s60, 0xbfb8aa3b
	s_lshl_b32 s62, s0, 2
	s_mov_b32 s64, 0x3dd2d3e7
	s_mov_b32 s66, 0xc0135761
	s_mov_b32 s93, 0x600000
	s_mov_b32 s94, 0x900000
	s_mov_b32 s95, 0x1800000
	s_mov_b32 s96, 0x1b00000
	s_mov_b32 s97, 0x1e00000
	s_mov_b32 s98, 0x2100000
	s_mov_b32 s99, 0x40000
	s_mov_b32 s22, 0x48000
	s_mov_b32 s23, 0x50000
	s_mov_b32 s24, 0
	s_cmpk_lt_u32 s61, 0x100
	s_cbranch_scc1 .Lsprio_0
	s_setprio 1
.Lsprio_0:
	s_barrier
	s_branch .LBB0_122

; #define PG8_STAGE(bufoff, gbase, voff) do { _Pragma("unroll") for (int _i = 0; _i < 2; ++_i) \
;         __builtin_amdgcn_global_load_lds((const unsigned*)((const char*)(gbase) + (voff)[_i]), (LAS unsigned*)(lds + (bufoff) + ldsw + _i * 8192), 16, 0, 0); } while (0)
; #define PG8_LDA(dst, b, h) do { _Pragma("unroll") for (int m = 0; m < 4; ++m) _Pragma("unroll") for (int k = 0; k < 2; ++k) dst[m][k] = *(const LAS bf16x8*)(lds + PG8_SA(b, h) + aoff + m * 2048 + k * 1024); } while (0)
; #define PG8_LDB(dst, b, h) do { _Pragma("unroll") for (int n = 0; n < 2; ++n) _Pragma("unroll") for (int k = 0; k < 2; ++k) dst[n][k] = *(const LAS bf16x8*)(lds + PG8_SB(b, h) + boff + n * 2048 + k * 1024); } while (0)
; #define PG8_MMA(ai, bj, At, Bt) do { __builtin_amdgcn_s_setprio(1); _Pragma("unroll") for (int m = 0; m < 4; ++m) _Pragma("unroll") for (int n = 0; n < 2; ++n) _Pragma("unroll") for (int k = 0; k < 2; ++k) \
;         acc[ai][bj][m][n] = __builtin_amdgcn_mfma_f32_16x16x32_bf16(Bt[n][k], At[m][k], acc[ai][bj][m][n], 0, 0, 0); __builtin_amdgcn_s_setprio(0); } while (0)
; #define PG8_WAIT_V(n) asm volatile("s_waitcnt vmcnt(" #n ")" ::: "memory")
; #define PG8_WAIT_L(n) asm volatile("s_waitcnt lgkmcnt(" #n ")" ::: "memory")
; template <class Epi, class Ptrs>
; __device__ __forceinline__ void gemm_phase(LAS unsigned char* lds, const int K, const StaticOrder& S, const Ptrs& P, const Epi& E) {
;     ...
;         for (int t = 0; t < nt; t += 2) {
;             const bool last = (t == nt - 2);
;             const char* a1 = cA + (size_t)(t + 1) * kstep;
;             const char* a2 = last ? nA : cA + (size_t)(t + 2) * kstep; const char* b2 = last ? nB : cB + (size_t)(t + 2) * kstep;
;             const char* a3 = a2 + kstep; const char* b3 = b2 + kstep;
;             PG8_LDB(B0, 0, 0); PG8_SCHED; PG8_LDA(At, 0, 0); PG8_STAGE(PG8_SA(1, 1), a1 + hstep, voffA);
;             PG8_WAIT_L(8); PG8_BAR; PG8_WAIT_L(0); PG8_MMA(0, 0, At, B0); PG8_BAR; PG8_SCHED;
;             PG8_LDB(B1, 0, 1); PG8_STAGE(PG8_SB(0, 0), b2, voffB);
;             PG8_BAR; PG8_WAIT_L(0); PG8_MMA(0, 1, At, B1); PG8_BAR;
;             PG8_LDA(At, 0, 1); PG8_STAGE(PG8_SA(0, 0), a2, voffA);
;             PG8_BAR; PG8_WAIT_L(0); PG8_MMA(1, 0, At, B0); PG8_BAR; PG8_SCHED;
;             PG8_STAGE(PG8_SB(0, 1), b2 + hstep, voffB);
;             PG8_WAIT_V(6); PG8_BAR; PG8_MMA(1, 1, At, B1); PG8_BAR;
.LBB0_127:
	ds_read_b128 v[150:153], v205
	ds_read_b128 v[154:157], v205 offset:1024
	ds_read_b128 v[158:161], v205 offset:2048
	ds_read_b128 v[162:165], v205 offset:3072
	s_add_u32 s69, s6, 0xfffc0080
	s_addc_u32 s71, s7, -1
	s_cmp_eq_u32 s63, 12
	s_cselect_b32 s81, s1, s71
	s_cselect_b32 s80, s0, s69
	s_cselect_b32 s79, s73, s25
	s_cselect_b32 s78, s72, s20
	s_add_i32 m0, s67, 0xc000
	ds_read_b128 v[166:169], v206
	ds_read_b128 v[170:173], v206 offset:1024
	ds_read_b128 v[174:177], v206 offset:2048
	ds_read_b128 v[178:181], v206 offset:3072
	ds_read_b128 v[182:185], v206 offset:4096
	ds_read_b128 v[186:189], v206 offset:5120
	ds_read_b128 v[190:193], v206 offset:6144
	ds_read_b128 v[194:197], v206 offset:7168
	global_load_lds_dwordx4 v142, s[6:7]
	s_add_i32 m0, s67, 0xe000
	s_nop 0
	global_load_lds_dwordx4 v144, s[6:7]
	s_waitcnt lgkmcnt(8)
	s_barrier
	s_waitcnt lgkmcnt(0)
	s_waitcnt lgkmcnt(0)
	v_mfma_f32_16x16x32_bf16 v[120:123], v[150:153], v[166:169], v[120:123]
	v_mfma_f32_16x16x32_bf16 v[120:123], v[154:157], v[170:173], v[120:123]
	v_mfma_f32_16x16x32_bf16 v[116:119], v[162:165], v[170:173], v[116:119]
	v_mfma_f32_16x16x32_bf16 v[116:119], v[158:161], v[166:169], v[116:119]
	v_mfma_f32_16x16x32_bf16 v[100:103], v[158:161], v[174:177], v[100:103]
	v_mfma_f32_16x16x32_bf16 v[100:103], v[162:165], v[178:181], v[100:103]
	v_mfma_f32_16x16x32_bf16 v[104:107], v[154:157], v[178:181], v[104:107]
	v_mfma_f32_16x16x32_bf16 v[104:107], v[150:153], v[174:177], v[104:107]
	v_mfma_f32_16x16x32_bf16 v[88:91], v[150:153], v[182:185], v[88:91]
	v_mfma_f32_16x16x32_bf16 v[88:91], v[154:157], v[186:189], v[88:91]
	v_mfma_f32_16x16x32_bf16 v[84:87], v[162:165], v[186:189], v[84:87]
	v_mfma_f32_16x16x32_bf16 v[84:87], v[158:161], v[182:185], v[84:87]
	v_mfma_f32_16x16x32_bf16 v[68:71], v[158:161], v[190:193], v[68:71]
	v_mfma_f32_16x16x32_bf16 v[68:71], v[162:165], v[194:197], v[68:71]
	v_mfma_f32_16x16x32_bf16 v[72:75], v[154:157], v[194:197], v[72:75]
	v_mfma_f32_16x16x32_bf16 v[72:75], v[150:153], v[190:193], v[72:75]
	s_barrier
	s_add_i32 s69, s91, s65
	v_lshl_add_u64 v[202:203], s[78:79], 0, v[134:135]
	s_mov_b32 m0, s69
	ds_read_b128 v[198:201], v207
	ds_read_b128 v[210:213], v207 offset:1024
	ds_read_b128 v[214:217], v207 offset:2048
	ds_read_b128 v[218:221], v207 offset:3072
	global_load_lds_dwordx4 v[202:203], off
	v_lshl_add_u64 v[222:223], s[78:79], 0, v[138:139]
	s_add_i32 m0, s69, 0x2000
	s_nop 0
	global_load_lds_dwordx4 v[222:223], off
	s_barrier
	s_waitcnt lgkmcnt(0)
	s_waitcnt lgkmcnt(0)
	v_mfma_f32_16x16x32_bf16 v[124:127], v[198:201], v[166:169], v[124:127]
	v_mfma_f32_16x16x32_bf16 v[124:127], v[210:213], v[170:173], v[124:127]
	v_mfma_f32_16x16x32_bf16 v[112:115], v[218:221], v[170:173], v[112:115]
	v_mfma_f32_16x16x32_bf16 v[112:115], v[214:217], v[166:169], v[112:115]
	v_mfma_f32_16x16x32_bf16 v[96:99], v[214:217], v[174:177], v[96:99]
	v_mfma_f32_16x16x32_bf16 v[96:99], v[218:221], v[178:181], v[96:99]
	v_mfma_f32_16x16x32_bf16 v[108:111], v[210:213], v[178:181], v[108:111]
	v_mfma_f32_16x16x32_bf16 v[108:111], v[198:201], v[174:177], v[108:111]
	v_mfma_f32_16x16x32_bf16 v[92:95], v[198:201], v[182:185], v[92:95]
	v_mfma_f32_16x16x32_bf16 v[92:95], v[210:213], v[186:189], v[92:95]
	v_mfma_f32_16x16x32_bf16 v[80:83], v[218:221], v[186:189], v[80:83]
	v_mfma_f32_16x16x32_bf16 v[80:83], v[214:217], v[182:185], v[80:83]
	v_mfma_f32_16x16x32_bf16 v[64:67], v[214:217], v[190:193], v[64:67]
	v_mfma_f32_16x16x32_bf16 v[64:67], v[218:221], v[194:197], v[64:67]
	v_mfma_f32_16x16x32_bf16 v[76:79], v[210:213], v[194:197], v[76:79]
	v_mfma_f32_16x16x32_bf16 v[76:79], v[198:201], v[190:193], v[76:79]
	s_mov_b32 m0, s67
	v_lshl_add_u64 v[224:225], s[80:81], 0, v[132:133]
	s_barrier
	ds_read_b128 v[166:169], v206 offset:16384
	ds_read_b128 v[170:173], v206 offset:17408
	ds_read_b128 v[174:177], v206 offset:18432
	ds_read_b128 v[178:181], v206 offset:19456
	ds_read_b128 v[182:185], v206 offset:20480
	ds_read_b128 v[186:189], v206 offset:21504
	ds_read_b128 v[190:193], v206 offset:22528
	ds_read_b128 v[194:197], v206 offset:23552
	global_load_lds_dwordx4 v[224:225], off
	v_lshl_add_u64 v[226:227], s[80:81], 0, v[136:137]
	s_mov_b32 m0, s75
	s_nop 0
	global_load_lds_dwordx4 v[226:227], off
	s_barrier
	s_waitcnt lgkmcnt(0)
	s_waitcnt lgkmcnt(0)
	v_mfma_f32_16x16x32_bf16 v[56:59], v[150:153], v[166:169], v[56:59]
	v_mfma_f32_16x16x32_bf16 v[56:59], v[154:157], v[170:173], v[56:59]
	v_mfma_f32_16x16x32_bf16 v[52:55], v[162:165], v[170:173], v[52:55]
	v_mfma_f32_16x16x32_bf16 v[52:55], v[158:161], v[166:169], v[52:55]
	v_mfma_f32_16x16x32_bf16 v[36:39], v[158:161], v[174:177], v[36:39]
	v_mfma_f32_16x16x32_bf16 v[36:39], v[162:165], v[178:181], v[36:39]
	v_mfma_f32_16x16x32_bf16 v[40:43], v[154:157], v[178:181], v[40:43]
	v_mfma_f32_16x16x32_bf16 v[40:43], v[150:153], v[174:177], v[40:43]
	v_mfma_f32_16x16x32_bf16 v[24:27], v[150:153], v[182:185], v[24:27]
	v_mfma_f32_16x16x32_bf16 v[24:27], v[154:157], v[186:189], v[24:27]
	v_mfma_f32_16x16x32_bf16 v[20:23], v[162:165], v[186:189], v[20:23]
	v_mfma_f32_16x16x32_bf16 v[20:23], v[158:161], v[182:185], v[20:23]
	v_mfma_f32_16x16x32_bf16 v[4:7], v[158:161], v[190:193], v[4:7]
	v_mfma_f32_16x16x32_bf16 v[4:7], v[162:165], v[194:197], v[4:7]
	v_mfma_f32_16x16x32_bf16 v[8:11], v[154:157], v[194:197], v[8:11]
	v_mfma_f32_16x16x32_bf16 v[8:11], v[150:153], v[190:193], v[8:11]
	s_barrier
	s_add_u32 s82, s78, 0x40000
	s_addc_u32 s83, s79, 0
	s_add_i32 s69, s92, s65
	s_mov_b32 m0, s69
	s_nop 0
	global_load_lds_dwordx4 v134, s[82:83]
	s_add_i32 m0, s69, 0x2000
	s_nop 0
	global_load_lds_dwordx4 v138, s[82:83]
	s_waitcnt vmcnt(6)
	s_barrier
; #define PG8_STAGE(bufoff, gbase, voff) do { _Pragma("unroll") for (int _i = 0; _i < 2; ++_i) \
;         __builtin_amdgcn_global_load_lds((const unsigned*)((const char*)(gbase) + (voff)[_i]), (LAS unsigned*)(lds + (bufoff) + ldsw + _i * 8192), 16, 0, 0); } while (0)
; #define PG8_LDA(dst, b, h) do { _Pragma("unroll") for (int m = 0; m < 4; ++m) _Pragma("unroll") for (int k = 0; k < 2; ++k) dst[m][k] = *(const LAS bf16x8*)(lds + PG8_SA(b, h) + aoff + m * 2048 + k * 1024); } while (0)
; #define PG8_LDB(dst, b, h) do { _Pragma("unroll") for (int n = 0; n < 2; ++n) _Pragma("unroll") for (int k = 0; k < 2; ++k) dst[n][k] = *(const LAS bf16x8*)(lds + PG8_SB(b, h) + boff + n * 2048 + k * 1024); } while (0)
; #define PG8_MMA(ai, bj, At, Bt) do { __builtin_amdgcn_s_setprio(1); _Pragma("unroll") for (int m = 0; m < 4; ++m) _Pragma("unroll") for (int n = 0; n < 2; ++n) _Pragma("unroll") for (int k = 0; k < 2; ++k) \
;         acc[ai][bj][m][n] = __builtin_amdgcn_mfma_f32_16x16x32_bf16(Bt[n][k], At[m][k], acc[ai][bj][m][n], 0, 0, 0); __builtin_amdgcn_s_setprio(0); } while (0)
; #define PG8_WAIT_V(n) asm volatile("s_waitcnt vmcnt(" #n ")" ::: "memory")
; #define PG8_WAIT_L(n) asm volatile("s_waitcnt lgkmcnt(" #n ")" ::: "memory")
; #define PG8_BAR __builtin_amdgcn_s_barrier()
; #define PG8_SCHED __builtin_amdgcn_sched_barrier(0)
; template <class Epi, class Ptrs>
; __device__ __forceinline__ void gemm_phase(LAS unsigned char* lds, const int K, const StaticOrder& S, const Ptrs& P, const Epi& E) {
;     ...
;             PG8_WAIT_V(6); PG8_BAR; PG8_MMA(1, 1, At, B1); PG8_BAR;
;             PG8_LDB(B0, 1, 0); PG8_SCHED; PG8_LDA(At, 1, 0); PG8_STAGE(PG8_SA(0, 1), a2 + hstep, voffA);
;             PG8_WAIT_L(8); PG8_BAR; PG8_WAIT_L(0); PG8_MMA(0, 0, At, B0); PG8_BAR; PG8_SCHED;
;             PG8_LDB(B1, 1, 1); PG8_STAGE(PG8_SB(1, 0), b3, voffB);
;             PG8_BAR; PG8_WAIT_L(0); PG8_MMA(0, 1, At, B1); PG8_BAR;
;             PG8_LDA(At, 1, 1); PG8_STAGE(PG8_SA(1, 0), a3, voffA);
	v_mfma_f32_16x16x32_bf16 v[60:63], v[198:201], v[166:169], v[60:63]
	v_mfma_f32_16x16x32_bf16 v[60:63], v[210:213], v[170:173], v[60:63]
	v_mfma_f32_16x16x32_bf16 v[48:51], v[218:221], v[170:173], v[48:51]
	v_mfma_f32_16x16x32_bf16 v[48:51], v[214:217], v[166:169], v[48:51]
	v_mfma_f32_16x16x32_bf16 v[32:35], v[214:217], v[174:177], v[32:35]
	v_mfma_f32_16x16x32_bf16 v[32:35], v[218:221], v[178:181], v[32:35]
	v_mfma_f32_16x16x32_bf16 v[44:47], v[210:213], v[178:181], v[44:47]
	v_mfma_f32_16x16x32_bf16 v[44:47], v[198:201], v[174:177], v[44:47]
	v_mfma_f32_16x16x32_bf16 v[28:31], v[198:201], v[182:185], v[28:31]
	v_mfma_f32_16x16x32_bf16 v[28:31], v[210:213], v[186:189], v[28:31]
	v_mfma_f32_16x16x32_bf16 v[16:19], v[218:221], v[186:189], v[16:19]
	v_mfma_f32_16x16x32_bf16 v[16:19], v[214:217], v[182:185], v[16:19]
	v_mfma_f32_16x16x32_bf16 v[0:3], v[214:217], v[190:193], v[0:3]
	v_mfma_f32_16x16x32_bf16 v[0:3], v[218:221], v[194:197], v[0:3]
	v_mfma_f32_16x16x32_bf16 v[12:15], v[210:213], v[194:197], v[12:15]
	v_mfma_f32_16x16x32_bf16 v[12:15], v[198:201], v[190:193], v[12:15]
	s_add_i32 s69, 0, 0x18000
	v_add_u32_e32 v140, s69, v131
	s_barrier
	ds_read_b128 v[150:153], v140
	ds_read_b128 v[154:157], v140 offset:1024
	ds_read_b128 v[158:161], v140 offset:2048
	ds_read_b128 v[162:165], v140 offset:3072
	s_add_u32 s80, s80, 0x40000
	s_addc_u32 s81, s81, 0
	s_mov_b32 m0, s77
	ds_read_b128 v[166:169], v206 offset:32768
	ds_read_b128 v[170:173], v206 offset:33792
	ds_read_b128 v[174:177], v206 offset:34816
	ds_read_b128 v[178:181], v206 offset:35840
	ds_read_b128 v[182:185], v206 offset:36864
	ds_read_b128 v[186:189], v206 offset:37888
	ds_read_b128 v[190:193], v206 offset:38912
	ds_read_b128 v[194:197], v206 offset:39936
	global_load_lds_dwordx4 v132, s[80:81]
	s_mov_b32 m0, s85
	s_nop 0
	global_load_lds_dwordx4 v136, s[80:81]
	s_waitcnt lgkmcnt(8)
	s_barrier
	s_waitcnt lgkmcnt(0)
	s_waitcnt lgkmcnt(0)
	v_mfma_f32_16x16x32_bf16 v[120:123], v[150:153], v[166:169], v[120:123]
	v_mfma_f32_16x16x32_bf16 v[120:123], v[154:157], v[170:173], v[120:123]
	v_mfma_f32_16x16x32_bf16 v[116:119], v[162:165], v[170:173], v[116:119]
	v_mfma_f32_16x16x32_bf16 v[116:119], v[158:161], v[166:169], v[116:119]
	v_mfma_f32_16x16x32_bf16 v[100:103], v[158:161], v[174:177], v[100:103]
	v_mfma_f32_16x16x32_bf16 v[100:103], v[162:165], v[178:181], v[100:103]
	v_mfma_f32_16x16x32_bf16 v[104:107], v[154:157], v[178:181], v[104:107]
	v_mfma_f32_16x16x32_bf16 v[104:107], v[150:153], v[174:177], v[104:107]
	v_mfma_f32_16x16x32_bf16 v[88:91], v[150:153], v[182:185], v[88:91]
	v_mfma_f32_16x16x32_bf16 v[88:91], v[154:157], v[186:189], v[88:91]
	v_mfma_f32_16x16x32_bf16 v[84:87], v[162:165], v[186:189], v[84:87]
	v_mfma_f32_16x16x32_bf16 v[84:87], v[158:161], v[182:185], v[84:87]
	v_mfma_f32_16x16x32_bf16 v[68:71], v[158:161], v[190:193], v[68:71]
	v_mfma_f32_16x16x32_bf16 v[68:71], v[162:165], v[194:197], v[68:71]
	v_mfma_f32_16x16x32_bf16 v[72:75], v[154:157], v[194:197], v[72:75]
	v_mfma_f32_16x16x32_bf16 v[72:75], v[150:153], v[190:193], v[72:75]
	s_barrier
	s_add_i32 s71, 0, 0x1c000
	s_add_i32 s69, s69, s65
	v_add_u32_e32 v140, s71, v131
	v_lshl_add_u64 v[202:203], v[202:203], 0, s[58:59]
	s_mov_b32 m0, s69
	ds_read_b128 v[198:201], v140
	ds_read_b128 v[210:213], v140 offset:1024
	ds_read_b128 v[214:217], v140 offset:2048
	ds_read_b128 v[218:221], v140 offset:3072
	global_load_lds_dwordx4 v[202:203], off
	v_lshl_add_u64 v[202:203], v[222:223], 0, s[58:59]
	s_add_i32 m0, s69, 0x2000
	s_nop 0
	global_load_lds_dwordx4 v[202:203], off
	s_barrier
	s_waitcnt lgkmcnt(0)
	s_waitcnt lgkmcnt(0)
	v_mfma_f32_16x16x32_bf16 v[124:127], v[198:201], v[166:169], v[124:127]
	v_mfma_f32_16x16x32_bf16 v[124:127], v[210:213], v[170:173], v[124:127]
	v_mfma_f32_16x16x32_bf16 v[112:115], v[218:221], v[170:173], v[112:115]
	v_mfma_f32_16x16x32_bf16 v[112:115], v[214:217], v[166:169], v[112:115]
	v_mfma_f32_16x16x32_bf16 v[96:99], v[214:217], v[174:177], v[96:99]
	v_mfma_f32_16x16x32_bf16 v[96:99], v[218:221], v[178:181], v[96:99]
	v_mfma_f32_16x16x32_bf16 v[108:111], v[210:213], v[178:181], v[108:111]
	v_mfma_f32_16x16x32_bf16 v[108:111], v[198:201], v[174:177], v[108:111]
	v_mfma_f32_16x16x32_bf16 v[92:95], v[198:201], v[182:185], v[92:95]
	v_mfma_f32_16x16x32_bf16 v[92:95], v[210:213], v[186:189], v[92:95]
	v_mfma_f32_16x16x32_bf16 v[80:83], v[218:221], v[186:189], v[80:83]
	v_mfma_f32_16x16x32_bf16 v[80:83], v[214:217], v[182:185], v[80:83]
	v_mfma_f32_16x16x32_bf16 v[64:67], v[214:217], v[190:193], v[64:67]
	v_mfma_f32_16x16x32_bf16 v[64:67], v[218:221], v[194:197], v[64:67]
	v_mfma_f32_16x16x32_bf16 v[76:79], v[210:213], v[194:197], v[76:79]
	v_mfma_f32_16x16x32_bf16 v[76:79], v[198:201], v[190:193], v[76:79]
	s_mov_b32 m0, s89
	v_lshl_add_u64 v[202:203], v[224:225], 0, s[58:59]
	s_barrier
; #define PG8_WAIT_V(n) asm volatile("s_waitcnt vmcnt(" #n ")" ::: "memory")
; template <class Epi, class Ptrs>
; __device__ __forceinline__ void gemm_phase(LAS unsigned char* lds, const int K, const StaticOrder& S, const Ptrs& P, const Epi& E) {
;     ...
;             PG8_LDA(At, 1, 1); PG8_STAGE(PG8_SA(1, 0), a3, voffA);
;             PG8_BAR; PG8_WAIT_L(0); PG8_MMA(1, 0, At, B0); PG8_BAR; PG8_SCHED;
;             PG8_STAGE(PG8_SB(1, 1), b3 + hstep, voffB);
;             PG8_WAIT_V(6); PG8_BAR; PG8_MMA(1, 1, At, B1); PG8_BAR;
;         }
;         E(acc, cur, ui, wr, wc, fr, fq);
;     __device__ __forceinline__ void operator()(const f32x4 (&acc)[2][2][4][2], const Unit& u, int ui, int wr, int wc, int fr, int fq) const {
;         const int pn = u.pn;
;         if (pn < 8) {
;             bf16_t* base = (bf16_t*)(ws + WS_U) + (size_t)(u.pm * 256 + wr * 64 + fr) * DM + pn * 128 + wc * 32 + 8 * fq;
; #pragma unroll
;             for (int ai = 0; ai < 2; ++ai)
; #pragma unroll
;                 for (int m = 0; m < 4; ++m) {
;                     const f32x4 g0 = g1_4(acc[ai][0][m][0], acc[ai][1][m][0]), g1 = g1_4(acc[ai][0][m][1], acc[ai][1][m][1]);
;                     *(u32x4*)(base + (size_t)(ai * 128 + m * 16) * DM) = pack8(g0, g1); }
;             return; }
;         if (pn >= 17 && pn < 21) {
;             bf16_t* base = (bf16_t*)(dout + DO_GVT) + (size_t)((pn - 17) * 256 + wr * 64 + fr) * MTOK + u.pm * 256 + wc * 32 + 8 * fq;
;             float* pp = (float*)(ws + WS_PART) + (size_t)(u.pm * 256 + wc * 32 + 8 * fq) * 8 + (pn - 17) * 2 + wr;
; #pragma unroll
;             for (int bj = 0; bj < 2; ++bj) { f32x4 sq0 = {0.f, 0.f, 0.f, 0.f}, sq1 = {0.f, 0.f, 0.f, 0.f};
; #pragma unroll
;                 for (int ai = 0; ai < 2; ++ai)
; #pragma unroll
;                     for (int m = 0; m < 4; ++m) { const f32x4 g0 = gelu4(acc[ai][bj][m][0]), g1 = gelu4(acc[ai][bj][m][1]);
;                         sq0 += g0 * g0; sq1 += g1 * g1;
;                         *(u32x4*)(base + (size_t)(ai * 128 + m * 16) * MTOK + bj * 128) = pack8(g0, g1); }
; #pragma unroll
;                 for (int j = 0; j < 4; ++j) { const float t0 = row16_sum(sq0[j]), t1 = row16_sum(sq1[j]); if (fr == 0) { pp[(size_t)(bj * 128 + j) * 8] = t0; pp[(size_t)(bj * 128 + 4 + j) * 8] = t1; } } }
;             return; }
;         bf16_t* base; size_t ld; int row0, col0, act;
	ds_read_b128 v[166:169], v206 offset:49152
	ds_read_b128 v[170:173], v206 offset:50176
	ds_read_b128 v[174:177], v206 offset:51200
	ds_read_b128 v[178:181], v206 offset:52224
	ds_read_b128 v[182:185], v206 offset:53248
	ds_read_b128 v[186:189], v206 offset:54272
	ds_read_b128 v[190:193], v206 offset:55296
	ds_read_b128 v[194:197], v206 offset:56320
	global_load_lds_dwordx4 v[202:203], off
	v_lshl_add_u64 v[202:203], v[226:227], 0, s[58:59]
	s_mov_b32 m0, s90
	s_nop 0
	global_load_lds_dwordx4 v[202:203], off
	s_barrier
	s_waitcnt lgkmcnt(0)
	s_waitcnt lgkmcnt(0)
	v_mfma_f32_16x16x32_bf16 v[56:59], v[150:153], v[166:169], v[56:59]
	v_mfma_f32_16x16x32_bf16 v[56:59], v[154:157], v[170:173], v[56:59]
	v_mfma_f32_16x16x32_bf16 v[52:55], v[162:165], v[170:173], v[52:55]
	v_mfma_f32_16x16x32_bf16 v[52:55], v[158:161], v[166:169], v[52:55]
	v_mfma_f32_16x16x32_bf16 v[36:39], v[158:161], v[174:177], v[36:39]
	v_mfma_f32_16x16x32_bf16 v[36:39], v[162:165], v[178:181], v[36:39]
	v_mfma_f32_16x16x32_bf16 v[40:43], v[154:157], v[178:181], v[40:43]
	v_mfma_f32_16x16x32_bf16 v[40:43], v[150:153], v[174:177], v[40:43]
	v_mfma_f32_16x16x32_bf16 v[24:27], v[150:153], v[182:185], v[24:27]
	v_mfma_f32_16x16x32_bf16 v[24:27], v[154:157], v[186:189], v[24:27]
	v_mfma_f32_16x16x32_bf16 v[20:23], v[162:165], v[186:189], v[20:23]
	v_mfma_f32_16x16x32_bf16 v[20:23], v[158:161], v[182:185], v[20:23]
	v_mfma_f32_16x16x32_bf16 v[4:7], v[158:161], v[190:193], v[4:7]
	v_mfma_f32_16x16x32_bf16 v[4:7], v[162:165], v[194:197], v[4:7]
	v_mfma_f32_16x16x32_bf16 v[8:11], v[154:157], v[194:197], v[8:11]
	v_mfma_f32_16x16x32_bf16 v[8:11], v[150:153], v[190:193], v[8:11]
	s_barrier
	s_add_u32 s78, s78, 0x40080
	s_addc_u32 s79, s79, 0
	s_add_i32 s69, s71, s65
	s_mov_b32 m0, s69
	s_nop 0
	global_load_lds_dwordx4 v134, s[78:79]
	s_add_i32 m0, s69, 0x2000
	s_nop 0
	global_load_lds_dwordx4 v138, s[78:79]
	s_waitcnt vmcnt(6)
	s_barrier
	v_mfma_f32_16x16x32_bf16 v[60:63], v[198:201], v[166:169], v[60:63]
	v_mfma_f32_16x16x32_bf16 v[60:63], v[210:213], v[170:173], v[60:63]
	v_mfma_f32_16x16x32_bf16 v[48:51], v[218:221], v[170:173], v[48:51]
	v_mfma_f32_16x16x32_bf16 v[48:51], v[214:217], v[166:169], v[48:51]
	v_mfma_f32_16x16x32_bf16 v[32:35], v[214:217], v[174:177], v[32:35]
	v_mfma_f32_16x16x32_bf16 v[32:35], v[218:221], v[178:181], v[32:35]
	v_mfma_f32_16x16x32_bf16 v[44:47], v[210:213], v[178:181], v[44:47]
	v_mfma_f32_16x16x32_bf16 v[44:47], v[198:201], v[174:177], v[44:47]
	v_mfma_f32_16x16x32_bf16 v[28:31], v[198:201], v[182:185], v[28:31]
	v_mfma_f32_16x16x32_bf16 v[28:31], v[210:213], v[186:189], v[28:31]
	v_mfma_f32_16x16x32_bf16 v[16:19], v[218:221], v[186:189], v[16:19]
	v_mfma_f32_16x16x32_bf16 v[16:19], v[214:217], v[182:185], v[16:19]
	v_mfma_f32_16x16x32_bf16 v[0:3], v[214:217], v[190:193], v[0:3]
	v_mfma_f32_16x16x32_bf16 v[0:3], v[218:221], v[194:197], v[0:3]
	v_mfma_f32_16x16x32_bf16 v[12:15], v[210:213], v[194:197], v[12:15]
	v_mfma_f32_16x16x32_bf16 v[12:15], v[198:201], v[190:193], v[12:15]
	s_add_i32 s63, s63, 2
	s_add_u32 s6, s6, 0x100
	s_addc_u32 s7, s7, 0
	s_add_u32 s20, s20, 0x100
	s_addc_u32 s25, s25, 0
	s_cmp_gt_u32 s63, 13
	s_barrier
	s_cbranch_scc0 .LBB0_127
	s_nop 0
	s_nop 0
	s_nop 0
	s_nop 0
	s_nop 0
	s_nop 0
	s_nop 0
	s_nop 0
	s_nop 0
	s_nop 0
	s_nop 0
	s_nop 0
	s_nop 0
	s_nop 0
	s_nop 0
	s_nop 0
	s_nop 0
	s_nop 0
	s_nop 0
	s_nop 0
	s_nop 0
	s_nop 0
	s_nop 0
	s_nop 0
	s_nop 0
	s_nop 0
	s_nop 0
	s_nop 0
	s_nop 0
	s_cmp_gt_i32 s74, 7
	s_mov_b64 s[6:7], -1
	s_cbranch_scc0 .LBB0_188
	s_sub_i32 s25, s74, 17
	s_cmp_gt_u32 s25, 3
	s_cbranch_scc0 .LBB0_170
	s_lshl_b32 s69, s76, 8
	s_cmp_gt_u32 s74, 11
	s_cbranch_scc0 .LBB0_135
	s_cmp_eq_u32 s74, 12
	s_mov_b64 s[6:7], 0
	s_cbranch_scc1 .LBB0_134
	s_cmp_gt_u32 s74, 16
	s_cbranch_scc1 .LBB0_191
	s_lshl_b32 s20, s74, 8
	v_readlane_b32 s80, v254, 2
	s_addk_i32 s20, 0xf300
	s_mov_b64 s[78:79], 0x400
	s_mov_b64 s[82:83], -1
	s_mov_b32 s63, s69
	v_readlane_b32 s81, v254, 3
	s_andn2_b64 vcc, exec, s[6:7]
	s_cbranch_vccz .LBB0_136
	s_branch .LBB0_137

; #define PG8_WAIT_V(n) asm volatile("s_waitcnt vmcnt(" #n ")" ::: "memory")
; #define PG8_BAR __builtin_amdgcn_s_barrier()
; template <class Epi, class Ptrs>
; __device__ __forceinline__ void gemm_phase(LAS unsigned char* lds, const int K, const StaticOrder& S, const Ptrs& P, const Epi& E) {
;     ...
;     PG8_WAIT_V(0);
;     if (wr == 0) PG8_BAR;
;     PG8_BAR;
.LBB0_192:
	s_waitcnt vmcnt(0)
	s_setprio 0
	s_cmpk_gt_u32 s61, 0xff
	s_cbranch_scc1 .LBB0_194
	s_barrier

; #define PG8_STAGE(bufoff, gbase, voff) do { _Pragma("unroll") for (int _i = 0; _i < 2; ++_i) \
;         __builtin_amdgcn_global_load_lds((const unsigned*)((const char*)(gbase) + (voff)[_i]), (LAS unsigned*)(lds + (bufoff) + ldsw + _i * 8192), 16, 0, 0); } while (0)
; #define PG8_WAIT_V(n) asm volatile("s_waitcnt vmcnt(" #n ")" ::: "memory")
; #define PG8_BAR __builtin_amdgcn_s_barrier()
; template <class Epi, class Ptrs>
; __device__ __forceinline__ void gemm_phase(LAS unsigned char* lds, const int K, const StaticOrder& S, const Ptrs& P, const Epi& E) {
;     const int tid = threadIdx.x, wid = __builtin_amdgcn_readfirstlane(tid >> 6), lane = tid & 63, wr = wid >> 2, wc = wid & 3, fr = lane & 15, fq = lane >> 4;
;     const int nt = K / BK;
;     unsigned voffA[2], voffB[2];
; #pragma unroll
;     for (int i = 0; i < 2; ++i) { int R, C; stage_rc(tid * 16 + i * 8192, R, C); const int Rb = (R & ~31) + perm32(R & 31);
;         voffA[i] = (unsigned)(R * K + C) * 2u; voffB[i] = (unsigned)(Rb * K + C) * 2u; }
;     const size_t kstep = (size_t)(BK * 2);
;     const size_t hstep = (size_t)HALF * K * 2;
;     const unsigned ldsw = (unsigned)wid * 1024u;
;     const int aoff = lds_byte(wr * 64 + fr, fq * 8), boff = lds_byte(wc * 32 + fr, fq * 8);
;     ...
;     PG8_STAGE(PG8_SB(0, 0), cB, voffB); PG8_STAGE(PG8_SA(0, 0), cA, voffA); PG8_STAGE(PG8_SB(0, 1), cB + hstep, voffB); PG8_STAGE(PG8_SA(0, 1), cA + hstep, voffA);
;     if (wr == 1) PG8_BAR;
;     PG8_WAIT_V(4); PG8_BAR;
;     PG8_STAGE(PG8_SB(1, 0), cB + kstep, voffB); PG8_STAGE(PG8_SA(1, 0), cA + kstep, voffA); PG8_STAGE(PG8_SB(1, 1), cB + hstep + kstep, voffB);
;     PG8_WAIT_V(6); PG8_BAR;
.LBB0_346:
	s_add_u32 s14, s28, 0x2000000
	s_addc_u32 s15, s29, 0
	s_add_u32 s16, s28, 0x3e000000
	s_addc_u32 s17, s29, 0
	s_ashr_i32 s58, s3, 31
	s_ashr_i32 s59, s2, 31
	s_add_u32 s60, s38, 0xf8000000
	s_mov_b64 s[18:19], 0x80
	s_addc_u32 s61, s39, -1
	s_and_b32 s62, s1, 3
	s_add_i32 m0, s54, 0x18000
	v_lshl_add_u64 v[6:7], v[6:7], 0, s[18:19]
	s_lshl_b32 s1, s0, 13
	s_lshl_b32 s20, s62, 12
	s_waitcnt vmcnt(4)
	s_barrier
	global_load_lds_dwordx4 v[6:7], off
	v_lshl_add_u64 v[4:5], v[4:5], 0, s[18:19]
	s_add_i32 m0, s54, 0x1a000
	s_add_i32 s63, s54, 0x8000
	s_add_i32 s64, s54, 0xa000
	global_load_lds_dwordx4 v[4:5], off
	v_lshl_add_u64 v[2:3], v[2:3], 0, s[18:19]
	s_mov_b32 m0, s63
	s_add_u32 s4, s42, 0x40080
	global_load_lds_dwordx4 v[2:3], off
	v_lshl_add_u64 v[0:1], v[0:1], 0, s[18:19]
	s_mov_b32 m0, s64
	s_addc_u32 s5, s43, 0
	global_load_lds_dwordx4 v[0:1], off
	s_add_i32 m0, s54, 0x1c000
	v_lshl_add_u64 v[0:1], s[4:5], 0, v[178:179]
	global_load_lds_dwordx4 v[0:1], off
	v_lshl_add_u64 v[0:1], s[4:5], 0, v[182:183]
	s_add_i32 m0, s54, 0x1e000
	v_lshlrev_b32_e32 v4, 6, v208
	global_load_lds_dwordx4 v[0:1], off
	v_bfe_u32 v1, v208, 4, 2
	v_lshlrev_b32_e32 v2, 3, v1
	v_lshlrev_b32_e32 v3, 4, v1
	v_cmp_eq_u32_e64 s[6:7], 0, v1
	v_lshlrev_b32_e32 v1, 8, v208
	v_lshl_or_b32 v206, s62, 5, v2
	v_and_b32_e32 v1, 0x38000, v1
	v_lshlrev_b32_e32 v2, 11, v10
	v_or3_b32 v1, v8, v1, v2
	v_and_b32_e32 v0, 15, v208
	s_movk_i32 s4, 0x3c0
	v_lshlrev_b32_e32 v5, 2, v208
	v_add_u32_e32 v184, v1, v9
	v_lshlrev_b32_e32 v1, 4, v11
	v_and_or_b32 v4, v4, s4, v3
	v_and_b32_e32 v5, 32, v5
	v_lshl_or_b32 v204, s0, 6, v0
	v_lshl_or_b32 v0, v0, 6, v3
	s_waitcnt vmcnt(6)
	v_and_b32_e32 v1, 0x78000, v1
	v_bitop3_b32 v0, v0, s1, v5 bitop3:0xde
	v_bitop3_b32 v205, s20, v4, v5 bitop3:0xf6
	v_or3_b32 v1, v8, v1, v2
	s_add_i32 s66, 0, 0x10000
	s_add_i32 s67, 0, 0x14000
	v_mov_b32_e32 v185, v179
	v_add_u32_e32 v186, v1, v9
	v_mov_b32_e32 v187, v179
	v_mov_b64_e32 v[188:189], 0x600
	v_mov_b64_e32 v[190:191], 0x5ff
	s_movk_i32 s65, 0xc1
	v_add_u32_e32 v207, s66, v205
	v_add_u32_e32 v209, 0, v0
	v_add_u32_e32 v210, s67, v205
	s_mov_b32 s68, 0
	s_cmpk_lt_u32 s46, 0x100
	s_cbranch_scc1 .Lsprio_1
	s_setprio 1

; #define PG8_STAGE(bufoff, gbase, voff) do { _Pragma("unroll") for (int _i = 0; _i < 2; ++_i) \
;         __builtin_amdgcn_global_load_lds((const unsigned*)((const char*)(gbase) + (voff)[_i]), (LAS unsigned*)(lds + (bufoff) + ldsw + _i * 8192), 16, 0, 0); } while (0)
; #define PG8_LDA(dst, b, h) do { _Pragma("unroll") for (int m = 0; m < 4; ++m) _Pragma("unroll") for (int k = 0; k < 2; ++k) dst[m][k] = *(const LAS bf16x8*)(lds + PG8_SA(b, h) + aoff + m * 2048 + k * 1024); } while (0)
; #define PG8_LDB(dst, b, h) do { _Pragma("unroll") for (int n = 0; n < 2; ++n) _Pragma("unroll") for (int k = 0; k < 2; ++k) dst[n][k] = *(const LAS bf16x8*)(lds + PG8_SB(b, h) + boff + n * 2048 + k * 1024); } while (0)
; #define PG8_MMA(ai, bj, At, Bt) do { __builtin_amdgcn_s_setprio(1); _Pragma("unroll") for (int m = 0; m < 4; ++m) _Pragma("unroll") for (int n = 0; n < 2; ++n) _Pragma("unroll") for (int k = 0; k < 2; ++k) \
;         acc[ai][bj][m][n] = __builtin_amdgcn_mfma_f32_16x16x32_bf16(Bt[n][k], At[m][k], acc[ai][bj][m][n], 0, 0, 0); __builtin_amdgcn_s_setprio(0); } while (0)
; #define PG8_WAIT_V(n) asm volatile("s_waitcnt vmcnt(" #n ")" ::: "memory")
; #define PG8_WAIT_L(n) asm volatile("s_waitcnt lgkmcnt(" #n ")" ::: "memory")
; template <class Epi, class Ptrs>
; __device__ __forceinline__ void gemm_phase(LAS unsigned char* lds, const int K, const StaticOrder& S, const Ptrs& P, const Epi& E) {
;     ...
;         for (int t = 0; t < nt; t += 2) {
;             const bool last = (t == nt - 2);
;             const char* a1 = cA + (size_t)(t + 1) * kstep;
;             const char* a2 = last ? nA : cA + (size_t)(t + 2) * kstep; const char* b2 = last ? nB : cB + (size_t)(t + 2) * kstep;
;             const char* a3 = a2 + kstep; const char* b3 = b2 + kstep;
;             PG8_LDB(B0, 0, 0); PG8_SCHED; PG8_LDA(At, 0, 0); PG8_STAGE(PG8_SA(1, 1), a1 + hstep, voffA);
;             PG8_WAIT_L(8); PG8_BAR; PG8_WAIT_L(0); PG8_MMA(0, 0, At, B0); PG8_BAR; PG8_SCHED;
;             PG8_LDB(B1, 0, 1); PG8_STAGE(PG8_SB(0, 0), b2, voffB);
;             PG8_BAR; PG8_WAIT_L(0); PG8_MMA(0, 1, At, B1); PG8_BAR;
;             PG8_LDA(At, 0, 1); PG8_STAGE(PG8_SA(0, 0), a2, voffA);
;             PG8_BAR; PG8_WAIT_L(0); PG8_MMA(1, 0, At, B0); PG8_BAR; PG8_SCHED;
;             PG8_STAGE(PG8_SB(0, 1), b2 + hstep, voffB);
;             PG8_WAIT_V(6); PG8_BAR; PG8_MMA(1, 1, At, B1); PG8_BAR;
.LBB0_353:
	ds_read_b128 v[128:131], v207
	ds_read_b128 v[132:135], v207 offset:1024
	ds_read_b128 v[136:139], v207 offset:2048
	ds_read_b128 v[140:143], v207 offset:3072
	s_add_u32 s42, s38, 0xfffc0080
	s_addc_u32 s43, s39, -1
	s_cmp_eq_u32 s41, 12
	s_cselect_b32 s45, s1, s43
	s_cselect_b32 s44, s0, s42
	s_cselect_b32 s43, s25, s23
	s_cselect_b32 s42, s24, s21
	s_add_i32 m0, s54, 0xc000
	ds_read_b128 v[144:147], v209
	ds_read_b128 v[148:151], v209 offset:1024
	ds_read_b128 v[152:155], v209 offset:2048
	ds_read_b128 v[156:159], v209 offset:3072
	ds_read_b128 v[160:163], v209 offset:4096
	ds_read_b128 v[164:167], v209 offset:5120
	ds_read_b128 v[168:171], v209 offset:6144
	ds_read_b128 v[172:175], v209 offset:7168
	global_load_lds_dwordx4 v184, s[38:39]
	s_add_i32 m0, s54, 0xe000
	s_nop 0
	global_load_lds_dwordx4 v186, s[38:39]
	s_waitcnt lgkmcnt(8)
	s_barrier
	s_waitcnt lgkmcnt(0)
	s_waitcnt lgkmcnt(0)
	v_mfma_f32_16x16x32_bf16 v[124:127], v[128:131], v[144:147], v[124:127]
	v_mfma_f32_16x16x32_bf16 v[124:127], v[132:135], v[148:151], v[124:127]
	v_mfma_f32_16x16x32_bf16 v[120:123], v[140:143], v[148:151], v[120:123]
	v_mfma_f32_16x16x32_bf16 v[120:123], v[136:139], v[144:147], v[120:123]
	v_mfma_f32_16x16x32_bf16 v[104:107], v[136:139], v[152:155], v[104:107]
	v_mfma_f32_16x16x32_bf16 v[104:107], v[140:143], v[156:159], v[104:107]
	v_mfma_f32_16x16x32_bf16 v[108:111], v[132:135], v[156:159], v[108:111]
	v_mfma_f32_16x16x32_bf16 v[108:111], v[128:131], v[152:155], v[108:111]
	v_mfma_f32_16x16x32_bf16 v[92:95], v[128:131], v[160:163], v[92:95]
	v_mfma_f32_16x16x32_bf16 v[92:95], v[132:135], v[164:167], v[92:95]
	v_mfma_f32_16x16x32_bf16 v[88:91], v[140:143], v[164:167], v[88:91]
	v_mfma_f32_16x16x32_bf16 v[88:91], v[136:139], v[160:163], v[88:91]
	v_mfma_f32_16x16x32_bf16 v[72:75], v[136:139], v[168:171], v[72:75]
	v_mfma_f32_16x16x32_bf16 v[72:75], v[140:143], v[172:175], v[72:75]
	v_mfma_f32_16x16x32_bf16 v[76:79], v[132:135], v[172:175], v[76:79]
	v_mfma_f32_16x16x32_bf16 v[76:79], v[128:131], v[168:171], v[76:79]
	s_barrier
	s_add_i32 s69, s66, s51
	v_lshl_add_u64 v[216:217], s[42:43], 0, v[178:179]
	s_mov_b32 m0, s69
	ds_read_b128 v[192:195], v210
	ds_read_b128 v[196:199], v210 offset:1024
	ds_read_b128 v[200:203], v210 offset:2048
	ds_read_b128 v[212:215], v210 offset:3072
	global_load_lds_dwordx4 v[216:217], off
	v_lshl_add_u64 v[218:219], s[42:43], 0, v[182:183]
	s_add_i32 m0, s69, 0x2000
	s_nop 0
	global_load_lds_dwordx4 v[218:219], off
	s_barrier
	s_waitcnt lgkmcnt(0)
	s_waitcnt lgkmcnt(0)
	v_mfma_f32_16x16x32_bf16 v[116:119], v[192:195], v[144:147], v[116:119]
	v_mfma_f32_16x16x32_bf16 v[116:119], v[196:199], v[148:151], v[116:119]
	v_mfma_f32_16x16x32_bf16 v[112:115], v[212:215], v[148:151], v[112:115]
	v_mfma_f32_16x16x32_bf16 v[112:115], v[200:203], v[144:147], v[112:115]
	v_mfma_f32_16x16x32_bf16 v[96:99], v[200:203], v[152:155], v[96:99]
	v_mfma_f32_16x16x32_bf16 v[96:99], v[212:215], v[156:159], v[96:99]
	v_mfma_f32_16x16x32_bf16 v[100:103], v[196:199], v[156:159], v[100:103]
	v_mfma_f32_16x16x32_bf16 v[100:103], v[192:195], v[152:155], v[100:103]
	v_mfma_f32_16x16x32_bf16 v[84:87], v[192:195], v[160:163], v[84:87]
	v_mfma_f32_16x16x32_bf16 v[84:87], v[196:199], v[164:167], v[84:87]
	v_mfma_f32_16x16x32_bf16 v[80:83], v[212:215], v[164:167], v[80:83]
	v_mfma_f32_16x16x32_bf16 v[80:83], v[200:203], v[160:163], v[80:83]
	v_mfma_f32_16x16x32_bf16 v[64:67], v[200:203], v[168:171], v[64:67]
	v_mfma_f32_16x16x32_bf16 v[64:67], v[212:215], v[172:175], v[64:67]
	v_mfma_f32_16x16x32_bf16 v[68:71], v[196:199], v[172:175], v[68:71]
	v_mfma_f32_16x16x32_bf16 v[68:71], v[192:195], v[168:171], v[68:71]
	s_mov_b32 m0, s54
	v_lshl_add_u64 v[220:221], s[44:45], 0, v[176:177]
	s_barrier
	ds_read_b128 v[144:147], v209 offset:16384
	ds_read_b128 v[148:151], v209 offset:17408
	ds_read_b128 v[152:155], v209 offset:18432
	ds_read_b128 v[156:159], v209 offset:19456
	ds_read_b128 v[160:163], v209 offset:20480
	ds_read_b128 v[164:167], v209 offset:21504
	ds_read_b128 v[168:171], v209 offset:22528
	ds_read_b128 v[172:175], v209 offset:23552
	global_load_lds_dwordx4 v[220:221], off
	v_lshl_add_u64 v[222:223], s[44:45], 0, v[180:181]
	s_mov_b32 m0, s55
	s_nop 0
	global_load_lds_dwordx4 v[222:223], off
	s_barrier
	s_waitcnt lgkmcnt(0)
	s_waitcnt lgkmcnt(0)
	v_mfma_f32_16x16x32_bf16 v[60:63], v[128:131], v[144:147], v[60:63]
	v_mfma_f32_16x16x32_bf16 v[60:63], v[132:135], v[148:151], v[60:63]
	v_mfma_f32_16x16x32_bf16 v[56:59], v[140:143], v[148:151], v[56:59]
	v_mfma_f32_16x16x32_bf16 v[56:59], v[136:139], v[144:147], v[56:59]
	v_mfma_f32_16x16x32_bf16 v[40:43], v[136:139], v[152:155], v[40:43]
	v_mfma_f32_16x16x32_bf16 v[40:43], v[140:143], v[156:159], v[40:43]
	v_mfma_f32_16x16x32_bf16 v[44:47], v[132:135], v[156:159], v[44:47]
	v_mfma_f32_16x16x32_bf16 v[44:47], v[128:131], v[152:155], v[44:47]
	v_mfma_f32_16x16x32_bf16 v[28:31], v[128:131], v[160:163], v[28:31]
	v_mfma_f32_16x16x32_bf16 v[28:31], v[132:135], v[164:167], v[28:31]
	v_mfma_f32_16x16x32_bf16 v[24:27], v[140:143], v[164:167], v[24:27]
	v_mfma_f32_16x16x32_bf16 v[24:27], v[136:139], v[160:163], v[24:27]
	v_mfma_f32_16x16x32_bf16 v[8:11], v[136:139], v[168:171], v[8:11]
	v_mfma_f32_16x16x32_bf16 v[8:11], v[140:143], v[172:175], v[8:11]
	v_mfma_f32_16x16x32_bf16 v[12:15], v[132:135], v[172:175], v[12:15]
	v_mfma_f32_16x16x32_bf16 v[12:15], v[128:131], v[168:171], v[12:15]
	s_barrier
	s_add_u32 s70, s42, 0x40000
	s_addc_u32 s71, s43, 0
	s_add_i32 s69, s67, s51
	s_mov_b32 m0, s69
	s_nop 0
	global_load_lds_dwordx4 v178, s[70:71]
	s_add_i32 m0, s69, 0x2000
	s_nop 0
	global_load_lds_dwordx4 v182, s[70:71]
	s_waitcnt vmcnt(6)
	s_barrier
; #define PG8_STAGE(bufoff, gbase, voff) do { _Pragma("unroll") for (int _i = 0; _i < 2; ++_i) \
;         __builtin_amdgcn_global_load_lds((const unsigned*)((const char*)(gbase) + (voff)[_i]), (LAS unsigned*)(lds + (bufoff) + ldsw + _i * 8192), 16, 0, 0); } while (0)
; #define PG8_LDA(dst, b, h) do { _Pragma("unroll") for (int m = 0; m < 4; ++m) _Pragma("unroll") for (int k = 0; k < 2; ++k) dst[m][k] = *(const LAS bf16x8*)(lds + PG8_SA(b, h) + aoff + m * 2048 + k * 1024); } while (0)
; #define PG8_LDB(dst, b, h) do { _Pragma("unroll") for (int n = 0; n < 2; ++n) _Pragma("unroll") for (int k = 0; k < 2; ++k) dst[n][k] = *(const LAS bf16x8*)(lds + PG8_SB(b, h) + boff + n * 2048 + k * 1024); } while (0)
; #define PG8_MMA(ai, bj, At, Bt) do { __builtin_amdgcn_s_setprio(1); _Pragma("unroll") for (int m = 0; m < 4; ++m) _Pragma("unroll") for (int n = 0; n < 2; ++n) _Pragma("unroll") for (int k = 0; k < 2; ++k) \
;         acc[ai][bj][m][n] = __builtin_amdgcn_mfma_f32_16x16x32_bf16(Bt[n][k], At[m][k], acc[ai][bj][m][n], 0, 0, 0); __builtin_amdgcn_s_setprio(0); } while (0)
; #define PG8_WAIT_V(n) asm volatile("s_waitcnt vmcnt(" #n ")" ::: "memory")
; #define PG8_WAIT_L(n) asm volatile("s_waitcnt lgkmcnt(" #n ")" ::: "memory")
; #define PG8_BAR __builtin_amdgcn_s_barrier()
; #define PG8_SCHED __builtin_amdgcn_sched_barrier(0)
; template <class Epi, class Ptrs>
; __device__ __forceinline__ void gemm_phase(LAS unsigned char* lds, const int K, const StaticOrder& S, const Ptrs& P, const Epi& E) {
;     ...
;             PG8_WAIT_V(6); PG8_BAR; PG8_MMA(1, 1, At, B1); PG8_BAR;
;             PG8_LDB(B0, 1, 0); PG8_SCHED; PG8_LDA(At, 1, 0); PG8_STAGE(PG8_SA(0, 1), a2 + hstep, voffA);
;             PG8_WAIT_L(8); PG8_BAR; PG8_WAIT_L(0); PG8_MMA(0, 0, At, B0); PG8_BAR; PG8_SCHED;
;             PG8_LDB(B1, 1, 1); PG8_STAGE(PG8_SB(1, 0), b3, voffB);
;             PG8_BAR; PG8_WAIT_L(0); PG8_MMA(0, 1, At, B1); PG8_BAR;
;             PG8_LDA(At, 1, 1); PG8_STAGE(PG8_SA(1, 0), a3, voffA);
	v_mfma_f32_16x16x32_bf16 v[52:55], v[192:195], v[144:147], v[52:55]
	v_mfma_f32_16x16x32_bf16 v[52:55], v[196:199], v[148:151], v[52:55]
	v_mfma_f32_16x16x32_bf16 v[48:51], v[212:215], v[148:151], v[48:51]
	v_mfma_f32_16x16x32_bf16 v[48:51], v[200:203], v[144:147], v[48:51]
	v_mfma_f32_16x16x32_bf16 v[32:35], v[200:203], v[152:155], v[32:35]
	v_mfma_f32_16x16x32_bf16 v[32:35], v[212:215], v[156:159], v[32:35]
	v_mfma_f32_16x16x32_bf16 v[36:39], v[196:199], v[156:159], v[36:39]
	v_mfma_f32_16x16x32_bf16 v[36:39], v[192:195], v[152:155], v[36:39]
	v_mfma_f32_16x16x32_bf16 v[20:23], v[192:195], v[160:163], v[20:23]
	v_mfma_f32_16x16x32_bf16 v[20:23], v[196:199], v[164:167], v[20:23]
	v_mfma_f32_16x16x32_bf16 v[16:19], v[212:215], v[164:167], v[16:19]
	v_mfma_f32_16x16x32_bf16 v[16:19], v[200:203], v[160:163], v[16:19]
	v_mfma_f32_16x16x32_bf16 v[0:3], v[200:203], v[168:171], v[0:3]
	v_mfma_f32_16x16x32_bf16 v[0:3], v[212:215], v[172:175], v[0:3]
	v_mfma_f32_16x16x32_bf16 v[4:7], v[196:199], v[172:175], v[4:7]
	v_mfma_f32_16x16x32_bf16 v[4:7], v[192:195], v[168:171], v[4:7]
	s_add_i32 s69, 0, 0x18000
	v_add_u32_e32 v140, s69, v205
	s_barrier
	ds_read_b128 v[128:131], v140
	ds_read_b128 v[132:135], v140 offset:1024
	ds_read_b128 v[136:139], v140 offset:2048
	ds_read_b128 v[140:143], v140 offset:3072
	s_add_u32 s44, s44, 0x40000
	s_addc_u32 s45, s45, 0
	s_mov_b32 m0, s56
	ds_read_b128 v[144:147], v209 offset:32768
	ds_read_b128 v[148:151], v209 offset:33792
	ds_read_b128 v[152:155], v209 offset:34816
	ds_read_b128 v[156:159], v209 offset:35840
	ds_read_b128 v[160:163], v209 offset:36864
	ds_read_b128 v[164:167], v209 offset:37888
	ds_read_b128 v[168:171], v209 offset:38912
	ds_read_b128 v[172:175], v209 offset:39936
	global_load_lds_dwordx4 v176, s[44:45]
	s_mov_b32 m0, s57
	s_nop 0
	global_load_lds_dwordx4 v180, s[44:45]
	s_waitcnt lgkmcnt(8)
	s_barrier
	s_waitcnt lgkmcnt(0)
	s_waitcnt lgkmcnt(0)
	v_mfma_f32_16x16x32_bf16 v[124:127], v[128:131], v[144:147], v[124:127]
	v_mfma_f32_16x16x32_bf16 v[124:127], v[132:135], v[148:151], v[124:127]
	v_mfma_f32_16x16x32_bf16 v[120:123], v[140:143], v[148:151], v[120:123]
	v_mfma_f32_16x16x32_bf16 v[120:123], v[136:139], v[144:147], v[120:123]
	v_mfma_f32_16x16x32_bf16 v[104:107], v[136:139], v[152:155], v[104:107]
	v_mfma_f32_16x16x32_bf16 v[104:107], v[140:143], v[156:159], v[104:107]
	v_mfma_f32_16x16x32_bf16 v[108:111], v[132:135], v[156:159], v[108:111]
	v_mfma_f32_16x16x32_bf16 v[108:111], v[128:131], v[152:155], v[108:111]
	v_mfma_f32_16x16x32_bf16 v[92:95], v[128:131], v[160:163], v[92:95]
	v_mfma_f32_16x16x32_bf16 v[92:95], v[132:135], v[164:167], v[92:95]
	v_mfma_f32_16x16x32_bf16 v[88:91], v[140:143], v[164:167], v[88:91]
	v_mfma_f32_16x16x32_bf16 v[88:91], v[136:139], v[160:163], v[88:91]
	v_mfma_f32_16x16x32_bf16 v[72:75], v[136:139], v[168:171], v[72:75]
	v_mfma_f32_16x16x32_bf16 v[72:75], v[140:143], v[172:175], v[72:75]
	v_mfma_f32_16x16x32_bf16 v[76:79], v[132:135], v[172:175], v[76:79]
	v_mfma_f32_16x16x32_bf16 v[76:79], v[128:131], v[168:171], v[76:79]
	s_barrier
	s_add_i32 s44, 0, 0x1c000
	s_add_i32 s45, s69, s51
	v_add_u32_e32 v211, s44, v205
	v_lshl_add_u64 v[216:217], v[216:217], 0, s[18:19]
	s_mov_b32 m0, s45
	ds_read_b128 v[192:195], v211
	ds_read_b128 v[196:199], v211 offset:1024
	ds_read_b128 v[200:203], v211 offset:2048
	ds_read_b128 v[212:215], v211 offset:3072
	global_load_lds_dwordx4 v[216:217], off
	v_lshl_add_u64 v[216:217], v[218:219], 0, s[18:19]
	s_add_i32 m0, s45, 0x2000
	s_nop 0
	global_load_lds_dwordx4 v[216:217], off
	s_barrier
	s_waitcnt lgkmcnt(0)
	s_waitcnt lgkmcnt(0)
	v_mfma_f32_16x16x32_bf16 v[116:119], v[192:195], v[144:147], v[116:119]
	v_mfma_f32_16x16x32_bf16 v[116:119], v[196:199], v[148:151], v[116:119]
	v_mfma_f32_16x16x32_bf16 v[112:115], v[212:215], v[148:151], v[112:115]
	v_mfma_f32_16x16x32_bf16 v[112:115], v[200:203], v[144:147], v[112:115]
	v_mfma_f32_16x16x32_bf16 v[96:99], v[200:203], v[152:155], v[96:99]
	v_mfma_f32_16x16x32_bf16 v[96:99], v[212:215], v[156:159], v[96:99]
	v_mfma_f32_16x16x32_bf16 v[100:103], v[196:199], v[156:159], v[100:103]
	v_mfma_f32_16x16x32_bf16 v[100:103], v[192:195], v[152:155], v[100:103]
	v_mfma_f32_16x16x32_bf16 v[84:87], v[192:195], v[160:163], v[84:87]
	v_mfma_f32_16x16x32_bf16 v[84:87], v[196:199], v[164:167], v[84:87]
	v_mfma_f32_16x16x32_bf16 v[80:83], v[212:215], v[164:167], v[80:83]
	v_mfma_f32_16x16x32_bf16 v[80:83], v[200:203], v[160:163], v[80:83]
	v_mfma_f32_16x16x32_bf16 v[64:67], v[200:203], v[168:171], v[64:67]
	v_mfma_f32_16x16x32_bf16 v[64:67], v[212:215], v[172:175], v[64:67]
	v_mfma_f32_16x16x32_bf16 v[68:71], v[196:199], v[172:175], v[68:71]
	v_mfma_f32_16x16x32_bf16 v[68:71], v[192:195], v[168:171], v[68:71]
	s_mov_b32 m0, s63
	v_lshl_add_u64 v[216:217], v[220:221], 0, s[18:19]
	s_barrier
	ds_read_b128 v[144:147], v209 offset:49152
	ds_read_b128 v[148:151], v209 offset:50176
	ds_read_b128 v[152:155], v209 offset:51200
	ds_read_b128 v[156:159], v209 offset:52224
	ds_read_b128 v[160:163], v209 offset:53248
	ds_read_b128 v[164:167], v209 offset:54272
	ds_read_b128 v[168:171], v209 offset:55296
	ds_read_b128 v[172:175], v209 offset:56320
	global_load_lds_dwordx4 v[216:217], off
	v_lshl_add_u64 v[216:217], v[222:223], 0, s[18:19]
	s_mov_b32 m0, s64
	s_nop 0
	global_load_lds_dwordx4 v[216:217], off
	s_barrier
; __device__ __forceinline__ unsigned cvt_pk_bf16(float lo, float hi) { unsigned r; asm volatile("v_cvt_pk_bf16_f32 %0, %1, %2" : "=v"(r) : "v"(lo), "v"(hi)); return r; }
; __device__ __forceinline__ float x16_sum(float x) { auto s = __builtin_amdgcn_permlane16_swap(__float_as_uint(x), __float_as_uint(x), false, false); return __uint_as_float(s[0]) + __uint_as_float(s[1]); }
; #define PG8_WAIT_V(n) asm volatile("s_waitcnt vmcnt(" #n ")" ::: "memory")
; template <class Epi, class Ptrs>
; __device__ __forceinline__ void gemm_phase(LAS unsigned char* lds, const int K, const StaticOrder& S, const Ptrs& P, const Epi& E) {
;     ...
;             PG8_BAR; PG8_WAIT_L(0); PG8_MMA(1, 0, At, B0); PG8_BAR; PG8_SCHED;
;             PG8_STAGE(PG8_SB(1, 1), b3 + hstep, voffB);
;             PG8_WAIT_V(6); PG8_BAR; PG8_MMA(1, 1, At, B1); PG8_BAR;
;     __device__ __forceinline__ void operator()(const f32x4 (&acc)[2][2][4][2], const Unit& u, int ui, int wr, int wc, int fr, int fq) const {
;         const int row0 = u.pm * 256 + wr * 64 + fr, col0 = u.pn * 256 + wc * 32 + 8 * fq;
;         const float* xb0 = (u.pm * 256 < MP) ? xp : xs - (size_t)MP * DM;
; #pragma unroll
;         for (int ai = 0; ai < 2; ++ai) {
;             f32x4 xv[4][2][2];
; #pragma unroll
;             for (int m = 0; m < 4; ++m)
; #pragma unroll
;                 for (int bj = 0; bj < 2; ++bj) { const float* p = xb0 + (size_t)(row0 + ai * 128 + m * 16) * DM + col0 + bj * 128; xv[m][bj][0] = *(const f32x4*)p; xv[m][bj][1] = *(const f32x4*)(p + 4); }
; #pragma unroll
;             for (int m = 0; m < 4; ++m) { const int row = row0 + ai * 128 + m * 16; const size_t off = (size_t)row * DM + col0; float ss = 0.f;
; #pragma unroll
;                 for (int bj = 0; bj < 2; ++bj) {
;                     const f32x4 v0 = acc[ai][bj][m][0] + xv[m][bj][0], v1 = acc[ai][bj][m][1] + xv[m][bj][1];
;                     u32x4 w; w.x = cvt_pk_bf16(v0[0], v0[1]); w.y = cvt_pk_bf16(v0[2], v0[3]); w.z = cvt_pk_bf16(v1[0], v1[1]); w.w = cvt_pk_bf16(v1[2], v1[3]);
;                     *(u32x4*)(xb + off + bj * 128) = w;
;                     ss += (v0[0] * v0[0] + v0[1] * v0[1]) + (v0[2] * v0[2] + v0[3] * v0[3]) + (v1[0] * v1[0] + v1[1] * v1[1]) + (v1[2] * v1[2] + v1[3] * v1[3]); }
;                 ss = x32_sum(x16_sum(ss));
;                 if (fq == 0) part[(size_t)row * 16 + u.pn * 4 + wc] = ss; }
	s_waitcnt lgkmcnt(0)
	s_waitcnt lgkmcnt(0)
	v_mfma_f32_16x16x32_bf16 v[60:63], v[128:131], v[144:147], v[60:63]
	v_mfma_f32_16x16x32_bf16 v[60:63], v[132:135], v[148:151], v[60:63]
	v_mfma_f32_16x16x32_bf16 v[56:59], v[140:143], v[148:151], v[56:59]
	v_mfma_f32_16x16x32_bf16 v[56:59], v[136:139], v[144:147], v[56:59]
	v_mfma_f32_16x16x32_bf16 v[40:43], v[136:139], v[152:155], v[40:43]
	v_mfma_f32_16x16x32_bf16 v[40:43], v[140:143], v[156:159], v[40:43]
	v_mfma_f32_16x16x32_bf16 v[44:47], v[132:135], v[156:159], v[44:47]
	v_mfma_f32_16x16x32_bf16 v[44:47], v[128:131], v[152:155], v[44:47]
	v_mfma_f32_16x16x32_bf16 v[28:31], v[128:131], v[160:163], v[28:31]
	v_mfma_f32_16x16x32_bf16 v[28:31], v[132:135], v[164:167], v[28:31]
	v_mfma_f32_16x16x32_bf16 v[24:27], v[140:143], v[164:167], v[24:27]
	v_mfma_f32_16x16x32_bf16 v[24:27], v[136:139], v[160:163], v[24:27]
	v_mfma_f32_16x16x32_bf16 v[8:11], v[136:139], v[168:171], v[8:11]
	v_mfma_f32_16x16x32_bf16 v[8:11], v[140:143], v[172:175], v[8:11]
	v_mfma_f32_16x16x32_bf16 v[12:15], v[132:135], v[172:175], v[12:15]
	v_mfma_f32_16x16x32_bf16 v[12:15], v[128:131], v[168:171], v[12:15]
	s_barrier
	s_add_u32 s42, s42, 0x40080
	s_addc_u32 s43, s43, 0
	s_add_i32 s44, s44, s51
	s_mov_b32 m0, s44
	s_nop 0
	global_load_lds_dwordx4 v178, s[42:43]
	s_add_i32 m0, s44, 0x2000
	s_nop 0
	global_load_lds_dwordx4 v182, s[42:43]
	s_waitcnt vmcnt(6)
	s_barrier
	v_mfma_f32_16x16x32_bf16 v[52:55], v[192:195], v[144:147], v[52:55]
	v_mfma_f32_16x16x32_bf16 v[52:55], v[196:199], v[148:151], v[52:55]
	v_mfma_f32_16x16x32_bf16 v[48:51], v[212:215], v[148:151], v[48:51]
	v_mfma_f32_16x16x32_bf16 v[48:51], v[200:203], v[144:147], v[48:51]
	v_mfma_f32_16x16x32_bf16 v[32:35], v[200:203], v[152:155], v[32:35]
	v_mfma_f32_16x16x32_bf16 v[32:35], v[212:215], v[156:159], v[32:35]
	v_mfma_f32_16x16x32_bf16 v[36:39], v[196:199], v[156:159], v[36:39]
	v_mfma_f32_16x16x32_bf16 v[36:39], v[192:195], v[152:155], v[36:39]
	v_mfma_f32_16x16x32_bf16 v[20:23], v[192:195], v[160:163], v[20:23]
	v_mfma_f32_16x16x32_bf16 v[20:23], v[196:199], v[164:167], v[20:23]
	v_mfma_f32_16x16x32_bf16 v[16:19], v[212:215], v[164:167], v[16:19]
	v_mfma_f32_16x16x32_bf16 v[16:19], v[200:203], v[160:163], v[16:19]
	v_mfma_f32_16x16x32_bf16 v[0:3], v[200:203], v[168:171], v[0:3]
	v_mfma_f32_16x16x32_bf16 v[0:3], v[212:215], v[172:175], v[0:3]
	v_mfma_f32_16x16x32_bf16 v[4:7], v[196:199], v[172:175], v[4:7]
	v_mfma_f32_16x16x32_bf16 v[4:7], v[192:195], v[168:171], v[4:7]
	s_add_i32 s41, s41, 2
	s_add_u32 s38, s38, 0x100
	s_addc_u32 s39, s39, 0
	s_add_u32 s21, s21, 0x100
	s_addc_u32 s23, s23, 0
	s_cmp_gt_u32 s41, 13
	s_barrier
	s_cbranch_scc0 .LBB0_353
	s_nop 0
	s_nop 0
	s_nop 0
	s_nop 0
	s_nop 0
	s_nop 0
	s_nop 0
	s_nop 0
	s_nop 0
	s_nop 0
	s_nop 0
	s_nop 0
	s_nop 0
	s_nop 0
	s_nop 0
	s_nop 0
	s_nop 0
	s_nop 0
	s_nop 0
	s_nop 0
	s_nop 0
	s_nop 0
	s_nop 0
	s_nop 0
	s_nop 0
	s_nop 0
	s_nop 0
	s_nop 0
	s_cmpk_lt_i32 s40, 0x80
	v_lshl_add_u32 v194, s40, 8, v204
	v_lshl_or_b32 v192, s12, 8, v206
	s_cselect_b32 s21, s37, s61
	s_cselect_b32 s23, s36, s60
	v_mov_b32_e32 v128, s23
	v_mov_b32_e32 v129, s21
	v_ashrrev_i32_e32 v193, 31, v192
	v_ashrrev_i32_e32 v195, 31, v194
	v_lshl_add_u64 v[196:197], v[192:193], 2, v[128:129]
	v_lshlrev_b64 v[128:129], 12, v[194:195]
	v_or_b32_e32 v202, 16, v194
	v_or_b32_e32 v200, 32, v194
	v_or_b32_e32 v198, 48, v194
	v_lshl_add_u64 v[128:129], v[196:197], 0, v[128:129]
	v_ashrrev_i32_e32 v203, 31, v202
	v_ashrrev_i32_e32 v201, 31, v200
	v_ashrrev_i32_e32 v199, 31, v198
	global_load_dwordx4 v[212:215], v[128:129], off
	global_load_dwordx4 v[216:219], v[128:129], off offset:16
	global_load_dwordx4 v[220:223], v[128:129], off offset:512
	global_load_dwordx4 v[224:227], v[128:129], off offset:528
	v_lshlrev_b64 v[128:129], 12, v[202:203]
	v_lshlrev_b64 v[130:131], 12, v[200:201]
	v_lshlrev_b64 v[132:133], 12, v[198:199]
	v_lshl_add_u64 v[128:129], v[196:197], 0, v[128:129]
	v_lshl_add_u64 v[130:131], v[196:197], 0, v[130:131]
	v_lshl_add_u64 v[132:133], v[196:197], 0, v[132:133]
	global_load_dwordx4 v[168:171], v[128:129], off offset:16
	global_load_dwordx4 v[172:175], v[128:129], off
	global_load_dwordx4 v[160:163], v[128:129], off offset:528
	global_load_dwordx4 v[164:167], v[128:129], off offset:512
	global_load_dwordx4 v[152:155], v[130:131], off offset:16
	global_load_dwordx4 v[156:159], v[130:131], off
	global_load_dwordx4 v[144:147], v[130:131], off offset:528
	global_load_dwordx4 v[148:151], v[130:131], off offset:512
	global_load_dwordx4 v[136:139], v[132:133], off offset:16
	global_load_dwordx4 v[140:143], v[132:133], off
	s_nop 0
	global_load_dwordx4 v[128:131], v[132:133], off offset:528
	s_nop 0
	global_load_dwordx4 v[132:135], v[132:133], off offset:512
	v_lshlrev_b64 v[228:229], 11, v[194:195]
	v_lshl_add_u64 v[228:229], s[14:15], 0, v[228:229]
	v_lshl_add_u64 v[228:229], v[192:193], 1, v[228:229]
	s_lshl_b32 s38, s12, 2
	s_ashr_i32 s39, s38, 31
	s_waitcnt vmcnt(0)
	v_pk_add_f32 v[126:127], v[126:127], v[214:215]
	v_pk_add_f32 v[124:125], v[124:125], v[212:213]
	v_pk_add_f32 v[118:119], v[118:119], v[222:223]
	v_pk_add_f32 v[116:117], v[116:117], v[220:221]
	v_pk_add_f32 v[120:121], v[120:121], v[216:217]
	v_pk_add_f32 v[214:215], v[112:113], v[224:225]
	v_cvt_pk_bf16_f32 v112, v124, v125
	v_cvt_pk_bf16_f32 v113, v126, v127
	v_mul_f32_e32 v125, v125, v125
	v_mul_f32_e32 v127, v127, v127
	v_mul_f32_e32 v211, v117, v117
	v_mul_f32_e32 v216, v119, v119
	v_pk_add_f32 v[122:123], v[122:123], v[218:219]
	v_pk_add_f32 v[212:213], v[114:115], v[226:227]
	v_cvt_pk_bf16_f32 v114, v120, v121
	v_cvt_pk_bf16_f32 v115, v122, v123
	v_mul_f32_e32 v121, v121, v121
	v_mul_f32_e32 v217, v215, v215
	global_store_dwordx4 v[228:229], v[112:115], off
	v_fmac_f32_e32 v125, v124, v124
	v_fmac_f32_e32 v127, v126, v126
	v_cvt_pk_bf16_f32 v112, v116, v117
	v_fmac_f32_e32 v211, v116, v116
	v_fmac_f32_e32 v216, v118, v118
	v_mul_f32_e32 v123, v123, v123
	v_mul_f32_e32 v218, v213, v213
	v_fmac_f32_e32 v121, v120, v120
	v_cvt_pk_bf16_f32 v113, v118, v119
	v_cvt_pk_bf16_f32 v114, v214, v215
	v_cvt_pk_bf16_f32 v115, v212, v213
	v_fmac_f32_e32 v217, v214, v214
	v_add_f32_e32 v116, v125, v127
	global_store_dwordx4 v[228:229], v[112:115], off offset:256
	v_fmac_f32_e32 v123, v122, v122
	v_fmac_f32_e32 v218, v212, v212
	v_add_f32_e32 v112, v211, v216
	v_add_f32_e32 v113, v116, v121
	v_add_f32_e32 v112, v112, v217
	v_add_f32_e32 v113, v123, v113
	v_add_f32_e32 v112, v218, v112
	v_add_f32_e32 v112, v113, v112
	v_mov_b32_e32 v113, v112
	s_nop 1
	v_permlane16_swap_b32_e32 v112, v113
	v_add_f32_e32 v112, v112, v113
	v_mov_b32_e32 v113, v112
	s_nop 1
	v_permlane32_swap_b32_e32 v112, v113
	s_and_saveexec_b64 s[40:41], s[6:7]
	s_cbranch_execz .LBB0_356
	v_lshlrev_b64 v[114:115], 6, v[194:195]
	v_lshl_add_u64 v[114:115], s[16:17], 0, v[114:115]
	v_lshl_add_u64 v[114:115], s[38:39], 2, v[114:115]
	s_lshl_b32 s12, s62, 2
	v_lshl_add_u64 v[114:115], v[114:115], 0, s[12:13]
	v_add_f32_e32 v112, v112, v113
	global_store_dword v[114:115], v112, off

; #define PG8_WAIT_V(n) asm volatile("s_waitcnt vmcnt(" #n ")" ::: "memory")
; #define PG8_BAR __builtin_amdgcn_s_barrier()
; template <class Epi, class Ptrs>
; __device__ __forceinline__ void gemm_phase(LAS unsigned char* lds, const int K, const StaticOrder& S, const Ptrs& P, const Epi& E) {
;     ...
;     PG8_WAIT_V(0);
;     if (wr == 0) PG8_BAR;
;     PG8_BAR;
.LBB0_370:
	s_waitcnt vmcnt(0)
	s_setprio 0
	s_cmpk_gt_u32 s46, 0xff
	s_cbranch_scc1 .LBB0_372
	s_barrier

; #define PG8_STAGE(bufoff, gbase, voff) do { _Pragma("unroll") for (int _i = 0; _i < 2; ++_i) \
;         __builtin_amdgcn_global_load_lds((const unsigned*)((const char*)(gbase) + (voff)[_i]), (LAS unsigned*)(lds + (bufoff) + ldsw + _i * 8192), 16, 0, 0); } while (0)
; #define PG8_WAIT_V(n) asm volatile("s_waitcnt vmcnt(" #n ")" ::: "memory")
; #define PG8_BAR __builtin_amdgcn_s_barrier()
;     __device__ bool next(int i, Unit& u) const {
;         if (rev && i >= rev) return false;
;         const long L = (long)(rev ? rev - 1 - i : i) * G + c; if (L >= nwg) return false;
;         int wgid = (int)L; { const int q = nwg / NXCD, r = nwg % NXCD, xcd = wgid % NXCD, off = wgid / NXCD; wgid = (xcd < r ? xcd * (q + 1) : r * (q + 1) + (xcd - r) * q) + off; }
;         const int nig = WGM * nN, gid = wgid / nig, fm = gid * WGM, gsz = (nM - fm) < WGM ? (nM - fm) : WGM;
;         u.pm = fm + ((wgid % nig) % gsz); u.pn = (wgid % nig) / gsz; return true;
; template <class Epi, class Ptrs>
; __device__ __forceinline__ void gemm_phase(LAS unsigned char* lds, const int K, const StaticOrder& S, const Ptrs& P, const Epi& E) {
;     ...
;     PG8_STAGE(PG8_SB(0, 0), cB, voffB); PG8_STAGE(PG8_SA(0, 0), cA, voffA); PG8_STAGE(PG8_SB(0, 1), cB + hstep, voffB); PG8_STAGE(PG8_SA(0, 1), cA + hstep, voffA);
;     if (wr == 1) PG8_BAR;
;     PG8_WAIT_V(4); PG8_BAR;
;     PG8_STAGE(PG8_SB(1, 0), cB + kstep, voffB); PG8_STAGE(PG8_SA(1, 0), cA + kstep, voffA); PG8_STAGE(PG8_SB(1, 1), cB + hstep + kstep, voffB);
;     PG8_WAIT_V(6); PG8_BAR;
.LBB0_427:
	s_nop 0
	s_nop 0
	s_nop 0
	s_nop 0
	s_nop 0
	s_nop 0
	s_nop 0
	s_nop 0
	s_nop 0
	s_nop 0
	s_nop 0
	s_nop 0
	s_nop 0
	s_nop 0
	s_nop 0
	s_nop 0
	s_nop 0
	s_nop 0
	s_nop 0
	s_nop 0
	s_nop 0
	s_nop 0
	s_nop 0
	s_nop 0
	s_nop 0
	s_nop 0
	s_nop 0
	s_nop 0
	s_nop 0
	s_nop 0
	s_nop 0
	s_nop 0
	s_nop 0
	s_nop 0
	s_nop 0
	s_nop 0
	s_nop 0
	s_nop 0
	s_nop 0
	s_nop 0
	s_nop 0
	s_nop 0
	s_nop 0
	s_nop 0
	s_nop 0
	s_nop 0
	s_nop 0
	s_nop 0
	s_nop 0
	s_nop 0
	s_nop 0
	s_nop 0
	s_nop 0
	s_add_u32 s10, s28, 0xe000000
	s_addc_u32 s11, s29, 0
	s_lshl_b32 s4, s4, 5
	s_mov_b64 s[12:13], 0x80
	s_and_b32 s15, s4, 0x60
	s_add_i32 m0, s39, 0x18000
	v_lshl_add_u64 v[6:7], v[6:7], 0, s[12:13]
	s_ashr_i32 s60, s3, 31
	s_lshl_b32 s14, s1, 13
	s_lshl_b32 s16, s15, 7
	s_waitcnt vmcnt(4)
	s_barrier
	global_load_lds_dwordx4 v[6:7], off
	v_lshl_add_u64 v[4:5], v[4:5], 0, s[12:13]
	s_add_i32 m0, s39, 0x1a000
	s_add_i32 s61, s39, 0x8000
	s_add_i32 s62, s39, 0xa000
	global_load_lds_dwordx4 v[4:5], off
	v_lshl_add_u64 v[2:3], v[2:3], 0, s[12:13]
	s_mov_b32 m0, s61
	s_add_u32 s4, s42, 0x40080
	global_load_lds_dwordx4 v[2:3], off
	v_lshl_add_u64 v[0:1], v[0:1], 0, s[12:13]
	s_mov_b32 m0, s62
	s_addc_u32 s5, s43, 0
	global_load_lds_dwordx4 v[0:1], off
	s_add_i32 m0, s39, 0x1c000
	v_lshl_add_u64 v[0:1], s[4:5], 0, v[130:131]
	global_load_lds_dwordx4 v[0:1], off
	v_lshl_add_u64 v[0:1], s[4:5], 0, v[134:135]
	s_add_i32 m0, s39, 0x1e000
	s_sext_i32_i8 s69, s0
	global_load_lds_dwordx4 v[0:1], off
	v_and_b32_e32 v0, 15, v208
	v_lshlrev_b32_e32 v1, 1, v11
	v_lshlrev_b32_e32 v2, 6, v208
	s_movk_i32 s0, 0x3c0
	v_lshlrev_b32_e32 v3, 2, v208
	v_and_or_b32 v2, v2, s0, v1
	v_and_b32_e32 v3, 32, v3
	v_lshl_or_b32 v146, s1, 6, v0
	v_lshl_or_b32 v0, v0, 6, v1
	v_lshlrev_b32_e32 v1, 8, v208
	v_bitop3_b32 v147, s16, v2, v3 bitop3:0xf6
	v_and_b32_e32 v1, 0x38000, v1
	v_lshlrev_b32_e32 v2, 11, v10
	v_or3_b32 v1, v8, v1, v2
	v_add_u32_e32 v136, v1, v9
	v_lshlrev_b32_e32 v1, 4, v12
	s_waitcnt vmcnt(6)
	v_and_b32_e32 v1, 0x78000, v1
	v_bitop3_b32 v0, v0, s14, v3 bitop3:0xde
	v_or3_b32 v1, v8, v1, v2
	s_add_i32 s63, 0, 0x10000
	s_add_i32 s64, 0, 0x14000
	v_or_b32_e32 v148, s15, v11
	v_mov_b32_e32 v137, v131
	v_add_u32_e32 v138, v1, v9
	v_mov_b32_e32 v139, v131
	v_mov_b64_e32 v[140:141], 0x1800
	v_mov_b64_e32 v[142:143], 0x17ff
	v_add_u32_e32 v149, s63, v147
	v_add_u32_e32 v150, 0, v0
	v_add_u32_e32 v151, s64, v147
	s_mov_b64 s[14:15], 0x100000
	s_mov_b32 s65, 0x100000
	s_mov_b64 s[16:17], 0x120000
	s_mov_b32 s66, 0x120000
	s_mov_b64 s[18:19], 0x140000
	s_mov_b32 s67, 0x140000
	s_mov_b64 s[20:21], 0x160000
	s_mov_b32 s68, 0x160000
	s_cmpk_lt_u32 s46, 0x100
	s_cbranch_scc1 .Lsprio_2
	s_setprio 1
.Lsprio_2:
	s_barrier
.LBB0_428:
	s_add_i32 s59, s59, 1
	s_sub_i32 s74, 23, s59
	s_cmpk_eq_i32 s3, 0x100
	s_cselect_b32 s74, s74, s59
	s_mul_i32 s0, s74, s60
	s_mul_hi_u32 s1, s74, s3
	s_add_i32 s1, s1, s0
	s_mul_i32 s0, s74, s3
	s_add_u32 s36, s0, s2
	s_addc_u32 s37, s1, s54
	v_cmp_gt_i64_e64 s[4:5], s[36:37], v[142:143]
	v_cmp_lt_i64_e64 s[0:1], s[36:37], v[140:141]
	s_and_b64 vcc, exec, s[4:5]
	s_cbranch_vccnz .LBB0_430
	s_ashr_i32 s22, s36, 31
	s_lshr_b32 s22, s22, 29
	s_add_i32 s22, s36, s22
	s_ashr_i32 s23, s22, 3
	s_and_b32 s22, s22, -8
	s_sub_i32 s22, s36, s22
	s_cmp_lt_i32 s22, 0
	s_cselect_b32 s24, s55, 0x300
	s_mul_i32 s22, s22, s24
	s_add_i32 s22, s22, s23
	s_ashr_i32 s23, s22, 31
	s_lshr_b32 s23, s23, 25
	s_add_i32 s23, s22, s23
	s_ashr_i32 s24, s23, 7
	s_lshl_b32 s24, s24, 3
	s_sub_i32 s25, 0x180, s24
	s_min_i32 s25, s25, 8
	s_abs_i32 s36, s25
	v_cvt_f32_u32_e32 v0, s36
	s_sub_i32 s44, 0, s36
	s_and_b32 s23, s23, 0xffffff80
	s_sub_i32 s23, s22, s23
	v_rcp_iflag_f32_e32 v0, v0
	s_abs_i32 s22, s23
	s_xor_b32 s37, s23, s25
	s_ashr_i32 s37, s37, 31
	v_mul_f32_e32 v0, 0x4f7ffffe, v0
	v_cvt_u32_f32_e32 v0, v0
	s_nop 0
	v_readfirstlane_b32 s45, v0
	s_mul_i32 s44, s44, s45
	s_mul_hi_u32 s44, s45, s44
	s_add_i32 s45, s45, s44
	s_mul_hi_u32 s44, s22, s45
	s_mul_i32 s45, s44, s36
	s_sub_i32 s22, s22, s45
	s_add_i32 s70, s44, 1
	s_sub_i32 s45, s22, s36
	s_cmp_ge_u32 s22, s36
	s_cselect_b32 s44, s70, s44
	s_cselect_b32 s22, s45, s22
	s_add_i32 s45, s44, 1
	s_cmp_ge_u32 s22, s36
	s_cselect_b32 s22, s45, s44
	s_xor_b32 s22, s22, s37
	s_sub_i32 s22, s22, s37
	s_mul_i32 s25, s22, s25
	s_sub_i32 s23, s23, s25
	s_add_i32 s24, s24, s23

; #define PG8_STAGE(bufoff, gbase, voff) do { _Pragma("unroll") for (int _i = 0; _i < 2; ++_i) \
;         __builtin_amdgcn_global_load_lds((const unsigned*)((const char*)(gbase) + (voff)[_i]), (LAS unsigned*)(lds + (bufoff) + ldsw + _i * 8192), 16, 0, 0); } while (0)
; #define PG8_LDA(dst, b, h) do { _Pragma("unroll") for (int m = 0; m < 4; ++m) _Pragma("unroll") for (int k = 0; k < 2; ++k) dst[m][k] = *(const LAS bf16x8*)(lds + PG8_SA(b, h) + aoff + m * 2048 + k * 1024); } while (0)
; #define PG8_LDB(dst, b, h) do { _Pragma("unroll") for (int n = 0; n < 2; ++n) _Pragma("unroll") for (int k = 0; k < 2; ++k) dst[n][k] = *(const LAS bf16x8*)(lds + PG8_SB(b, h) + boff + n * 2048 + k * 1024); } while (0)
; #define PG8_MMA(ai, bj, At, Bt) do { __builtin_amdgcn_s_setprio(1); _Pragma("unroll") for (int m = 0; m < 4; ++m) _Pragma("unroll") for (int n = 0; n < 2; ++n) _Pragma("unroll") for (int k = 0; k < 2; ++k) \
;         acc[ai][bj][m][n] = __builtin_amdgcn_mfma_f32_16x16x32_bf16(Bt[n][k], At[m][k], acc[ai][bj][m][n], 0, 0, 0); __builtin_amdgcn_s_setprio(0); } while (0)
; #define PG8_WAIT_V(n) asm volatile("s_waitcnt vmcnt(" #n ")" ::: "memory")
; #define PG8_WAIT_L(n) asm volatile("s_waitcnt lgkmcnt(" #n ")" ::: "memory")
; template <class Epi, class Ptrs>
; __device__ __forceinline__ void gemm_phase(LAS unsigned char* lds, const int K, const StaticOrder& S, const Ptrs& P, const Epi& E) {
;     ...
;         for (int t = 0; t < nt; t += 2) {
;             const bool last = (t == nt - 2);
;             const char* a1 = cA + (size_t)(t + 1) * kstep;
;             const char* a2 = last ? nA : cA + (size_t)(t + 2) * kstep; const char* b2 = last ? nB : cB + (size_t)(t + 2) * kstep;
;             const char* a3 = a2 + kstep; const char* b3 = b2 + kstep;
;             PG8_LDB(B0, 0, 0); PG8_SCHED; PG8_LDA(At, 0, 0); PG8_STAGE(PG8_SA(1, 1), a1 + hstep, voffA);
;             PG8_WAIT_L(8); PG8_BAR; PG8_WAIT_L(0); PG8_MMA(0, 0, At, B0); PG8_BAR; PG8_SCHED;
;             PG8_LDB(B1, 0, 1); PG8_STAGE(PG8_SB(0, 0), b2, voffB);
;             PG8_BAR; PG8_WAIT_L(0); PG8_MMA(0, 1, At, B1); PG8_BAR;
;             PG8_LDA(At, 0, 1); PG8_STAGE(PG8_SA(0, 0), a2, voffA);
;             PG8_BAR; PG8_WAIT_L(0); PG8_MMA(1, 0, At, B0); PG8_BAR; PG8_SCHED;
;             PG8_STAGE(PG8_SB(0, 1), b2 + hstep, voffB);
;             PG8_WAIT_V(6); PG8_BAR; PG8_MMA(1, 1, At, B1); PG8_BAR;
.LBB0_433:
	ds_read_b128 v[152:155], v149
	ds_read_b128 v[156:159], v149 offset:1024
	ds_read_b128 v[160:163], v149 offset:2048
	ds_read_b128 v[164:167], v149 offset:3072
	s_add_u32 s42, s40, 0xfffc0080
	s_addc_u32 s43, s41, -1
	s_cmp_eq_u32 s70, 12
	s_cselect_b32 s45, s1, s43
	s_cselect_b32 s44, s0, s42
	s_cselect_b32 s43, s37, s25
	s_cselect_b32 s42, s36, s23
	s_add_i32 m0, s39, 0xc000
	ds_read_b128 v[168:171], v150
	ds_read_b128 v[172:175], v150 offset:1024
	ds_read_b128 v[176:179], v150 offset:2048
	ds_read_b128 v[180:183], v150 offset:3072
	ds_read_b128 v[184:187], v150 offset:4096
	ds_read_b128 v[188:191], v150 offset:5120
	ds_read_b128 v[192:195], v150 offset:6144
	ds_read_b128 v[196:199], v150 offset:7168
	global_load_lds_dwordx4 v136, s[40:41]
	s_add_i32 m0, s39, 0xe000
	s_nop 0
	global_load_lds_dwordx4 v138, s[40:41]
	s_waitcnt lgkmcnt(8)
	s_barrier
	s_waitcnt lgkmcnt(0)
	s_waitcnt lgkmcnt(0)
	v_mfma_f32_16x16x32_bf16 v[124:127], v[152:155], v[168:171], v[124:127]
	v_mfma_f32_16x16x32_bf16 v[124:127], v[156:159], v[172:175], v[124:127]
	v_mfma_f32_16x16x32_bf16 v[120:123], v[164:167], v[172:175], v[120:123]
	v_mfma_f32_16x16x32_bf16 v[120:123], v[160:163], v[168:171], v[120:123]
	v_mfma_f32_16x16x32_bf16 v[104:107], v[160:163], v[176:179], v[104:107]
	v_mfma_f32_16x16x32_bf16 v[104:107], v[164:167], v[180:183], v[104:107]
	v_mfma_f32_16x16x32_bf16 v[108:111], v[156:159], v[180:183], v[108:111]
	v_mfma_f32_16x16x32_bf16 v[108:111], v[152:155], v[176:179], v[108:111]
	v_mfma_f32_16x16x32_bf16 v[92:95], v[152:155], v[184:187], v[92:95]
	v_mfma_f32_16x16x32_bf16 v[92:95], v[156:159], v[188:191], v[92:95]
	v_mfma_f32_16x16x32_bf16 v[88:91], v[164:167], v[188:191], v[88:91]
	v_mfma_f32_16x16x32_bf16 v[88:91], v[160:163], v[184:187], v[88:91]
	v_mfma_f32_16x16x32_bf16 v[72:75], v[160:163], v[192:195], v[72:75]
	v_mfma_f32_16x16x32_bf16 v[72:75], v[164:167], v[196:199], v[72:75]
	v_mfma_f32_16x16x32_bf16 v[76:79], v[156:159], v[196:199], v[76:79]
	v_mfma_f32_16x16x32_bf16 v[76:79], v[152:155], v[192:195], v[76:79]
	s_barrier
	s_add_i32 s71, s63, s51
	v_lshl_add_u64 v[144:145], s[42:43], 0, v[130:131]
	s_mov_b32 m0, s71
	ds_read_b128 v[200:203], v151
	ds_read_b128 v[204:207], v151 offset:1024
	ds_read_b128 v[210:213], v151 offset:2048
	ds_read_b128 v[214:217], v151 offset:3072
	global_load_lds_dwordx4 v[144:145], off
	v_lshl_add_u64 v[218:219], s[42:43], 0, v[134:135]
	s_add_i32 m0, s71, 0x2000
	s_nop 0
	global_load_lds_dwordx4 v[218:219], off
	s_barrier
	s_waitcnt lgkmcnt(0)
	s_waitcnt lgkmcnt(0)
	v_mfma_f32_16x16x32_bf16 v[116:119], v[200:203], v[168:171], v[116:119]
	v_mfma_f32_16x16x32_bf16 v[116:119], v[204:207], v[172:175], v[116:119]
	v_mfma_f32_16x16x32_bf16 v[112:115], v[214:217], v[172:175], v[112:115]
	v_mfma_f32_16x16x32_bf16 v[112:115], v[210:213], v[168:171], v[112:115]
	v_mfma_f32_16x16x32_bf16 v[96:99], v[210:213], v[176:179], v[96:99]
	v_mfma_f32_16x16x32_bf16 v[96:99], v[214:217], v[180:183], v[96:99]
	v_mfma_f32_16x16x32_bf16 v[100:103], v[204:207], v[180:183], v[100:103]
	v_mfma_f32_16x16x32_bf16 v[100:103], v[200:203], v[176:179], v[100:103]
	v_mfma_f32_16x16x32_bf16 v[84:87], v[200:203], v[184:187], v[84:87]
	v_mfma_f32_16x16x32_bf16 v[84:87], v[204:207], v[188:191], v[84:87]
	v_mfma_f32_16x16x32_bf16 v[80:83], v[214:217], v[188:191], v[80:83]
	v_mfma_f32_16x16x32_bf16 v[80:83], v[210:213], v[184:187], v[80:83]
	v_mfma_f32_16x16x32_bf16 v[64:67], v[210:213], v[192:195], v[64:67]
	v_mfma_f32_16x16x32_bf16 v[64:67], v[214:217], v[196:199], v[64:67]
	v_mfma_f32_16x16x32_bf16 v[68:71], v[204:207], v[196:199], v[68:71]
	v_mfma_f32_16x16x32_bf16 v[68:71], v[200:203], v[192:195], v[68:71]
	s_mov_b32 m0, s39
	v_lshl_add_u64 v[220:221], s[44:45], 0, v[128:129]
	s_barrier
	ds_read_b128 v[168:171], v150 offset:16384
	ds_read_b128 v[172:175], v150 offset:17408
	ds_read_b128 v[176:179], v150 offset:18432
	ds_read_b128 v[180:183], v150 offset:19456
	ds_read_b128 v[184:187], v150 offset:20480
	ds_read_b128 v[188:191], v150 offset:21504
	ds_read_b128 v[192:195], v150 offset:22528
	ds_read_b128 v[196:199], v150 offset:23552
	global_load_lds_dwordx4 v[220:221], off
	v_lshl_add_u64 v[222:223], s[44:45], 0, v[132:133]
	s_mov_b32 m0, s56
	s_nop 0
	global_load_lds_dwordx4 v[222:223], off
	s_barrier
	s_waitcnt lgkmcnt(0)
	s_waitcnt lgkmcnt(0)
	v_mfma_f32_16x16x32_bf16 v[60:63], v[152:155], v[168:171], v[60:63]
	v_mfma_f32_16x16x32_bf16 v[60:63], v[156:159], v[172:175], v[60:63]
	v_mfma_f32_16x16x32_bf16 v[56:59], v[164:167], v[172:175], v[56:59]
	v_mfma_f32_16x16x32_bf16 v[56:59], v[160:163], v[168:171], v[56:59]
	v_mfma_f32_16x16x32_bf16 v[40:43], v[160:163], v[176:179], v[40:43]
	v_mfma_f32_16x16x32_bf16 v[40:43], v[164:167], v[180:183], v[40:43]
	v_mfma_f32_16x16x32_bf16 v[44:47], v[156:159], v[180:183], v[44:47]
	v_mfma_f32_16x16x32_bf16 v[44:47], v[152:155], v[176:179], v[44:47]
	v_mfma_f32_16x16x32_bf16 v[28:31], v[152:155], v[184:187], v[28:31]
	v_mfma_f32_16x16x32_bf16 v[28:31], v[156:159], v[188:191], v[28:31]
	v_mfma_f32_16x16x32_bf16 v[24:27], v[164:167], v[188:191], v[24:27]
	v_mfma_f32_16x16x32_bf16 v[24:27], v[160:163], v[184:187], v[24:27]
	v_mfma_f32_16x16x32_bf16 v[8:11], v[160:163], v[192:195], v[8:11]
	v_mfma_f32_16x16x32_bf16 v[8:11], v[164:167], v[196:199], v[8:11]
	v_mfma_f32_16x16x32_bf16 v[12:15], v[156:159], v[196:199], v[12:15]
	v_mfma_f32_16x16x32_bf16 v[12:15], v[152:155], v[192:195], v[12:15]
	s_barrier
	s_add_u32 s72, s42, 0x40000
	s_addc_u32 s73, s43, 0
	s_add_i32 s71, s64, s51
	s_mov_b32 m0, s71
	s_nop 0
	global_load_lds_dwordx4 v130, s[72:73]
	s_add_i32 m0, s71, 0x2000
	s_nop 0
	global_load_lds_dwordx4 v134, s[72:73]
	s_waitcnt vmcnt(6)
	s_barrier
; #define PG8_STAGE(bufoff, gbase, voff) do { _Pragma("unroll") for (int _i = 0; _i < 2; ++_i) \
;         __builtin_amdgcn_global_load_lds((const unsigned*)((const char*)(gbase) + (voff)[_i]), (LAS unsigned*)(lds + (bufoff) + ldsw + _i * 8192), 16, 0, 0); } while (0)
; #define PG8_LDA(dst, b, h) do { _Pragma("unroll") for (int m = 0; m < 4; ++m) _Pragma("unroll") for (int k = 0; k < 2; ++k) dst[m][k] = *(const LAS bf16x8*)(lds + PG8_SA(b, h) + aoff + m * 2048 + k * 1024); } while (0)
; #define PG8_LDB(dst, b, h) do { _Pragma("unroll") for (int n = 0; n < 2; ++n) _Pragma("unroll") for (int k = 0; k < 2; ++k) dst[n][k] = *(const LAS bf16x8*)(lds + PG8_SB(b, h) + boff + n * 2048 + k * 1024); } while (0)
; #define PG8_MMA(ai, bj, At, Bt) do { __builtin_amdgcn_s_setprio(1); _Pragma("unroll") for (int m = 0; m < 4; ++m) _Pragma("unroll") for (int n = 0; n < 2; ++n) _Pragma("unroll") for (int k = 0; k < 2; ++k) \
;         acc[ai][bj][m][n] = __builtin_amdgcn_mfma_f32_16x16x32_bf16(Bt[n][k], At[m][k], acc[ai][bj][m][n], 0, 0, 0); __builtin_amdgcn_s_setprio(0); } while (0)
; #define PG8_WAIT_V(n) asm volatile("s_waitcnt vmcnt(" #n ")" ::: "memory")
; #define PG8_WAIT_L(n) asm volatile("s_waitcnt lgkmcnt(" #n ")" ::: "memory")
; #define PG8_BAR __builtin_amdgcn_s_barrier()
; #define PG8_SCHED __builtin_amdgcn_sched_barrier(0)
; template <class Epi, class Ptrs>
; __device__ __forceinline__ void gemm_phase(LAS unsigned char* lds, const int K, const StaticOrder& S, const Ptrs& P, const Epi& E) {
;     ...
;             PG8_WAIT_V(6); PG8_BAR; PG8_MMA(1, 1, At, B1); PG8_BAR;
;             PG8_LDB(B0, 1, 0); PG8_SCHED; PG8_LDA(At, 1, 0); PG8_STAGE(PG8_SA(0, 1), a2 + hstep, voffA);
;             PG8_WAIT_L(8); PG8_BAR; PG8_WAIT_L(0); PG8_MMA(0, 0, At, B0); PG8_BAR; PG8_SCHED;
;             PG8_LDB(B1, 1, 1); PG8_STAGE(PG8_SB(1, 0), b3, voffB);
;             PG8_BAR; PG8_WAIT_L(0); PG8_MMA(0, 1, At, B1); PG8_BAR;
;             PG8_LDA(At, 1, 1); PG8_STAGE(PG8_SA(1, 0), a3, voffA);
	v_mfma_f32_16x16x32_bf16 v[52:55], v[200:203], v[168:171], v[52:55]
	v_mfma_f32_16x16x32_bf16 v[52:55], v[204:207], v[172:175], v[52:55]
	v_mfma_f32_16x16x32_bf16 v[48:51], v[214:217], v[172:175], v[48:51]
	v_mfma_f32_16x16x32_bf16 v[48:51], v[210:213], v[168:171], v[48:51]
	v_mfma_f32_16x16x32_bf16 v[32:35], v[210:213], v[176:179], v[32:35]
	v_mfma_f32_16x16x32_bf16 v[32:35], v[214:217], v[180:183], v[32:35]
	v_mfma_f32_16x16x32_bf16 v[36:39], v[204:207], v[180:183], v[36:39]
	v_mfma_f32_16x16x32_bf16 v[36:39], v[200:203], v[176:179], v[36:39]
	v_mfma_f32_16x16x32_bf16 v[20:23], v[200:203], v[184:187], v[20:23]
	v_mfma_f32_16x16x32_bf16 v[20:23], v[204:207], v[188:191], v[20:23]
	v_mfma_f32_16x16x32_bf16 v[16:19], v[214:217], v[188:191], v[16:19]
	v_mfma_f32_16x16x32_bf16 v[16:19], v[210:213], v[184:187], v[16:19]
	v_mfma_f32_16x16x32_bf16 v[0:3], v[210:213], v[192:195], v[0:3]
	v_mfma_f32_16x16x32_bf16 v[0:3], v[214:217], v[196:199], v[0:3]
	v_mfma_f32_16x16x32_bf16 v[4:7], v[204:207], v[196:199], v[4:7]
	v_mfma_f32_16x16x32_bf16 v[4:7], v[200:203], v[192:195], v[4:7]
	s_add_i32 s71, 0, 0x18000
	v_add_u32_e32 v164, s71, v147
	s_barrier
	ds_read_b128 v[152:155], v164
	ds_read_b128 v[156:159], v164 offset:1024
	ds_read_b128 v[160:163], v164 offset:2048
	ds_read_b128 v[164:167], v164 offset:3072
	s_add_u32 s44, s44, 0x40000
	s_addc_u32 s45, s45, 0
	s_mov_b32 m0, s57
	ds_read_b128 v[168:171], v150 offset:32768
	ds_read_b128 v[172:175], v150 offset:33792
	ds_read_b128 v[176:179], v150 offset:34816
	ds_read_b128 v[180:183], v150 offset:35840
	ds_read_b128 v[184:187], v150 offset:36864
	ds_read_b128 v[188:191], v150 offset:37888
	ds_read_b128 v[192:195], v150 offset:38912
	ds_read_b128 v[196:199], v150 offset:39936
	global_load_lds_dwordx4 v128, s[44:45]
	s_mov_b32 m0, s58
	s_nop 0
	global_load_lds_dwordx4 v132, s[44:45]
	s_waitcnt lgkmcnt(8)
	s_barrier
	s_waitcnt lgkmcnt(0)
	s_waitcnt lgkmcnt(0)
	v_mfma_f32_16x16x32_bf16 v[124:127], v[152:155], v[168:171], v[124:127]
	v_mfma_f32_16x16x32_bf16 v[124:127], v[156:159], v[172:175], v[124:127]
	v_mfma_f32_16x16x32_bf16 v[120:123], v[164:167], v[172:175], v[120:123]
	v_mfma_f32_16x16x32_bf16 v[120:123], v[160:163], v[168:171], v[120:123]
	v_mfma_f32_16x16x32_bf16 v[104:107], v[160:163], v[176:179], v[104:107]
	v_mfma_f32_16x16x32_bf16 v[104:107], v[164:167], v[180:183], v[104:107]
	v_mfma_f32_16x16x32_bf16 v[108:111], v[156:159], v[180:183], v[108:111]
	v_mfma_f32_16x16x32_bf16 v[108:111], v[152:155], v[176:179], v[108:111]
	v_mfma_f32_16x16x32_bf16 v[92:95], v[152:155], v[184:187], v[92:95]
	v_mfma_f32_16x16x32_bf16 v[92:95], v[156:159], v[188:191], v[92:95]
	v_mfma_f32_16x16x32_bf16 v[88:91], v[164:167], v[188:191], v[88:91]
	v_mfma_f32_16x16x32_bf16 v[88:91], v[160:163], v[184:187], v[88:91]
	v_mfma_f32_16x16x32_bf16 v[72:75], v[160:163], v[192:195], v[72:75]
	v_mfma_f32_16x16x32_bf16 v[72:75], v[164:167], v[196:199], v[72:75]
	v_mfma_f32_16x16x32_bf16 v[76:79], v[156:159], v[196:199], v[76:79]
	v_mfma_f32_16x16x32_bf16 v[76:79], v[152:155], v[192:195], v[76:79]
	s_barrier
	s_add_i32 s44, 0, 0x1c000
	s_add_i32 s45, s71, s51
	v_add_u32_e32 v209, s44, v147
	v_lshl_add_u64 v[144:145], v[144:145], 0, s[12:13]
	s_mov_b32 m0, s45
	ds_read_b128 v[200:203], v209
	ds_read_b128 v[204:207], v209 offset:1024
	ds_read_b128 v[210:213], v209 offset:2048
	ds_read_b128 v[214:217], v209 offset:3072
	global_load_lds_dwordx4 v[144:145], off
	v_lshl_add_u64 v[144:145], v[218:219], 0, s[12:13]
	s_add_i32 m0, s45, 0x2000
	s_nop 0
	global_load_lds_dwordx4 v[144:145], off
	s_barrier
	s_waitcnt lgkmcnt(0)
	s_waitcnt lgkmcnt(0)
	v_mfma_f32_16x16x32_bf16 v[116:119], v[200:203], v[168:171], v[116:119]
	v_mfma_f32_16x16x32_bf16 v[116:119], v[204:207], v[172:175], v[116:119]
	v_mfma_f32_16x16x32_bf16 v[112:115], v[214:217], v[172:175], v[112:115]
	v_mfma_f32_16x16x32_bf16 v[112:115], v[210:213], v[168:171], v[112:115]
	v_mfma_f32_16x16x32_bf16 v[96:99], v[210:213], v[176:179], v[96:99]
	v_mfma_f32_16x16x32_bf16 v[96:99], v[214:217], v[180:183], v[96:99]
	v_mfma_f32_16x16x32_bf16 v[100:103], v[204:207], v[180:183], v[100:103]
	v_mfma_f32_16x16x32_bf16 v[100:103], v[200:203], v[176:179], v[100:103]
	v_mfma_f32_16x16x32_bf16 v[84:87], v[200:203], v[184:187], v[84:87]
	v_mfma_f32_16x16x32_bf16 v[84:87], v[204:207], v[188:191], v[84:87]
	v_mfma_f32_16x16x32_bf16 v[80:83], v[214:217], v[188:191], v[80:83]
	v_mfma_f32_16x16x32_bf16 v[80:83], v[210:213], v[184:187], v[80:83]
	v_mfma_f32_16x16x32_bf16 v[64:67], v[210:213], v[192:195], v[64:67]
	v_mfma_f32_16x16x32_bf16 v[64:67], v[214:217], v[196:199], v[64:67]
	v_mfma_f32_16x16x32_bf16 v[68:71], v[204:207], v[196:199], v[68:71]
	v_mfma_f32_16x16x32_bf16 v[68:71], v[200:203], v[192:195], v[68:71]
	s_mov_b32 m0, s61
	v_lshl_add_u64 v[144:145], v[220:221], 0, s[12:13]
	s_barrier
	ds_read_b128 v[168:171], v150 offset:49152
	ds_read_b128 v[172:175], v150 offset:50176
	ds_read_b128 v[176:179], v150 offset:51200
	ds_read_b128 v[180:183], v150 offset:52224
	ds_read_b128 v[184:187], v150 offset:53248
	ds_read_b128 v[188:191], v150 offset:54272
	ds_read_b128 v[192:195], v150 offset:55296
	ds_read_b128 v[196:199], v150 offset:56320
	global_load_lds_dwordx4 v[144:145], off
	v_lshl_add_u64 v[144:145], v[222:223], 0, s[12:13]
	s_mov_b32 m0, s62
	s_nop 0
	global_load_lds_dwordx4 v[144:145], off
	s_barrier
; __device__ __forceinline__ unsigned cvt_pk_bf16(float lo, float hi) { unsigned r; asm volatile("v_cvt_pk_bf16_f32 %0, %1, %2" : "=v"(r) : "v"(lo), "v"(hi)); return r; }
; #define PG8_STAGE(bufoff, gbase, voff) do { _Pragma("unroll") for (int _i = 0; _i < 2; ++_i) \
;         __builtin_amdgcn_global_load_lds((const unsigned*)((const char*)(gbase) + (voff)[_i]), (LAS unsigned*)(lds + (bufoff) + ldsw + _i * 8192), 16, 0, 0); } while (0)
; #define PG8_MMA(ai, bj, At, Bt) do { __builtin_amdgcn_s_setprio(1); _Pragma("unroll") for (int m = 0; m < 4; ++m) _Pragma("unroll") for (int n = 0; n < 2; ++n) _Pragma("unroll") for (int k = 0; k < 2; ++k) \
;         acc[ai][bj][m][n] = __builtin_amdgcn_mfma_f32_16x16x32_bf16(Bt[n][k], At[m][k], acc[ai][bj][m][n], 0, 0, 0); __builtin_amdgcn_s_setprio(0); } while (0)
; #define PG8_WAIT_V(n) asm volatile("s_waitcnt vmcnt(" #n ")" ::: "memory")
; #define PG8_WAIT_L(n) asm volatile("s_waitcnt lgkmcnt(" #n ")" ::: "memory")
; #define PG8_BAR __builtin_amdgcn_s_barrier()
; #define PG8_SCHED __builtin_amdgcn_sched_barrier(0)
; template <class Epi, class Ptrs>
; __device__ __forceinline__ void gemm_phase(LAS unsigned char* lds, const int K, const StaticOrder& S, const Ptrs& P, const Epi& E) {
;     ...
;             PG8_BAR; PG8_WAIT_L(0); PG8_MMA(1, 0, At, B0); PG8_BAR; PG8_SCHED;
;             PG8_STAGE(PG8_SB(1, 1), b3 + hstep, voffB);
;             PG8_WAIT_V(6); PG8_BAR; PG8_MMA(1, 1, At, B1); PG8_BAR;
;     __device__ __forceinline__ void operator()(const f32x4 (&acc)[2][2][4][2], const Unit& u, int ui, int wr, int wc, int fr, int fq) const {
;         const int row0 = u.pm * 256 + wr * 64 + fr, col0 = u.pn * 256 + wc * 32 + 8 * fq;
; #pragma unroll
;         for (int ai = 0; ai < 2; ++ai)
; #pragma unroll
;             for (int m = 0; m < 4; ++m) { bf16_t* rowp = hid + (size_t)(row0 + ai * 128 + m * 16) * DFF + col0;
; #pragma unroll
;                 for (int bj = 0; bj < 2; ++bj) { f32x4 v0 = acc[ai][bj][m][0], v1 = acc[ai][bj][m][1];
; #pragma unroll
;                     for (int j = 0; j < 4; ++j) { const float a = fmaxf(v0[j], 0.f), b = fmaxf(v1[j], 0.f); v0[j] = a * a; v1[j] = b * b; }
;                     u32x4 w; w.x = cvt_pk_bf16(v0[0], v0[1]); w.y = cvt_pk_bf16(v0[2], v0[3]); w.z = cvt_pk_bf16(v1[0], v1[1]); w.w = cvt_pk_bf16(v1[2], v1[3]);
;                     *(u32x4*)(rowp + bj * 128) = w; } }
	s_waitcnt lgkmcnt(0)
	s_waitcnt lgkmcnt(0)
	v_mfma_f32_16x16x32_bf16 v[60:63], v[152:155], v[168:171], v[60:63]
	v_mfma_f32_16x16x32_bf16 v[60:63], v[156:159], v[172:175], v[60:63]
	v_mfma_f32_16x16x32_bf16 v[56:59], v[164:167], v[172:175], v[56:59]
	v_mfma_f32_16x16x32_bf16 v[56:59], v[160:163], v[168:171], v[56:59]
	v_mfma_f32_16x16x32_bf16 v[40:43], v[160:163], v[176:179], v[40:43]
	v_mfma_f32_16x16x32_bf16 v[40:43], v[164:167], v[180:183], v[40:43]
	v_mfma_f32_16x16x32_bf16 v[44:47], v[156:159], v[180:183], v[44:47]
	v_mfma_f32_16x16x32_bf16 v[44:47], v[152:155], v[176:179], v[44:47]
	v_mfma_f32_16x16x32_bf16 v[28:31], v[152:155], v[184:187], v[28:31]
	v_mfma_f32_16x16x32_bf16 v[28:31], v[156:159], v[188:191], v[28:31]
	v_mfma_f32_16x16x32_bf16 v[24:27], v[164:167], v[188:191], v[24:27]
	v_mfma_f32_16x16x32_bf16 v[24:27], v[160:163], v[184:187], v[24:27]
	v_mfma_f32_16x16x32_bf16 v[8:11], v[160:163], v[192:195], v[8:11]
	v_mfma_f32_16x16x32_bf16 v[8:11], v[164:167], v[196:199], v[8:11]
	v_mfma_f32_16x16x32_bf16 v[12:15], v[156:159], v[196:199], v[12:15]
	v_mfma_f32_16x16x32_bf16 v[12:15], v[152:155], v[192:195], v[12:15]
	s_barrier
	s_add_u32 s42, s42, 0x40080
	s_addc_u32 s43, s43, 0
	s_add_i32 s44, s44, s51
	s_mov_b32 m0, s44
	s_nop 0
	global_load_lds_dwordx4 v130, s[42:43]
	s_add_i32 m0, s44, 0x2000
	s_nop 0
	global_load_lds_dwordx4 v134, s[42:43]
	s_waitcnt vmcnt(6)
	s_barrier
	v_mfma_f32_16x16x32_bf16 v[52:55], v[200:203], v[168:171], v[52:55]
	v_mfma_f32_16x16x32_bf16 v[52:55], v[204:207], v[172:175], v[52:55]
	v_mfma_f32_16x16x32_bf16 v[48:51], v[214:217], v[172:175], v[48:51]
	v_mfma_f32_16x16x32_bf16 v[48:51], v[210:213], v[168:171], v[48:51]
	v_mfma_f32_16x16x32_bf16 v[32:35], v[210:213], v[176:179], v[32:35]
	v_mfma_f32_16x16x32_bf16 v[32:35], v[214:217], v[180:183], v[32:35]
	v_mfma_f32_16x16x32_bf16 v[36:39], v[204:207], v[180:183], v[36:39]
	v_mfma_f32_16x16x32_bf16 v[36:39], v[200:203], v[176:179], v[36:39]
	v_mfma_f32_16x16x32_bf16 v[20:23], v[200:203], v[184:187], v[20:23]
	v_mfma_f32_16x16x32_bf16 v[20:23], v[204:207], v[188:191], v[20:23]
	v_mfma_f32_16x16x32_bf16 v[16:19], v[214:217], v[188:191], v[16:19]
	v_mfma_f32_16x16x32_bf16 v[16:19], v[210:213], v[184:187], v[16:19]
	v_mfma_f32_16x16x32_bf16 v[0:3], v[210:213], v[192:195], v[0:3]
	v_mfma_f32_16x16x32_bf16 v[0:3], v[214:217], v[196:199], v[0:3]
	v_mfma_f32_16x16x32_bf16 v[4:7], v[204:207], v[196:199], v[4:7]
	v_mfma_f32_16x16x32_bf16 v[4:7], v[200:203], v[192:195], v[4:7]
	s_add_i32 s70, s70, 2
	s_add_u32 s40, s40, 0x100
	s_addc_u32 s41, s41, 0
	s_add_u32 s23, s23, 0x100
	s_addc_u32 s25, s25, 0
	s_cmp_gt_u32 s70, 13
	s_barrier
	s_cbranch_scc0 .LBB0_433
	s_nop 0
	s_nop 0
	s_nop 0
	s_nop 0
	s_nop 0
	s_nop 0
	s_nop 0
	s_nop 0
	s_nop 0
	s_nop 0
	s_nop 0
	s_nop 0
	s_nop 0
	s_nop 0
	s_nop 0
	s_nop 0
	s_nop 0
	s_nop 0
	s_nop 0
	s_nop 0
	s_nop 0
	s_nop 0
	s_nop 0
	s_nop 0
	s_nop 0
	s_nop 0
	s_nop 0
	s_nop 0
	s_nop 0
	s_nop 0
	s_nop 0
	s_nop 0
	v_lshl_add_u32 v152, s38, 8, v146
	v_max_f32_e32 v120, 0, v120
	v_ashrrev_i32_e32 v153, 31, v152
	v_max_f32_e32 v121, 0, v121
	v_max_f32_e32 v122, 0, v122
	v_lshl_or_b32 v144, s69, 8, v148
	v_lshlrev_b64 v[154:155], 13, v[152:153]
	v_mul_f32_e32 v153, v120, v120
	v_max_f32_e32 v120, 0, v125
	v_ashrrev_i32_e32 v145, 31, v144
	v_max_f32_e32 v124, 0, v124
	v_mul_f32_e32 v125, v121, v121
	v_max_f32_e32 v121, 0, v126
	v_mul_f32_e32 v126, v122, v122
	v_max_f32_e32 v122, 0, v127
	v_max_f32_e32 v123, 0, v123
	v_lshl_add_u64 v[154:155], s[10:11], 0, v[154:155]
	v_lshlrev_b64 v[156:157], 1, v[144:145]
	v_mul_f32_e32 v120, v120, v120
	v_max_f32_e32 v112, 0, v112
	v_lshl_add_u64 v[144:145], v[154:155], 0, v[156:157]
	v_mul_f32_e32 v124, v124, v124
	v_mul_f32_e32 v121, v121, v121
	v_mul_f32_e32 v122, v122, v122
	v_mul_f32_e32 v123, v123, v123
	v_cvt_pk_bf16_f32 v120, v124, v120
	v_max_f32_e32 v113, 0, v113
	v_max_f32_e32 v114, 0, v114
	v_cvt_pk_bf16_f32 v121, v121, v122
	v_cvt_pk_bf16_f32 v122, v153, v125
	v_cvt_pk_bf16_f32 v123, v126, v123
	global_store_dwordx4 v[144:145], v[120:123], off
	s_nop 1
	v_mul_f32_e32 v120, v112, v112
	v_max_f32_e32 v112, 0, v117
	v_max_f32_e32 v116, 0, v116
	v_mul_f32_e32 v117, v113, v113
	v_max_f32_e32 v113, 0, v118
	v_mul_f32_e32 v118, v114, v114
	v_max_f32_e32 v114, 0, v119
	v_max_f32_e32 v115, 0, v115
	v_mul_f32_e32 v112, v112, v112
	v_mul_f32_e32 v116, v116, v116
	v_mul_f32_e32 v113, v113, v113
	v_mul_f32_e32 v114, v114, v114
	v_mul_f32_e32 v115, v115, v115
	v_cvt_pk_bf16_f32 v112, v116, v112
	v_max_f32_e32 v104, 0, v104
	v_cvt_pk_bf16_f32 v113, v113, v114
	v_cvt_pk_bf16_f32 v114, v120, v117
	v_cvt_pk_bf16_f32 v115, v118, v115
	global_store_dwordx4 v[144:145], v[112:115], off offset:256
	s_nop 0
	v_max_f32_e32 v105, 0, v105
	v_or_b32_e32 v112, 16, v152
	v_max_f32_e32 v106, 0, v106
	v_ashrrev_i32_e32 v113, 31, v112
	v_mul_f32_e32 v114, v104, v104
	v_max_f32_e32 v104, 0, v109
	v_lshlrev_b64 v[112:113], 13, v[112:113]
	v_max_f32_e32 v108, 0, v108
	v_mul_f32_e32 v109, v105, v105
	v_max_f32_e32 v105, 0, v110
	v_mul_f32_e32 v110, v106, v106
	v_max_f32_e32 v106, 0, v111
	v_max_f32_e32 v107, 0, v107
	v_lshl_add_u64 v[112:113], s[10:11], 0, v[112:113]
	v_mul_f32_e32 v104, v104, v104
	v_max_f32_e32 v96, 0, v96
	v_lshl_add_u64 v[112:113], v[112:113], 0, v[156:157]
	v_mul_f32_e32 v108, v108, v108
	v_mul_f32_e32 v105, v105, v105
	v_mul_f32_e32 v106, v106, v106
	v_mul_f32_e32 v107, v107, v107
	v_cvt_pk_bf16_f32 v104, v108, v104
	v_max_f32_e32 v97, 0, v97
	v_max_f32_e32 v98, 0, v98
	v_cvt_pk_bf16_f32 v105, v105, v106
	v_cvt_pk_bf16_f32 v106, v114, v109
	v_cvt_pk_bf16_f32 v107, v110, v107
	global_store_dwordx4 v[112:113], v[104:107], off
; __device__ __forceinline__ unsigned cvt_pk_bf16(float lo, float hi) { unsigned r; asm volatile("v_cvt_pk_bf16_f32 %0, %1, %2" : "=v"(r) : "v"(lo), "v"(hi)); return r; }
;     __device__ __forceinline__ void operator()(const f32x4 (&acc)[2][2][4][2], const Unit& u, int ui, int wr, int wc, int fr, int fq) const {
;     ...
;             for (int m = 0; m < 4; ++m) { bf16_t* rowp = hid + (size_t)(row0 + ai * 128 + m * 16) * DFF + col0;
; #pragma unroll
;                 for (int bj = 0; bj < 2; ++bj) { f32x4 v0 = acc[ai][bj][m][0], v1 = acc[ai][bj][m][1];
; #pragma unroll
;                     for (int j = 0; j < 4; ++j) { const float a = fmaxf(v0[j], 0.f), b = fmaxf(v1[j], 0.f); v0[j] = a * a; v1[j] = b * b; }
;                     u32x4 w; w.x = cvt_pk_bf16(v0[0], v0[1]); w.y = cvt_pk_bf16(v0[2], v0[3]); w.z = cvt_pk_bf16(v1[0], v1[1]); w.w = cvt_pk_bf16(v1[2], v1[3]);
;                     *(u32x4*)(rowp + bj * 128) = w; } }
	s_nop 1
	v_mul_f32_e32 v104, v96, v96
	v_max_f32_e32 v96, 0, v101
	v_max_f32_e32 v100, 0, v100
	v_mul_f32_e32 v101, v97, v97
	v_max_f32_e32 v97, 0, v102
	v_mul_f32_e32 v102, v98, v98
	v_max_f32_e32 v98, 0, v103
	v_max_f32_e32 v99, 0, v99
	v_mul_f32_e32 v96, v96, v96
	v_mul_f32_e32 v100, v100, v100
	v_mul_f32_e32 v97, v97, v97
	v_mul_f32_e32 v98, v98, v98
	v_mul_f32_e32 v99, v99, v99
	v_cvt_pk_bf16_f32 v96, v100, v96
	v_max_f32_e32 v88, 0, v88
	v_cvt_pk_bf16_f32 v97, v97, v98
	v_cvt_pk_bf16_f32 v98, v104, v101
	v_cvt_pk_bf16_f32 v99, v102, v99
	global_store_dwordx4 v[112:113], v[96:99], off offset:256
	s_nop 0
	v_max_f32_e32 v89, 0, v89
	v_or_b32_e32 v96, 32, v152
	v_max_f32_e32 v90, 0, v90
	v_ashrrev_i32_e32 v97, 31, v96
	v_mul_f32_e32 v98, v88, v88
	v_max_f32_e32 v88, 0, v93
	v_lshlrev_b64 v[96:97], 13, v[96:97]
	v_max_f32_e32 v92, 0, v92
	v_mul_f32_e32 v93, v89, v89
	v_max_f32_e32 v89, 0, v94
	v_mul_f32_e32 v94, v90, v90
	v_max_f32_e32 v90, 0, v95
	v_max_f32_e32 v91, 0, v91
	v_lshl_add_u64 v[96:97], s[10:11], 0, v[96:97]
	v_mul_f32_e32 v88, v88, v88
	v_max_f32_e32 v80, 0, v80
	v_lshl_add_u64 v[96:97], v[96:97], 0, v[156:157]
	v_mul_f32_e32 v92, v92, v92
	v_mul_f32_e32 v89, v89, v89
	v_mul_f32_e32 v90, v90, v90
	v_mul_f32_e32 v91, v91, v91
	v_cvt_pk_bf16_f32 v88, v92, v88
	v_max_f32_e32 v81, 0, v81
	v_max_f32_e32 v82, 0, v82
	v_cvt_pk_bf16_f32 v89, v89, v90
	v_cvt_pk_bf16_f32 v90, v98, v93
	v_cvt_pk_bf16_f32 v91, v94, v91
	global_store_dwordx4 v[96:97], v[88:91], off
	s_nop 1
	v_mul_f32_e32 v88, v80, v80
	v_max_f32_e32 v80, 0, v85
	v_max_f32_e32 v84, 0, v84
	v_mul_f32_e32 v85, v81, v81
	v_max_f32_e32 v81, 0, v86
	v_mul_f32_e32 v86, v82, v82
	v_max_f32_e32 v82, 0, v87
	v_max_f32_e32 v83, 0, v83
	v_mul_f32_e32 v80, v80, v80
	v_mul_f32_e32 v84, v84, v84
	v_mul_f32_e32 v81, v81, v81
	v_mul_f32_e32 v82, v82, v82
	v_mul_f32_e32 v83, v83, v83
	v_cvt_pk_bf16_f32 v80, v84, v80
	v_max_f32_e32 v72, 0, v72
	v_cvt_pk_bf16_f32 v81, v81, v82
	v_cvt_pk_bf16_f32 v82, v88, v85
	v_cvt_pk_bf16_f32 v83, v86, v83
	global_store_dwordx4 v[96:97], v[80:83], off offset:256
	s_nop 0
	v_max_f32_e32 v73, 0, v73
	v_or_b32_e32 v80, 48, v152
	v_max_f32_e32 v74, 0, v74
	v_ashrrev_i32_e32 v81, 31, v80
	v_mul_f32_e32 v82, v72, v72
	v_max_f32_e32 v72, 0, v77
	v_lshlrev_b64 v[80:81], 13, v[80:81]
	v_max_f32_e32 v76, 0, v76
	v_mul_f32_e32 v77, v73, v73
	v_max_f32_e32 v73, 0, v78
	v_mul_f32_e32 v78, v74, v74
	v_max_f32_e32 v74, 0, v79
	v_max_f32_e32 v75, 0, v75
	v_lshl_add_u64 v[80:81], s[10:11], 0, v[80:81]
	v_mul_f32_e32 v72, v72, v72
	v_max_f32_e32 v64, 0, v64
	v_max_f32_e32 v65, 0, v65
	v_max_f32_e32 v66, 0, v66
	v_lshl_add_u64 v[80:81], v[80:81], 0, v[156:157]
	v_mul_f32_e32 v76, v76, v76
	v_mul_f32_e32 v73, v73, v73
	v_mul_f32_e32 v74, v74, v74
	v_mul_f32_e32 v75, v75, v75
	v_cvt_pk_bf16_f32 v72, v76, v72
	v_cvt_pk_bf16_f32 v73, v73, v74
	v_cvt_pk_bf16_f32 v74, v82, v77
	v_cvt_pk_bf16_f32 v75, v78, v75
	global_store_dwordx4 v[80:81], v[72:75], off
	v_max_f32_e32 v68, 0, v68
	v_max_f32_e32 v67, 0, v67
	v_mul_f32_e32 v72, v64, v64
	v_max_f32_e32 v64, 0, v69
	v_mul_f32_e32 v69, v65, v65
	v_max_f32_e32 v65, 0, v70
	v_mul_f32_e32 v70, v66, v66
	v_max_f32_e32 v66, 0, v71
	v_mul_f32_e32 v64, v64, v64
	v_mul_f32_e32 v65, v65, v65
	v_mul_f32_e32 v66, v66, v66
	v_max_f32_e32 v56, 0, v56
	v_mul_f32_e32 v68, v68, v68
	v_mul_f32_e32 v67, v67, v67
	v_cvt_pk_bf16_f32 v64, v68, v64
	v_cvt_pk_bf16_f32 v65, v65, v66
	v_cvt_pk_bf16_f32 v66, v72, v69
	v_max_f32_e32 v57, 0, v57
	v_max_f32_e32 v58, 0, v58
	v_cvt_pk_bf16_f32 v67, v70, v67
	global_store_dwordx4 v[80:81], v[64:67], off offset:256
	s_nop 0
	v_max_f32_e32 v60, 0, v60
	v_mul_f32_e32 v66, v56, v56
	v_max_f32_e32 v56, 0, v61
	v_mul_f32_e32 v61, v57, v57
	v_max_f32_e32 v57, 0, v62
	v_mul_f32_e32 v62, v58, v58
	v_max_f32_e32 v58, 0, v63
	v_mul_f32_e32 v60, v60, v60
	v_mul_f32_e32 v56, v56, v56
	v_max_f32_e32 v59, 0, v59
	v_mul_f32_e32 v57, v57, v57
	v_mul_f32_e32 v58, v58, v58
	v_cvt_pk_bf16_f32 v56, v60, v56
	v_add_co_u32_e32 v60, vcc, s65, v144
	v_max_f32_e32 v48, 0, v48
	v_max_f32_e32 v49, 0, v49
	v_max_f32_e32 v50, 0, v50
	v_mul_f32_e32 v59, v59, v59
	v_cvt_pk_bf16_f32 v57, v57, v58
	v_cvt_pk_bf16_f32 v58, v66, v61
	v_addc_co_u32_e32 v61, vcc, 0, v145, vcc
	v_cvt_pk_bf16_f32 v59, v62, v59
	global_store_dwordx4 v[60:61], v[56:59], off
	v_max_f32_e32 v52, 0, v52
	v_max_f32_e32 v51, 0, v51
	v_mul_f32_e32 v56, v48, v48
	v_max_f32_e32 v48, 0, v53
	v_mul_f32_e32 v53, v49, v49
	v_max_f32_e32 v49, 0, v54
	v_mul_f32_e32 v54, v50, v50
	v_max_f32_e32 v50, 0, v55
	v_mul_f32_e32 v48, v48, v48
	v_mul_f32_e32 v49, v49, v49
	v_mul_f32_e32 v50, v50, v50
	v_max_f32_e32 v40, 0, v40
; __device__ __forceinline__ unsigned cvt_pk_bf16(float lo, float hi) { unsigned r; asm volatile("v_cvt_pk_bf16_f32 %0, %1, %2" : "=v"(r) : "v"(lo), "v"(hi)); return r; }
; #define PG8_WAIT_V(n) asm volatile("s_waitcnt vmcnt(" #n ")" ::: "memory")
; #define PG8_BAR __builtin_amdgcn_s_barrier()
; template <class Epi, class Ptrs>
; __device__ __forceinline__ void gemm_phase(LAS unsigned char* lds, const int K, const StaticOrder& S, const Ptrs& P, const Epi& E) {
;     ...
;         if (!has_next) break;
; #pragma unroll
;         for (int a = 0; a < 2; ++a)
; #pragma unroll
;             for (int b = 0; b < 2; ++b)
; #pragma unroll
;                 for (int m = 0; m < 4; ++m)
; #pragma unroll
;                     for (int n = 0; n < 2; ++n) acc[a][b][m][n] = (f32x4){0.f, 0.f, 0.f, 0.f};
;         cur = nxt; cA = nA; cB = nB; ++ui;
;     }
;     PG8_WAIT_V(0);
;     if (wr == 0) PG8_BAR;
;     PG8_BAR;
;     __device__ __forceinline__ void operator()(const f32x4 (&acc)[2][2][4][2], const Unit& u, int ui, int wr, int wc, int fr, int fq) const {
;     ...
;             for (int m = 0; m < 4; ++m) { bf16_t* rowp = hid + (size_t)(row0 + ai * 128 + m * 16) * DFF + col0;
; #pragma unroll
;                 for (int bj = 0; bj < 2; ++bj) { f32x4 v0 = acc[ai][bj][m][0], v1 = acc[ai][bj][m][1];
; #pragma unroll
;                     for (int j = 0; j < 4; ++j) { const float a = fmaxf(v0[j], 0.f), b = fmaxf(v1[j], 0.f); v0[j] = a * a; v1[j] = b * b; }
;                     u32x4 w; w.x = cvt_pk_bf16(v0[0], v0[1]); w.y = cvt_pk_bf16(v0[2], v0[3]); w.z = cvt_pk_bf16(v1[0], v1[1]); w.w = cvt_pk_bf16(v1[2], v1[3]);
;                     *(u32x4*)(rowp + bj * 128) = w; } }
	v_lshl_add_u64 v[64:65], v[144:145], 0, s[14:15]
	v_mul_f32_e32 v52, v52, v52
	v_mul_f32_e32 v51, v51, v51
	v_cvt_pk_bf16_f32 v48, v52, v48
	v_cvt_pk_bf16_f32 v49, v49, v50
	v_cvt_pk_bf16_f32 v50, v56, v53
	v_max_f32_e32 v41, 0, v41
	v_max_f32_e32 v42, 0, v42
	v_cvt_pk_bf16_f32 v51, v54, v51
	global_store_dwordx4 v[64:65], v[48:51], off offset:256
	s_nop 0
	v_max_f32_e32 v44, 0, v44
	v_mul_f32_e32 v50, v40, v40
	v_max_f32_e32 v40, 0, v45
	v_mul_f32_e32 v45, v41, v41
	v_max_f32_e32 v41, 0, v46
	v_mul_f32_e32 v46, v42, v42
	v_max_f32_e32 v42, 0, v47
	v_mul_f32_e32 v44, v44, v44
	v_mul_f32_e32 v40, v40, v40
	v_max_f32_e32 v43, 0, v43
	v_mul_f32_e32 v41, v41, v41
	v_mul_f32_e32 v42, v42, v42
	v_cvt_pk_bf16_f32 v40, v44, v40
	v_add_co_u32_e32 v44, vcc, s66, v144
	v_max_f32_e32 v32, 0, v32
	v_max_f32_e32 v33, 0, v33
	v_max_f32_e32 v34, 0, v34
	v_mul_f32_e32 v43, v43, v43
	v_cvt_pk_bf16_f32 v41, v41, v42
	v_cvt_pk_bf16_f32 v42, v50, v45
	v_addc_co_u32_e32 v45, vcc, 0, v145, vcc
	v_cvt_pk_bf16_f32 v43, v46, v43
	global_store_dwordx4 v[44:45], v[40:43], off
	v_max_f32_e32 v36, 0, v36
	v_max_f32_e32 v35, 0, v35
	v_mul_f32_e32 v40, v32, v32
	v_max_f32_e32 v32, 0, v37
	v_mul_f32_e32 v37, v33, v33
	v_max_f32_e32 v33, 0, v38
	v_mul_f32_e32 v38, v34, v34
	v_max_f32_e32 v34, 0, v39
	v_mul_f32_e32 v32, v32, v32
	v_mul_f32_e32 v33, v33, v33
	v_mul_f32_e32 v34, v34, v34
	v_max_f32_e32 v24, 0, v24
	v_lshl_add_u64 v[48:49], v[144:145], 0, s[16:17]
	v_mul_f32_e32 v36, v36, v36
	v_mul_f32_e32 v35, v35, v35
	v_cvt_pk_bf16_f32 v32, v36, v32
	v_cvt_pk_bf16_f32 v33, v33, v34
	v_cvt_pk_bf16_f32 v34, v40, v37
	v_max_f32_e32 v25, 0, v25
	v_max_f32_e32 v26, 0, v26
	v_cvt_pk_bf16_f32 v35, v38, v35
	global_store_dwordx4 v[48:49], v[32:35], off offset:256
	s_nop 0
	v_max_f32_e32 v28, 0, v28
	v_mul_f32_e32 v34, v24, v24
	v_max_f32_e32 v24, 0, v29
	v_mul_f32_e32 v29, v25, v25
	v_max_f32_e32 v25, 0, v30
	v_mul_f32_e32 v30, v26, v26
	v_max_f32_e32 v26, 0, v31
	v_mul_f32_e32 v28, v28, v28
	v_mul_f32_e32 v24, v24, v24
	v_max_f32_e32 v27, 0, v27
	v_mul_f32_e32 v25, v25, v25
	v_mul_f32_e32 v26, v26, v26
	v_cvt_pk_bf16_f32 v24, v28, v24
	v_add_co_u32_e32 v28, vcc, s67, v144
	v_max_f32_e32 v16, 0, v16
	v_max_f32_e32 v17, 0, v17
	v_max_f32_e32 v18, 0, v18
	v_mul_f32_e32 v27, v27, v27
	v_cvt_pk_bf16_f32 v25, v25, v26
	v_cvt_pk_bf16_f32 v26, v34, v29
	v_addc_co_u32_e32 v29, vcc, 0, v145, vcc
	v_cvt_pk_bf16_f32 v27, v30, v27
	global_store_dwordx4 v[28:29], v[24:27], off
	v_max_f32_e32 v20, 0, v20
	v_max_f32_e32 v19, 0, v19
	v_mul_f32_e32 v24, v16, v16
	v_max_f32_e32 v16, 0, v21
	v_mul_f32_e32 v21, v17, v17
	v_max_f32_e32 v17, 0, v22
	v_mul_f32_e32 v22, v18, v18
	v_max_f32_e32 v18, 0, v23
	v_mul_f32_e32 v16, v16, v16
	v_mul_f32_e32 v17, v17, v17
	v_mul_f32_e32 v18, v18, v18
	v_max_f32_e32 v8, 0, v8
	v_lshl_add_u64 v[32:33], v[144:145], 0, s[18:19]
	v_mul_f32_e32 v20, v20, v20
	v_mul_f32_e32 v19, v19, v19
	v_cvt_pk_bf16_f32 v16, v20, v16
	v_cvt_pk_bf16_f32 v17, v17, v18
	v_cvt_pk_bf16_f32 v18, v24, v21
	v_max_f32_e32 v9, 0, v9
	v_max_f32_e32 v10, 0, v10
	v_cvt_pk_bf16_f32 v19, v22, v19
	global_store_dwordx4 v[32:33], v[16:19], off offset:256
	s_nop 0
	v_max_f32_e32 v12, 0, v12
	v_mul_f32_e32 v18, v8, v8
	v_max_f32_e32 v8, 0, v13
	v_mul_f32_e32 v13, v9, v9
	v_max_f32_e32 v9, 0, v14
	v_mul_f32_e32 v14, v10, v10
	v_max_f32_e32 v10, 0, v15
	v_mul_f32_e32 v12, v12, v12
	v_mul_f32_e32 v8, v8, v8
	v_max_f32_e32 v11, 0, v11
	v_mul_f32_e32 v9, v9, v9
	v_mul_f32_e32 v10, v10, v10
	v_cvt_pk_bf16_f32 v8, v12, v8
	v_add_co_u32_e32 v12, vcc, s68, v144
	v_max_f32_e32 v0, 0, v0
	v_max_f32_e32 v1, 0, v1
	v_max_f32_e32 v2, 0, v2
	v_mul_f32_e32 v11, v11, v11
	v_cvt_pk_bf16_f32 v9, v9, v10
	v_cvt_pk_bf16_f32 v10, v18, v13
	v_addc_co_u32_e32 v13, vcc, 0, v145, vcc
	v_cvt_pk_bf16_f32 v11, v14, v11
	global_store_dwordx4 v[12:13], v[8:11], off
	v_max_f32_e32 v3, 0, v3
	v_max_f32_e32 v4, 0, v4
	v_mul_f32_e32 v8, v0, v0
	v_max_f32_e32 v0, 0, v5
	v_mul_f32_e32 v5, v1, v1
	v_max_f32_e32 v1, 0, v6
	v_mul_f32_e32 v6, v2, v2
	v_max_f32_e32 v2, 0, v7
	v_lshl_add_u64 v[16:17], v[144:145], 0, s[20:21]
	v_mul_f32_e32 v0, v0, v0
	v_mul_f32_e32 v1, v1, v1
	v_mul_f32_e32 v2, v2, v2
	v_mul_f32_e32 v3, v3, v3
	s_and_b64 vcc, exec, s[4:5]
	s_mov_b32 s69, s22
	s_mov_b32 s38, s24
	s_mov_b64 s[40:41], s[0:1]
	s_mov_b64 s[42:43], s[36:37]
	v_mul_f32_e32 v4, v4, v4
	v_cvt_pk_bf16_f32 v0, v4, v0
	v_cvt_pk_bf16_f32 v1, v1, v2
	v_cvt_pk_bf16_f32 v2, v8, v5
	v_cvt_pk_bf16_f32 v3, v6, v3
	global_store_dwordx4 v[16:17], v[0:3], off offset:256
	s_cbranch_vccz .LBB0_428
	s_waitcnt vmcnt(0)
	s_setprio 0
	s_cmpk_gt_u32 s46, 0xff
	s_cbranch_scc1 .LBB0_437
	s_barrier

; __device__ __forceinline__ unsigned xb_ld(unsigned* p)              { return __hip_atomic_load(p, __ATOMIC_RELAXED, __HIP_MEMORY_SCOPE_AGENT); }
; __device__ __forceinline__ void xcd_barrier_complete(unsigned* bar, unsigned x, unsigned& nloc, unsigned& nx) {
;     const unsigned G = gridDim.x * gridDim.y * gridDim.z;
;     unsigned sum, cnt, mine, sp = 0u;
;     for (;;) {
;         sum = 0u; cnt = 0u; mine = 0u;
; #pragma unroll
;         for (unsigned j = 0; j < 16; ++j) { const unsigned c = xb_ld(&bar[XB_XCNT(j)]); sum += c; cnt += (c > 0u) ? 1u : 0u; mine = (j == x) ? c : mine; }
; __device__ __forceinline__ void xcd_barrier(const XcdBarrier& b) {
;     asm volatile("s_waitcnt vmcnt(0)" ::: "memory");
;     __syncthreads();
;     if (threadIdx.x == 0) {
;         unsigned* bar = b.bar;
;         __builtin_amdgcn_s_waitcnt(0);
;         unsigned nloc = b.st[0], nx = b.st[1];
;         if (nloc == 0u) { xcd_barrier_complete(bar, b.x, nloc, nx); b.st[0] = nloc; b.st[1] = nx; }
.LBB0_438:
	s_nop 0
	s_nop 0
	s_nop 0
	s_nop 0
	s_nop 0
	s_nop 0
	s_nop 0
	s_nop 0
	s_nop 0
	s_nop 0
	s_nop 0
	s_nop 0
	s_nop 0
	s_nop 0
	s_nop 0
	s_nop 0
	s_nop 0
	s_nop 0
	s_nop 0
	s_nop 0
	s_nop 0
	s_nop 0
	s_nop 0
	s_nop 0
	s_nop 0
	s_nop 0
	s_nop 0
	s_nop 0
	s_nop 0
	s_nop 0
	s_nop 0
	s_nop 0
	s_nop 0
	s_nop 0
	s_nop 0
	s_nop 0
	s_nop 0
	s_nop 0
	s_nop 0
	s_nop 0
	s_nop 0
	s_nop 0
	s_nop 0
	s_nop 0
	s_nop 0
	s_nop 0
	s_nop 0
	s_nop 0
	s_nop 0
	s_nop 0
	s_nop 0
	s_nop 0
	s_nop 0
	s_cmp_gt_i32 s31, 5
	s_cselect_b64 s[0:1], -1, 0
	s_and_b64 s[4:5], s[6:7], s[0:1]
	s_andn2_b64 vcc, exec, s[4:5]
	s_cbranch_vccnz .LBB0_488
	s_waitcnt vmcnt(0)
	s_waitcnt vmcnt(0) lgkmcnt(0)
	s_barrier
	s_and_saveexec_b64 s[4:5], s[8:9]
	s_cbranch_execz .LBB0_487
	s_add_i32 s6, 0, 0x25ff0
	v_mov_b32_e32 v0, s6
	s_waitcnt vmcnt(0) expcnt(0) lgkmcnt(0)
	ds_read_b32 v2, v0
	s_add_i32 s6, 0, 0x25ff4
	v_mov_b32_e32 v0, s6
	ds_read_b32 v0, v0
	s_waitcnt lgkmcnt(1)
	v_cmp_ne_u32_e32 vcc, 0, v2
	s_cbranch_vccnz .LBB0_455
	s_load_dwordx2 s[10:11], s[52:53], 0x4
	s_add_u32 s6, s28, 0x3e800200
	s_addc_u32 s7, s29, 0
	s_add_u32 s8, s28, 0x3e800400
	s_addc_u32 s9, s29, 0
	s_waitcnt lgkmcnt(0)
	s_mul_i32 s31, s10, s3
	s_add_u32 s10, s28, 0x3e800500
	s_mul_i32 s31, s31, s11
	s_addc_u32 s11, s29, 0
	s_add_u32 s12, s28, 0x3e800600
	s_addc_u32 s13, s29, 0
	s_add_u32 s14, s28, 0x3e800700
	s_addc_u32 s15, s29, 0
	s_add_u32 s16, s28, 0x3e800800
	s_addc_u32 s17, s29, 0
	s_add_u32 s18, s28, 0x3e800900
	s_addc_u32 s19, s29, 0
	s_add_u32 s20, s28, 0x3e800a00
	s_addc_u32 s21, s29, 0
	s_add_u32 s22, s28, 0x3e800b00
	s_addc_u32 s23, s29, 0
	s_add_u32 s24, s28, 0x3e800c00
	s_addc_u32 s25, s29, 0
	s_add_u32 s36, s28, 0x3e800d00
	s_addc_u32 s37, s29, 0
	s_add_u32 s38, s28, 0x3e800e00
	s_addc_u32 s39, s29, 0
	s_add_u32 s40, s28, 0x3e800f00
	s_addc_u32 s41, s29, 0
	s_add_u32 s42, s28, 0x3e801000
	s_addc_u32 s43, s29, 0
	s_add_u32 s44, s28, 0x3e801100
	s_addc_u32 s45, s29, 0
	s_add_u32 s46, s28, 0x3e801200
	s_addc_u32 s47, s29, 0
	s_add_u32 s48, s28, 0x3e801300
	s_addc_u32 s49, s29, 0
	s_mov_b32 s56, 1
	v_mov_b32_e32 v16, 0
	s_branch .LBB0_443

; #define PG8_STAGE(bufoff, gbase, voff) do { _Pragma("unroll") for (int _i = 0; _i < 2; ++_i) \
;         __builtin_amdgcn_global_load_lds((const unsigned*)((const char*)(gbase) + (voff)[_i]), (LAS unsigned*)(lds + (bufoff) + ldsw + _i * 8192), 16, 0, 0); } while (0)
; #define PG8_WAIT_V(n) asm volatile("s_waitcnt vmcnt(" #n ")" ::: "memory")
; #define PG8_BAR __builtin_amdgcn_s_barrier()
;     __device__ bool next(int i, Unit& u) const {
;         if (rev && i >= rev) return false;
;         const long L = (long)(rev ? rev - 1 - i : i) * G + c; if (L >= nwg) return false;
;         int wgid = (int)L; { const int q = nwg / NXCD, r = nwg % NXCD, xcd = wgid % NXCD, off = wgid / NXCD; wgid = (xcd < r ? xcd * (q + 1) : r * (q + 1) + (xcd - r) * q) + off; }
;         const int nig = WGM * nN, gid = wgid / nig, fm = gid * WGM, gsz = (nM - fm) < WGM ? (nM - fm) : WGM;
;         u.pm = fm + ((wgid % nig) % gsz); u.pn = (wgid % nig) / gsz; return true;
; template <class Epi, class Ptrs>
; __device__ __forceinline__ void gemm_phase(LAS unsigned char* lds, const int K, const StaticOrder& S, const Ptrs& P, const Epi& E) {
;     ...
;     PG8_STAGE(PG8_SB(0, 0), cB, voffB); PG8_STAGE(PG8_SA(0, 0), cA, voffA); PG8_STAGE(PG8_SB(0, 1), cB + hstep, voffB); PG8_STAGE(PG8_SA(0, 1), cA + hstep, voffA);
;     if (wr == 1) PG8_BAR;
;     PG8_WAIT_V(4); PG8_BAR;
;     PG8_STAGE(PG8_SB(1, 0), cB + kstep, voffB); PG8_STAGE(PG8_SA(1, 0), cA + kstep, voffA); PG8_STAGE(PG8_SB(1, 1), cB + hstep + kstep, voffB);
;     PG8_WAIT_V(6); PG8_BAR;
.LBB0_516:
	s_lshl_b32 s1, s1, 5
	s_and_b32 s1, s1, 0x60
	s_lshl_b32 s10, s0, 13
	s_lshl_b32 s11, s1, 7
	s_add_u32 s6, s28, 0x2000000
	s_mov_b64 s[8:9], 0x80
	s_addc_u32 s7, s29, 0
	s_add_i32 m0, s17, 0x18000
	v_lshl_add_u64 v[6:7], v[6:7], 0, s[8:9]
	s_waitcnt vmcnt(4)
	s_barrier
	global_load_lds_dwordx4 v[6:7], off
	v_lshl_add_u64 v[4:5], v[4:5], 0, s[8:9]
	s_add_i32 m0, s17, 0x1a000
	s_add_i32 s28, s17, 0x8000
	s_add_i32 s29, s17, 0xa000
	global_load_lds_dwordx4 v[4:5], off
	v_lshl_add_u64 v[2:3], v[2:3], 0, s[8:9]
	s_mov_b32 m0, s28
	s_add_u32 s4, s22, 0x100080
	global_load_lds_dwordx4 v[2:3], off
	v_lshl_add_u64 v[0:1], v[0:1], 0, s[8:9]
	s_mov_b32 m0, s29
	s_addc_u32 s5, s23, 0
	global_load_lds_dwordx4 v[0:1], off
	s_add_i32 m0, s17, 0x1c000
	v_lshl_add_u64 v[0:1], s[4:5], 0, v[162:163]
	global_load_lds_dwordx4 v[0:1], off
	v_lshl_add_u64 v[0:1], s[4:5], 0, v[166:167]
	s_add_i32 m0, s17, 0x1e000
	v_lshlrev_b32_e32 v2, 6, v208
	global_load_lds_dwordx4 v[0:1], off
	v_and_b32_e32 v0, 15, v208
	v_lshlrev_b32_e32 v1, 1, v11
	s_movk_i32 s4, 0x3c0
	v_lshl_or_b32 v186, s0, 6, v0
	v_and_or_b32 v2, v2, s4, v1
	v_lshlrev_b32_e32 v3, 2, v208
	v_lshl_or_b32 v0, v0, 6, v1
	v_lshlrev_b32_e32 v1, 2, v186
	s_add_i32 s0, 0, 0x20000
	v_and_b32_e32 v3, 32, v3
	v_and_b32_e32 v4, 32, v1
	v_add_u32_e32 v192, s0, v1
	v_lshlrev_b32_e32 v1, 10, v208
	v_bitop3_b32 v187, s11, v2, v3 bitop3:0xf6
	v_and_b32_e32 v1, 0xe0000, v1
	v_lshlrev_b32_e32 v2, 13, v10
	v_or3_b32 v1, v8, v1, v2
	v_add_u32_e32 v168, v1, v9
	v_lshlrev_b32_e32 v1, 6, v12
	s_waitcnt vmcnt(6)
	v_and_b32_e32 v1, 0x1e0000, v1
	v_bitop3_b32 v0, v0, s10, v4 bitop3:0xde
	v_or3_b32 v1, v8, v1, v2
	s_add_i32 s42, 0, 0x10000
	s_add_i32 s43, 0, 0x14000
	v_or_b32_e32 v188, 16, v186
	v_or_b32_e32 v189, 32, v186
	v_or_b32_e32 v190, 48, v186
	v_or_b32_e32 v191, s1, v11
	v_mov_b32_e32 v169, v163
	v_add_u32_e32 v170, v1, v9
	v_mov_b32_e32 v171, v163
	v_mov_b64_e32 v[172:173], 0x600
	v_mov_b64_e32 v[174:175], 0x5ff
	v_add_u32_e32 v193, s42, v187
	v_add_u32_e32 v194, 0, v0
	v_add_u32_e32 v195, s43, v187
	s_cmpk_lt_u32 s33, 0x100
	s_cbranch_scc1 .Lsprio_3
	s_setprio 1
.Lsprio_3:
	s_barrier
.LBB0_517:
	s_add_i32 s44, s45, 1
	s_mul_i32 s0, s44, s30
	s_mul_hi_u32 s1, s44, s3
	s_add_i32 s1, s1, s0
	s_mul_i32 s0, s44, s3
	s_add_u32 s14, s0, s2
	s_addc_u32 s15, s1, s31
	v_cmp_gt_i64_e64 s[0:1], s[14:15], v[174:175]
	v_cmp_lt_i64_e64 s[4:5], s[14:15], v[172:173]
	s_and_b64 vcc, exec, s[0:1]
	s_cbranch_vccnz .LBB0_519
	s_ashr_i32 s10, s14, 31
	s_lshr_b32 s10, s10, 29
	s_add_i32 s10, s14, s10
	s_ashr_i32 s11, s10, 3
	s_and_b32 s10, s10, -8
	s_sub_i32 s10, s14, s10
	s_cmp_lt_i32 s10, 0
	s_cselect_b32 s12, s39, 0xc0
	s_mul_i32 s10, s10, s12
	s_add_i32 s10, s10, s11
	s_ashr_i32 s11, s10, 31
	s_lshr_b32 s11, s11, 27
	s_add_i32 s11, s10, s11
	s_ashr_i32 s12, s11, 5
	s_lshl_b32 s12, s12, 3
	s_sub_i32 s13, 0x180, s12
	s_min_i32 s13, s13, 8
	s_abs_i32 s14, s13
	v_cvt_f32_u32_e32 v0, s14
	s_sub_i32 s24, 0, s14
	s_andn2_b32 s11, s11, 31
	s_sub_i32 s11, s10, s11
	v_rcp_iflag_f32_e32 v0, v0
	s_abs_i32 s10, s11
	s_xor_b32 s15, s11, s13
	s_ashr_i32 s15, s15, 31
	v_mul_f32_e32 v0, 0x4f7ffffe, v0
	v_cvt_u32_f32_e32 v0, v0
	s_nop 0
	v_readfirstlane_b32 s25, v0
	s_mul_i32 s24, s24, s25
	s_mul_hi_u32 s24, s25, s24
	s_add_i32 s25, s25, s24
	s_mul_hi_u32 s24, s10, s25
	s_mul_i32 s25, s24, s14
	s_sub_i32 s10, s10, s25
	s_add_i32 s46, s24, 1
	s_sub_i32 s25, s10, s14
	s_cmp_ge_u32 s10, s14
	s_cselect_b32 s24, s46, s24
	s_cselect_b32 s10, s25, s10
	s_add_i32 s25, s24, 1
	s_cmp_ge_u32 s10, s14
	s_cselect_b32 s10, s25, s24
	s_xor_b32 s10, s10, s15
	s_sub_i32 s10, s10, s15
	s_mul_i32 s13, s10, s13
	s_sub_i32 s11, s11, s13
	s_add_i32 s12, s12, s11

; #define PG8_STAGE(bufoff, gbase, voff) do { _Pragma("unroll") for (int _i = 0; _i < 2; ++_i) \
;         __builtin_amdgcn_global_load_lds((const unsigned*)((const char*)(gbase) + (voff)[_i]), (LAS unsigned*)(lds + (bufoff) + ldsw + _i * 8192), 16, 0, 0); } while (0)
; #define PG8_LDA(dst, b, h) do { _Pragma("unroll") for (int m = 0; m < 4; ++m) _Pragma("unroll") for (int k = 0; k < 2; ++k) dst[m][k] = *(const LAS bf16x8*)(lds + PG8_SA(b, h) + aoff + m * 2048 + k * 1024); } while (0)
; #define PG8_LDB(dst, b, h) do { _Pragma("unroll") for (int n = 0; n < 2; ++n) _Pragma("unroll") for (int k = 0; k < 2; ++k) dst[n][k] = *(const LAS bf16x8*)(lds + PG8_SB(b, h) + boff + n * 2048 + k * 1024); } while (0)
; #define PG8_MMA(ai, bj, At, Bt) do { __builtin_amdgcn_s_setprio(1); _Pragma("unroll") for (int m = 0; m < 4; ++m) _Pragma("unroll") for (int n = 0; n < 2; ++n) _Pragma("unroll") for (int k = 0; k < 2; ++k) \
;         acc[ai][bj][m][n] = __builtin_amdgcn_mfma_f32_16x16x32_bf16(Bt[n][k], At[m][k], acc[ai][bj][m][n], 0, 0, 0); __builtin_amdgcn_s_setprio(0); } while (0)
; #define PG8_WAIT_V(n) asm volatile("s_waitcnt vmcnt(" #n ")" ::: "memory")
; #define PG8_WAIT_L(n) asm volatile("s_waitcnt lgkmcnt(" #n ")" ::: "memory")
; template <class Epi, class Ptrs>
; __device__ __forceinline__ void gemm_phase(LAS unsigned char* lds, const int K, const StaticOrder& S, const Ptrs& P, const Epi& E) {
;     ...
;         for (int t = 0; t < nt; t += 2) {
;             const bool last = (t == nt - 2);
;             const char* a1 = cA + (size_t)(t + 1) * kstep;
;             const char* a2 = last ? nA : cA + (size_t)(t + 2) * kstep; const char* b2 = last ? nB : cB + (size_t)(t + 2) * kstep;
;             const char* a3 = a2 + kstep; const char* b3 = b2 + kstep;
;             PG8_LDB(B0, 0, 0); PG8_SCHED; PG8_LDA(At, 0, 0); PG8_STAGE(PG8_SA(1, 1), a1 + hstep, voffA);
;             PG8_WAIT_L(8); PG8_BAR; PG8_WAIT_L(0); PG8_MMA(0, 0, At, B0); PG8_BAR; PG8_SCHED;
;             PG8_LDB(B1, 0, 1); PG8_STAGE(PG8_SB(0, 0), b2, voffB);
;             PG8_BAR; PG8_WAIT_L(0); PG8_MMA(0, 1, At, B1); PG8_BAR;
;             PG8_LDA(At, 0, 1); PG8_STAGE(PG8_SA(0, 0), a2, voffA);
;             PG8_BAR; PG8_WAIT_L(0); PG8_MMA(1, 0, At, B0); PG8_BAR; PG8_SCHED;
;             PG8_STAGE(PG8_SB(0, 1), b2 + hstep, voffB);
;             PG8_WAIT_V(6); PG8_BAR; PG8_MMA(1, 1, At, B1); PG8_BAR;
.LBB0_522:
	ds_read_b128 v[128:131], v193
	ds_read_b128 v[132:135], v193 offset:1024
	ds_read_b128 v[136:139], v193 offset:2048
	ds_read_b128 v[140:143], v193 offset:3072
	s_add_u32 s22, s20, 0xfff00080
	s_addc_u32 s23, s21, -1
	s_cmp_eq_u32 s46, 60
	s_cselect_b32 s25, s5, s23
	s_cselect_b32 s24, s4, s22
	s_cselect_b32 s23, s15, s13
	s_cselect_b32 s22, s14, s11
	s_add_i32 m0, s17, 0xc000
	ds_read_b128 v[144:147], v194
	ds_read_b128 v[148:151], v194 offset:1024
	ds_read_b128 v[152:155], v194 offset:2048
	ds_read_b128 v[156:159], v194 offset:3072
	ds_read_b128 v[176:179], v194 offset:4096
	ds_read_b128 v[180:183], v194 offset:5120
	ds_read_b128 v[196:199], v194 offset:6144
	ds_read_b128 v[200:203], v194 offset:7168
	global_load_lds_dwordx4 v168, s[20:21]
	s_add_i32 m0, s17, 0xe000
	s_nop 0
	global_load_lds_dwordx4 v170, s[20:21]
	s_waitcnt lgkmcnt(8)
	s_barrier
	s_waitcnt lgkmcnt(0)
	s_waitcnt lgkmcnt(0)
	v_mfma_f32_16x16x32_bf16 v[124:127], v[128:131], v[144:147], v[124:127]
	v_mfma_f32_16x16x32_bf16 v[124:127], v[132:135], v[148:151], v[124:127]
	v_mfma_f32_16x16x32_bf16 v[120:123], v[140:143], v[148:151], v[120:123]
	v_mfma_f32_16x16x32_bf16 v[120:123], v[136:139], v[144:147], v[120:123]
	v_mfma_f32_16x16x32_bf16 v[104:107], v[136:139], v[152:155], v[104:107]
	v_mfma_f32_16x16x32_bf16 v[104:107], v[140:143], v[156:159], v[104:107]
	v_mfma_f32_16x16x32_bf16 v[112:115], v[132:135], v[156:159], v[112:115]
	v_mfma_f32_16x16x32_bf16 v[112:115], v[128:131], v[152:155], v[112:115]
	v_mfma_f32_16x16x32_bf16 v[92:95], v[128:131], v[176:179], v[92:95]
	v_mfma_f32_16x16x32_bf16 v[92:95], v[132:135], v[180:183], v[92:95]
	v_mfma_f32_16x16x32_bf16 v[88:91], v[140:143], v[180:183], v[88:91]
	v_mfma_f32_16x16x32_bf16 v[88:91], v[136:139], v[176:179], v[88:91]
	v_mfma_f32_16x16x32_bf16 v[72:75], v[136:139], v[196:199], v[72:75]
	v_mfma_f32_16x16x32_bf16 v[72:75], v[140:143], v[200:203], v[72:75]
	v_mfma_f32_16x16x32_bf16 v[76:79], v[132:135], v[200:203], v[76:79]
	v_mfma_f32_16x16x32_bf16 v[76:79], v[128:131], v[196:199], v[76:79]
	s_barrier
	s_add_i32 s47, s42, s34
	v_lshl_add_u64 v[184:185], s[22:23], 0, v[162:163]
	s_mov_b32 m0, s47
	ds_read_b128 v[204:207], v195
	ds_read_b128 v[208:211], v195 offset:1024
	ds_read_b128 v[212:215], v195 offset:2048
	ds_read_b128 v[216:219], v195 offset:3072
	global_load_lds_dwordx4 v[184:185], off
	v_lshl_add_u64 v[220:221], s[22:23], 0, v[166:167]
	s_add_i32 m0, s47, 0x2000
	s_nop 0
	global_load_lds_dwordx4 v[220:221], off
	s_barrier
	s_waitcnt lgkmcnt(0)
	s_waitcnt lgkmcnt(0)
	v_mfma_f32_16x16x32_bf16 v[116:119], v[204:207], v[144:147], v[116:119]
	v_mfma_f32_16x16x32_bf16 v[116:119], v[208:211], v[148:151], v[116:119]
	v_mfma_f32_16x16x32_bf16 v[108:111], v[216:219], v[148:151], v[108:111]
	v_mfma_f32_16x16x32_bf16 v[108:111], v[212:215], v[144:147], v[108:111]
	v_mfma_f32_16x16x32_bf16 v[96:99], v[212:215], v[152:155], v[96:99]
	v_mfma_f32_16x16x32_bf16 v[96:99], v[216:219], v[156:159], v[96:99]
	v_mfma_f32_16x16x32_bf16 v[100:103], v[208:211], v[156:159], v[100:103]
	v_mfma_f32_16x16x32_bf16 v[100:103], v[204:207], v[152:155], v[100:103]
	v_mfma_f32_16x16x32_bf16 v[84:87], v[204:207], v[176:179], v[84:87]
	v_mfma_f32_16x16x32_bf16 v[84:87], v[208:211], v[180:183], v[84:87]
	v_mfma_f32_16x16x32_bf16 v[80:83], v[216:219], v[180:183], v[80:83]
	v_mfma_f32_16x16x32_bf16 v[80:83], v[212:215], v[176:179], v[80:83]
	v_mfma_f32_16x16x32_bf16 v[64:67], v[212:215], v[196:199], v[64:67]
	v_mfma_f32_16x16x32_bf16 v[64:67], v[216:219], v[200:203], v[64:67]
	v_mfma_f32_16x16x32_bf16 v[68:71], v[208:211], v[200:203], v[68:71]
	v_mfma_f32_16x16x32_bf16 v[68:71], v[204:207], v[196:199], v[68:71]
	s_mov_b32 m0, s17
	v_lshl_add_u64 v[222:223], s[24:25], 0, v[160:161]
	s_barrier
	ds_read_b128 v[144:147], v194 offset:16384
	ds_read_b128 v[148:151], v194 offset:17408
	ds_read_b128 v[152:155], v194 offset:18432
	ds_read_b128 v[156:159], v194 offset:19456
	ds_read_b128 v[176:179], v194 offset:20480
	ds_read_b128 v[180:183], v194 offset:21504
	ds_read_b128 v[196:199], v194 offset:22528
	ds_read_b128 v[200:203], v194 offset:23552
	global_load_lds_dwordx4 v[222:223], off
	v_lshl_add_u64 v[224:225], s[24:25], 0, v[164:165]
	s_mov_b32 m0, s19
	s_nop 0
	global_load_lds_dwordx4 v[224:225], off
	s_barrier
	s_waitcnt lgkmcnt(0)
	s_waitcnt lgkmcnt(0)
	v_mfma_f32_16x16x32_bf16 v[60:63], v[128:131], v[144:147], v[60:63]
	v_mfma_f32_16x16x32_bf16 v[60:63], v[132:135], v[148:151], v[60:63]
	v_mfma_f32_16x16x32_bf16 v[56:59], v[140:143], v[148:151], v[56:59]
	v_mfma_f32_16x16x32_bf16 v[56:59], v[136:139], v[144:147], v[56:59]
	v_mfma_f32_16x16x32_bf16 v[40:43], v[136:139], v[152:155], v[40:43]
	v_mfma_f32_16x16x32_bf16 v[40:43], v[140:143], v[156:159], v[40:43]
	v_mfma_f32_16x16x32_bf16 v[48:51], v[132:135], v[156:159], v[48:51]
	v_mfma_f32_16x16x32_bf16 v[48:51], v[128:131], v[152:155], v[48:51]
	v_mfma_f32_16x16x32_bf16 v[32:35], v[128:131], v[176:179], v[32:35]
	v_mfma_f32_16x16x32_bf16 v[32:35], v[132:135], v[180:183], v[32:35]
	v_mfma_f32_16x16x32_bf16 v[24:27], v[140:143], v[180:183], v[24:27]
	v_mfma_f32_16x16x32_bf16 v[24:27], v[136:139], v[176:179], v[24:27]
	v_mfma_f32_16x16x32_bf16 v[8:11], v[136:139], v[196:199], v[8:11]
	v_mfma_f32_16x16x32_bf16 v[8:11], v[140:143], v[200:203], v[8:11]
	v_mfma_f32_16x16x32_bf16 v[16:19], v[132:135], v[200:203], v[16:19]
	v_mfma_f32_16x16x32_bf16 v[16:19], v[128:131], v[196:199], v[16:19]
	s_barrier
	s_add_u32 s48, s22, 0x100000
	s_addc_u32 s49, s23, 0
	s_add_i32 s47, s43, s34
	s_mov_b32 m0, s47
	s_nop 0
	global_load_lds_dwordx4 v162, s[48:49]
	s_add_i32 m0, s47, 0x2000
	s_nop 0
	global_load_lds_dwordx4 v166, s[48:49]
	s_waitcnt vmcnt(6)
	s_barrier
; #define PG8_STAGE(bufoff, gbase, voff) do { _Pragma("unroll") for (int _i = 0; _i < 2; ++_i) \
;         __builtin_amdgcn_global_load_lds((const unsigned*)((const char*)(gbase) + (voff)[_i]), (LAS unsigned*)(lds + (bufoff) + ldsw + _i * 8192), 16, 0, 0); } while (0)
; #define PG8_LDA(dst, b, h) do { _Pragma("unroll") for (int m = 0; m < 4; ++m) _Pragma("unroll") for (int k = 0; k < 2; ++k) dst[m][k] = *(const LAS bf16x8*)(lds + PG8_SA(b, h) + aoff + m * 2048 + k * 1024); } while (0)
; #define PG8_LDB(dst, b, h) do { _Pragma("unroll") for (int n = 0; n < 2; ++n) _Pragma("unroll") for (int k = 0; k < 2; ++k) dst[n][k] = *(const LAS bf16x8*)(lds + PG8_SB(b, h) + boff + n * 2048 + k * 1024); } while (0)
; #define PG8_MMA(ai, bj, At, Bt) do { __builtin_amdgcn_s_setprio(1); _Pragma("unroll") for (int m = 0; m < 4; ++m) _Pragma("unroll") for (int n = 0; n < 2; ++n) _Pragma("unroll") for (int k = 0; k < 2; ++k) \
;         acc[ai][bj][m][n] = __builtin_amdgcn_mfma_f32_16x16x32_bf16(Bt[n][k], At[m][k], acc[ai][bj][m][n], 0, 0, 0); __builtin_amdgcn_s_setprio(0); } while (0)
; #define PG8_WAIT_V(n) asm volatile("s_waitcnt vmcnt(" #n ")" ::: "memory")
; #define PG8_WAIT_L(n) asm volatile("s_waitcnt lgkmcnt(" #n ")" ::: "memory")
; #define PG8_BAR __builtin_amdgcn_s_barrier()
; #define PG8_SCHED __builtin_amdgcn_sched_barrier(0)
; template <class Epi, class Ptrs>
; __device__ __forceinline__ void gemm_phase(LAS unsigned char* lds, const int K, const StaticOrder& S, const Ptrs& P, const Epi& E) {
;     ...
;             PG8_WAIT_V(6); PG8_BAR; PG8_MMA(1, 1, At, B1); PG8_BAR;
;             PG8_LDB(B0, 1, 0); PG8_SCHED; PG8_LDA(At, 1, 0); PG8_STAGE(PG8_SA(0, 1), a2 + hstep, voffA);
;             PG8_WAIT_L(8); PG8_BAR; PG8_WAIT_L(0); PG8_MMA(0, 0, At, B0); PG8_BAR; PG8_SCHED;
;             PG8_LDB(B1, 1, 1); PG8_STAGE(PG8_SB(1, 0), b3, voffB);
;             PG8_BAR; PG8_WAIT_L(0); PG8_MMA(0, 1, At, B1); PG8_BAR;
;             PG8_LDA(At, 1, 1); PG8_STAGE(PG8_SA(1, 0), a3, voffA);
	v_mfma_f32_16x16x32_bf16 v[52:55], v[204:207], v[144:147], v[52:55]
	v_mfma_f32_16x16x32_bf16 v[52:55], v[208:211], v[148:151], v[52:55]
	v_mfma_f32_16x16x32_bf16 v[44:47], v[216:219], v[148:151], v[44:47]
	v_mfma_f32_16x16x32_bf16 v[44:47], v[212:215], v[144:147], v[44:47]
	v_mfma_f32_16x16x32_bf16 v[28:31], v[212:215], v[152:155], v[28:31]
	v_mfma_f32_16x16x32_bf16 v[28:31], v[216:219], v[156:159], v[28:31]
	v_mfma_f32_16x16x32_bf16 v[36:39], v[208:211], v[156:159], v[36:39]
	v_mfma_f32_16x16x32_bf16 v[36:39], v[204:207], v[152:155], v[36:39]
	v_mfma_f32_16x16x32_bf16 v[20:23], v[204:207], v[176:179], v[20:23]
	v_mfma_f32_16x16x32_bf16 v[20:23], v[208:211], v[180:183], v[20:23]
	v_mfma_f32_16x16x32_bf16 v[12:15], v[216:219], v[180:183], v[12:15]
	v_mfma_f32_16x16x32_bf16 v[12:15], v[212:215], v[176:179], v[12:15]
	v_mfma_f32_16x16x32_bf16 v[0:3], v[212:215], v[196:199], v[0:3]
	v_mfma_f32_16x16x32_bf16 v[0:3], v[216:219], v[200:203], v[0:3]
	v_mfma_f32_16x16x32_bf16 v[4:7], v[208:211], v[200:203], v[4:7]
	v_mfma_f32_16x16x32_bf16 v[4:7], v[204:207], v[196:199], v[4:7]
	s_add_i32 s47, 0, 0x18000
	v_add_u32_e32 v140, s47, v187
	s_barrier
	ds_read_b128 v[128:131], v140
	ds_read_b128 v[132:135], v140 offset:1024
	ds_read_b128 v[136:139], v140 offset:2048
	ds_read_b128 v[140:143], v140 offset:3072
	s_add_u32 s24, s24, 0x100000
	s_addc_u32 s25, s25, 0
	s_mov_b32 m0, s40
	ds_read_b128 v[144:147], v194 offset:32768
	ds_read_b128 v[148:151], v194 offset:33792
	ds_read_b128 v[152:155], v194 offset:34816
	ds_read_b128 v[156:159], v194 offset:35840
	ds_read_b128 v[176:179], v194 offset:36864
	ds_read_b128 v[180:183], v194 offset:37888
	ds_read_b128 v[196:199], v194 offset:38912
	ds_read_b128 v[200:203], v194 offset:39936
	global_load_lds_dwordx4 v160, s[24:25]
	s_mov_b32 m0, s41
	s_nop 0
	global_load_lds_dwordx4 v164, s[24:25]
	s_waitcnt lgkmcnt(8)
	s_barrier
	s_waitcnt lgkmcnt(0)
	s_waitcnt lgkmcnt(0)
	v_mfma_f32_16x16x32_bf16 v[124:127], v[128:131], v[144:147], v[124:127]
	v_mfma_f32_16x16x32_bf16 v[124:127], v[132:135], v[148:151], v[124:127]
	v_mfma_f32_16x16x32_bf16 v[120:123], v[140:143], v[148:151], v[120:123]
	v_mfma_f32_16x16x32_bf16 v[120:123], v[136:139], v[144:147], v[120:123]
	v_mfma_f32_16x16x32_bf16 v[104:107], v[136:139], v[152:155], v[104:107]
	v_mfma_f32_16x16x32_bf16 v[104:107], v[140:143], v[156:159], v[104:107]
	v_mfma_f32_16x16x32_bf16 v[112:115], v[132:135], v[156:159], v[112:115]
	v_mfma_f32_16x16x32_bf16 v[112:115], v[128:131], v[152:155], v[112:115]
	v_mfma_f32_16x16x32_bf16 v[92:95], v[128:131], v[176:179], v[92:95]
	v_mfma_f32_16x16x32_bf16 v[92:95], v[132:135], v[180:183], v[92:95]
	v_mfma_f32_16x16x32_bf16 v[88:91], v[140:143], v[180:183], v[88:91]
	v_mfma_f32_16x16x32_bf16 v[88:91], v[136:139], v[176:179], v[88:91]
	v_mfma_f32_16x16x32_bf16 v[72:75], v[136:139], v[196:199], v[72:75]
	v_mfma_f32_16x16x32_bf16 v[72:75], v[140:143], v[200:203], v[72:75]
	v_mfma_f32_16x16x32_bf16 v[76:79], v[132:135], v[200:203], v[76:79]
	v_mfma_f32_16x16x32_bf16 v[76:79], v[128:131], v[196:199], v[76:79]
	s_barrier
	s_add_i32 s24, 0, 0x1c000
	s_add_i32 s25, s47, s34
	v_add_u32_e32 v216, s24, v187
	v_lshl_add_u64 v[184:185], v[184:185], 0, s[8:9]
	s_mov_b32 m0, s25
	ds_read_b128 v[204:207], v216
	ds_read_b128 v[208:211], v216 offset:1024
	ds_read_b128 v[212:215], v216 offset:2048
	ds_read_b128 v[216:219], v216 offset:3072
	global_load_lds_dwordx4 v[184:185], off
	v_lshl_add_u64 v[184:185], v[220:221], 0, s[8:9]
	s_add_i32 m0, s25, 0x2000
	s_nop 0
	global_load_lds_dwordx4 v[184:185], off
	s_barrier
	s_waitcnt lgkmcnt(0)
	s_waitcnt lgkmcnt(0)
	v_mfma_f32_16x16x32_bf16 v[116:119], v[204:207], v[144:147], v[116:119]
	v_mfma_f32_16x16x32_bf16 v[116:119], v[208:211], v[148:151], v[116:119]
	v_mfma_f32_16x16x32_bf16 v[108:111], v[216:219], v[148:151], v[108:111]
	v_mfma_f32_16x16x32_bf16 v[108:111], v[212:215], v[144:147], v[108:111]
	v_mfma_f32_16x16x32_bf16 v[96:99], v[212:215], v[152:155], v[96:99]
	v_mfma_f32_16x16x32_bf16 v[96:99], v[216:219], v[156:159], v[96:99]
	v_mfma_f32_16x16x32_bf16 v[100:103], v[208:211], v[156:159], v[100:103]
	v_mfma_f32_16x16x32_bf16 v[100:103], v[204:207], v[152:155], v[100:103]
	v_mfma_f32_16x16x32_bf16 v[84:87], v[204:207], v[176:179], v[84:87]
	v_mfma_f32_16x16x32_bf16 v[84:87], v[208:211], v[180:183], v[84:87]
	v_mfma_f32_16x16x32_bf16 v[80:83], v[216:219], v[180:183], v[80:83]
	v_mfma_f32_16x16x32_bf16 v[80:83], v[212:215], v[176:179], v[80:83]
	v_mfma_f32_16x16x32_bf16 v[64:67], v[212:215], v[196:199], v[64:67]
	v_mfma_f32_16x16x32_bf16 v[64:67], v[216:219], v[200:203], v[64:67]
	v_mfma_f32_16x16x32_bf16 v[68:71], v[208:211], v[200:203], v[68:71]
	v_mfma_f32_16x16x32_bf16 v[68:71], v[204:207], v[196:199], v[68:71]
	s_mov_b32 m0, s28
	v_lshl_add_u64 v[184:185], v[222:223], 0, s[8:9]
	s_barrier
	ds_read_b128 v[144:147], v194 offset:49152
	ds_read_b128 v[148:151], v194 offset:50176
	ds_read_b128 v[152:155], v194 offset:51200
	ds_read_b128 v[156:159], v194 offset:52224
	ds_read_b128 v[176:179], v194 offset:53248
	ds_read_b128 v[180:183], v194 offset:54272
	ds_read_b128 v[196:199], v194 offset:55296
	ds_read_b128 v[200:203], v194 offset:56320
	global_load_lds_dwordx4 v[184:185], off
	v_lshl_add_u64 v[184:185], v[224:225], 0, s[8:9]
	s_mov_b32 m0, s29
	s_nop 0
	global_load_lds_dwordx4 v[184:185], off
	s_barrier
; #define PG8_STAGE(bufoff, gbase, voff) do { _Pragma("unroll") for (int _i = 0; _i < 2; ++_i) \
;         __builtin_amdgcn_global_load_lds((const unsigned*)((const char*)(gbase) + (voff)[_i]), (LAS unsigned*)(lds + (bufoff) + ldsw + _i * 8192), 16, 0, 0); } while (0)
; #define PG8_LDA(dst, b, h) do { _Pragma("unroll") for (int m = 0; m < 4; ++m) _Pragma("unroll") for (int k = 0; k < 2; ++k) dst[m][k] = *(const LAS bf16x8*)(lds + PG8_SA(b, h) + aoff + m * 2048 + k * 1024); } while (0)
; #define PG8_MMA(ai, bj, At, Bt) do { __builtin_amdgcn_s_setprio(1); _Pragma("unroll") for (int m = 0; m < 4; ++m) _Pragma("unroll") for (int n = 0; n < 2; ++n) _Pragma("unroll") for (int k = 0; k < 2; ++k) \
;         acc[ai][bj][m][n] = __builtin_amdgcn_mfma_f32_16x16x32_bf16(Bt[n][k], At[m][k], acc[ai][bj][m][n], 0, 0, 0); __builtin_amdgcn_s_setprio(0); } while (0)
; #define PG8_WAIT_V(n) asm volatile("s_waitcnt vmcnt(" #n ")" ::: "memory")
; #define PG8_WAIT_L(n) asm volatile("s_waitcnt lgkmcnt(" #n ")" ::: "memory")
; #define PG8_BAR __builtin_amdgcn_s_barrier()
; #define PG8_SCHED __builtin_amdgcn_sched_barrier(0)
; template <class Epi, class Ptrs>
; __device__ __forceinline__ void gemm_phase(LAS unsigned char* lds, const int K, const StaticOrder& S, const Ptrs& P, const Epi& E) {
;     ...
;             PG8_BAR; PG8_WAIT_L(0); PG8_MMA(0, 1, At, B1); PG8_BAR;
;             PG8_LDA(At, 1, 1); PG8_STAGE(PG8_SA(1, 0), a3, voffA);
;             PG8_BAR; PG8_WAIT_L(0); PG8_MMA(1, 0, At, B0); PG8_BAR; PG8_SCHED;
;             PG8_STAGE(PG8_SB(1, 1), b3 + hstep, voffB);
;             PG8_WAIT_V(6); PG8_BAR; PG8_MMA(1, 1, At, B1); PG8_BAR;
;     __device__ __forceinline__ void operator()(const f32x4 (&acc)[2][2][4][2], const Unit& u, int ui, int wr, int wc, int fr, int fq) const {
;         const int rl0 = wr * 64 + fr, col0 = u.pn * 256 + wc * 32 + 8 * fq;
;         u32x4 xv[2][4][2];
; #pragma unroll
;         for (int ai = 0; ai < 2; ++ai)
; #pragma unroll
;             for (int m = 0; m < 4; ++m)
; #pragma unroll
;                 for (int bj = 0; bj < 2; ++bj) xv[ai][m][bj] = *(const u32x4*)(xb + (size_t)(u.pm * 256 + rl0 + ai * 128 + m * 16) * DM + col0 + bj * 128);
	s_waitcnt lgkmcnt(0)
	s_waitcnt lgkmcnt(0)
	v_mfma_f32_16x16x32_bf16 v[60:63], v[128:131], v[144:147], v[60:63]
	v_mfma_f32_16x16x32_bf16 v[60:63], v[132:135], v[148:151], v[60:63]
	v_mfma_f32_16x16x32_bf16 v[56:59], v[140:143], v[148:151], v[56:59]
	v_mfma_f32_16x16x32_bf16 v[56:59], v[136:139], v[144:147], v[56:59]
	v_mfma_f32_16x16x32_bf16 v[40:43], v[136:139], v[152:155], v[40:43]
	v_mfma_f32_16x16x32_bf16 v[40:43], v[140:143], v[156:159], v[40:43]
	v_mfma_f32_16x16x32_bf16 v[48:51], v[132:135], v[156:159], v[48:51]
	v_mfma_f32_16x16x32_bf16 v[48:51], v[128:131], v[152:155], v[48:51]
	v_mfma_f32_16x16x32_bf16 v[32:35], v[128:131], v[176:179], v[32:35]
	v_mfma_f32_16x16x32_bf16 v[32:35], v[132:135], v[180:183], v[32:35]
	v_mfma_f32_16x16x32_bf16 v[24:27], v[140:143], v[180:183], v[24:27]
	v_mfma_f32_16x16x32_bf16 v[24:27], v[136:139], v[176:179], v[24:27]
	v_mfma_f32_16x16x32_bf16 v[8:11], v[136:139], v[196:199], v[8:11]
	v_mfma_f32_16x16x32_bf16 v[8:11], v[140:143], v[200:203], v[8:11]
	v_mfma_f32_16x16x32_bf16 v[16:19], v[132:135], v[200:203], v[16:19]
	v_mfma_f32_16x16x32_bf16 v[16:19], v[128:131], v[196:199], v[16:19]
	s_barrier
	s_add_u32 s22, s22, 0x100080
	s_addc_u32 s23, s23, 0
	s_add_i32 s24, s24, s34
	s_mov_b32 m0, s24
	s_nop 0
	global_load_lds_dwordx4 v162, s[22:23]
	s_add_i32 m0, s24, 0x2000
	s_nop 0
	global_load_lds_dwordx4 v166, s[22:23]
	s_waitcnt vmcnt(6)
	s_barrier
	v_mfma_f32_16x16x32_bf16 v[52:55], v[204:207], v[144:147], v[52:55]
	v_mfma_f32_16x16x32_bf16 v[52:55], v[208:211], v[148:151], v[52:55]
	v_mfma_f32_16x16x32_bf16 v[44:47], v[216:219], v[148:151], v[44:47]
	v_mfma_f32_16x16x32_bf16 v[44:47], v[212:215], v[144:147], v[44:47]
	v_mfma_f32_16x16x32_bf16 v[28:31], v[212:215], v[152:155], v[28:31]
	v_mfma_f32_16x16x32_bf16 v[28:31], v[216:219], v[156:159], v[28:31]
	v_mfma_f32_16x16x32_bf16 v[36:39], v[208:211], v[156:159], v[36:39]
	v_mfma_f32_16x16x32_bf16 v[36:39], v[204:207], v[152:155], v[36:39]
	v_mfma_f32_16x16x32_bf16 v[20:23], v[204:207], v[176:179], v[20:23]
	v_mfma_f32_16x16x32_bf16 v[20:23], v[208:211], v[180:183], v[20:23]
	v_mfma_f32_16x16x32_bf16 v[12:15], v[216:219], v[180:183], v[12:15]
	v_mfma_f32_16x16x32_bf16 v[12:15], v[212:215], v[176:179], v[12:15]
	v_mfma_f32_16x16x32_bf16 v[0:3], v[212:215], v[196:199], v[0:3]
	v_mfma_f32_16x16x32_bf16 v[0:3], v[216:219], v[200:203], v[0:3]
	v_mfma_f32_16x16x32_bf16 v[4:7], v[208:211], v[200:203], v[4:7]
	v_mfma_f32_16x16x32_bf16 v[4:7], v[204:207], v[196:199], v[4:7]
	s_add_i32 s46, s46, 2
	s_add_u32 s20, s20, 0x100
	s_addc_u32 s21, s21, 0
	s_add_u32 s11, s11, 0x100
	s_addc_u32 s13, s13, 0
	s_cmp_gt_u32 s46, 61
	s_barrier
	s_cbranch_scc0 .LBB0_522
	s_nop 0
	s_nop 0
	s_nop 0
	s_nop 0
	s_nop 0
	s_nop 0
	s_nop 0
	s_nop 0
	s_nop 0
	s_nop 0
	s_nop 0
	s_nop 0
	s_nop 0
	s_nop 0
	s_nop 0
	s_nop 0
	s_nop 0
	s_nop 0
	s_nop 0
	s_nop 0
	s_nop 0
	s_nop 0
	s_nop 0
	s_nop 0
	s_nop 0
	s_nop 0
	s_nop 0
	s_nop 0
	s_nop 0
	s_lshl_b32 s11, s18, 8
	v_lshl_or_b32 v128, s16, 8, v191
	v_add_u32_e32 v130, s11, v186
	v_ashrrev_i32_e32 v129, 31, v128
	v_ashrrev_i32_e32 v131, 31, v130
	v_lshl_add_u64 v[132:133], v[128:129], 1, s[6:7]
	v_lshlrev_b64 v[134:135], 11, v[130:131]
	v_lshl_add_u64 v[134:135], v[132:133], 0, v[134:135]
	global_load_dwordx4 v[198:201], v[134:135], off
	global_load_dwordx4 v[202:205], v[134:135], off offset:256
	v_or_b32_e32 v134, 16, v130
	v_ashrrev_i32_e32 v135, 31, v134
	v_lshlrev_b64 v[134:135], 11, v[134:135]
	v_lshl_add_u64 v[134:135], v[132:133], 0, v[134:135]
	global_load_dwordx4 v[206:209], v[134:135], off
	global_load_dwordx4 v[210:213], v[134:135], off offset:256
	v_or_b32_e32 v136, 32, v130
	v_ashrrev_i32_e32 v137, 31, v136
	v_or_b32_e32 v138, 48, v130
	v_add_u32_e32 v184, 0x80, v130
	v_add_u32_e32 v182, 0x90, v130
	v_add_u32_e32 v180, 0xa0, v130
	v_add_u32_e32 v178, 0xb0, v130
	v_lshlrev_b64 v[176:177], 2, v[128:129]
	v_lshlrev_b64 v[128:129], 12, v[130:131]
	v_lshlrev_b64 v[130:131], 11, v[136:137]
	v_lshl_add_u64 v[130:131], v[132:133], 0, v[130:131]
	global_load_dwordx4 v[214:217], v[130:131], off
	v_ashrrev_i32_e32 v139, 31, v138
	v_ashrrev_i32_e32 v185, 31, v184
	v_ashrrev_i32_e32 v183, 31, v182
	v_ashrrev_i32_e32 v181, 31, v180
	v_ashrrev_i32_e32 v179, 31, v178
	v_lshlrev_b64 v[134:135], 11, v[138:139]
	v_lshlrev_b64 v[136:137], 11, v[184:185]
	v_lshlrev_b64 v[138:139], 11, v[182:183]
	v_lshl_add_u32 v196, s45, 10, v192
	v_lshlrev_b64 v[140:141], 11, v[180:181]
	v_lshlrev_b64 v[142:143], 11, v[178:179]
	v_lshl_add_u64 v[128:129], s[26:27], 0, v[128:129]
	v_lshl_add_u64 v[134:135], v[132:133], 0, v[134:135]
	v_lshl_add_u64 v[136:137], v[132:133], 0, v[136:137]
	v_lshl_add_u64 v[138:139], v[132:133], 0, v[138:139]
	ds_read2_b32 v[230:231], v196 offset1:16
	v_lshl_add_u64 v[234:235], v[132:133], 0, v[140:141]
	v_lshl_add_u64 v[236:237], v[132:133], 0, v[142:143]
	v_lshl_add_u64 v[238:239], v[128:129], 0, v[176:177]
	global_load_dwordx4 v[218:221], v[130:131], off offset:256
	global_load_dwordx4 v[222:225], v[134:135], off
	global_load_dwordx4 v[226:229], v[134:135], off offset:256
	global_load_dwordx4 v[156:159], v[136:137], off
	global_load_dwordx4 v[152:155], v[136:137], off offset:256
	global_load_dwordx4 v[148:151], v[138:139], off
	global_load_dwordx4 v[144:147], v[138:139], off offset:256
	global_load_dwordx4 v[140:143], v[234:235], off
	s_nop 0
	global_load_dwordx4 v[136:139], v[234:235], off offset:256
	global_load_dwordx4 v[132:135], v[236:237], off
	global_load_dwordx4 v[128:131], v[236:237], off offset:256
	v_add_u32_e32 v232, s11, v188
	v_ashrrev_i32_e32 v233, 31, v232
	s_and_b64 vcc, exec, s[0:1]
	s_mov_b32 s16, s10
	s_mov_b32 s18, s12
	s_mov_b64 s[20:21], s[4:5]
	s_mov_b64 s[22:23], s[14:15]
	s_mov_b32 s45, s44
	s_waitcnt vmcnt(0)
; __device__ __forceinline__ float bf_lo(unsigned w) { return __uint_as_float(w << 16); }
; __device__ __forceinline__ float bf_hi(unsigned w) { return __uint_as_float(w & 0xffff0000u); }
;     __device__ __forceinline__ void operator()(const f32x4 (&acc)[2][2][4][2], const Unit& u, int ui, int wr, int wc, int fr, int fq) const {
;     ...
;             for (int m = 0; m < 4; ++m) { const int rl = rl0 + ai * 128 + m * 16; float* rowp = out + (size_t)(u.pm * 256 + rl) * DM + col0;
;                 const float r2 = tab[ui * 256 + rl];
; #pragma unroll
;                 for (int bj = 0; bj < 2; ++bj) { const u32x4 x = xv[ai][m][bj];
;                     const f32x4 x0 = {bf_lo(x.x), bf_hi(x.x), bf_lo(x.y), bf_hi(x.y)}, x1 = {bf_lo(x.z), bf_hi(x.z), bf_lo(x.w), bf_hi(x.w)};
;                     *(f32x4*)(rowp + bj * 128) = acc[ai][bj][m][0] * r2 + x0; *(f32x4*)(rowp + bj * 128 + 4) = acc[ai][bj][m][1] * r2 + x1; } }
	v_lshlrev_b32_e32 v234, 16, v198
	v_and_b32_e32 v235, 0xffff0000, v198
	v_lshlrev_b32_e32 v198, 16, v199
	v_and_b32_e32 v199, 0xffff0000, v199
	v_lshlrev_b32_e32 v242, 16, v204
	v_and_b32_e32 v243, 0xffff0000, v204
	v_lshlrev_b32_e32 v236, 16, v200
	v_and_b32_e32 v237, 0xffff0000, v200
	v_lshlrev_b32_e32 v200, 16, v201
	v_and_b32_e32 v201, 0xffff0000, v201
	v_lshlrev_b32_e32 v240, 16, v202
	v_and_b32_e32 v241, 0xffff0000, v202
	v_lshlrev_b32_e32 v202, 16, v203
	v_and_b32_e32 v203, 0xffff0000, v203
	v_lshlrev_b32_e32 v204, 16, v205
	v_and_b32_e32 v205, 0xffff0000, v205
	s_waitcnt lgkmcnt(0)
	v_pk_fma_f32 v[126:127], v[126:127], v[230:231], v[198:199] op_sel_hi:[1,0,1]
	v_pk_fma_f32 v[124:125], v[124:125], v[230:231], v[234:235] op_sel_hi:[1,0,1]
	v_pk_fma_f32 v[108:109], v[108:109], v[230:231], v[242:243] op_sel_hi:[1,0,1]
	v_pk_fma_f32 v[122:123], v[122:123], v[230:231], v[200:201] op_sel_hi:[1,0,1]
	v_pk_fma_f32 v[120:121], v[120:121], v[230:231], v[236:237] op_sel_hi:[1,0,1]
	v_pk_fma_f32 v[118:119], v[118:119], v[230:231], v[202:203] op_sel_hi:[1,0,1]
	v_pk_fma_f32 v[116:117], v[116:117], v[230:231], v[240:241] op_sel_hi:[1,0,1]
	v_pk_fma_f32 v[110:111], v[110:111], v[230:231], v[204:205] op_sel_hi:[1,0,1]
	global_store_dwordx4 v[238:239], v[124:127], off
	global_store_dwordx4 v[238:239], v[120:123], off offset:16
	global_store_dwordx4 v[238:239], v[116:119], off offset:512
	global_store_dwordx4 v[238:239], v[108:111], off offset:528
	v_mov_b32_e32 v122, v231
	v_lshlrev_b32_e32 v118, 16, v208
	v_lshlrev_b64 v[108:109], 12, v[232:233]
	v_lshl_add_u64 v[108:109], s[26:27], 0, v[108:109]
	v_lshl_add_u64 v[116:117], v[108:109], 0, v[176:177]
	v_lshlrev_b32_e32 v108, 16, v206
	v_and_b32_e32 v109, 0xffff0000, v206
	v_lshlrev_b32_e32 v110, 16, v207
	v_and_b32_e32 v111, 0xffff0000, v207
	v_pk_fma_f32 v[110:111], v[114:115], v[122:123], v[110:111] op_sel_hi:[1,0,1]
	v_pk_fma_f32 v[108:109], v[112:113], v[122:123], v[108:109] op_sel_hi:[1,0,1]
	global_store_dwordx4 v[116:117], v[108:111], off
	v_and_b32_e32 v119, 0xffff0000, v208
	v_lshlrev_b32_e32 v120, 16, v209
	v_lshlrev_b32_e32 v108, 16, v212
	v_and_b32_e32 v109, 0xffff0000, v212
	v_lshlrev_b32_e32 v110, 16, v213
	v_and_b32_e32 v111, 0xffff0000, v213
	v_pk_fma_f32 v[98:99], v[98:99], v[122:123], v[110:111] op_sel_hi:[1,0,1]
	v_pk_fma_f32 v[96:97], v[96:97], v[122:123], v[108:109] op_sel_hi:[1,0,1]
	v_and_b32_e32 v121, 0xffff0000, v209
	global_store_dwordx4 v[116:117], v[96:99], off offset:528
	ds_read2_b32 v[98:99], v196 offset0:32 offset1:48
	v_pk_fma_f32 v[106:107], v[106:107], v[122:123], v[120:121] op_sel_hi:[1,0,1]
	v_pk_fma_f32 v[104:105], v[104:105], v[122:123], v[118:119] op_sel_hi:[1,0,1]
	v_add_u32_e32 v96, s11, v189
	global_store_dwordx4 v[116:117], v[104:107], off offset:16
	v_ashrrev_i32_e32 v97, 31, v96
	v_lshlrev_b64 v[96:97], 12, v[96:97]
	v_lshlrev_b32_e32 v104, 16, v210
	v_and_b32_e32 v105, 0xffff0000, v210
	v_lshlrev_b32_e32 v106, 16, v211
	v_and_b32_e32 v107, 0xffff0000, v211
	v_pk_fma_f32 v[102:103], v[102:103], v[122:123], v[106:107] op_sel_hi:[1,0,1]
	v_pk_fma_f32 v[100:101], v[100:101], v[122:123], v[104:105] op_sel_hi:[1,0,1]
	global_store_dwordx4 v[116:117], v[100:103], off offset:512
	v_lshl_add_u64 v[96:97], s[26:27], 0, v[96:97]
	v_lshl_add_u64 v[96:97], v[96:97], 0, v[176:177]
	v_lshlrev_b32_e32 v100, 16, v214
	v_and_b32_e32 v101, 0xffff0000, v214
	v_lshlrev_b32_e32 v102, 16, v215
	v_and_b32_e32 v103, 0xffff0000, v215
	s_waitcnt lgkmcnt(0)
	v_pk_fma_f32 v[94:95], v[94:95], v[98:99], v[102:103] op_sel_hi:[1,0,1]
	v_pk_fma_f32 v[92:93], v[92:93], v[98:99], v[100:101] op_sel_hi:[1,0,1]
	global_store_dwordx4 v[96:97], v[92:95], off
	v_lshlrev_b32_e32 v104, 16, v216
	v_and_b32_e32 v105, 0xffff0000, v216
	v_lshlrev_b32_e32 v92, 16, v220
	v_and_b32_e32 v93, 0xffff0000, v220
	v_lshlrev_b32_e32 v94, 16, v221
	v_and_b32_e32 v95, 0xffff0000, v221
	v_lshlrev_b32_e32 v106, 16, v217
	v_and_b32_e32 v107, 0xffff0000, v217
	v_pk_fma_f32 v[82:83], v[82:83], v[98:99], v[94:95] op_sel_hi:[1,0,1]
	v_pk_fma_f32 v[80:81], v[80:81], v[98:99], v[92:93] op_sel_hi:[1,0,1]
	v_pk_fma_f32 v[90:91], v[90:91], v[98:99], v[106:107] op_sel_hi:[1,0,1]
	v_pk_fma_f32 v[88:89], v[88:89], v[98:99], v[104:105] op_sel_hi:[1,0,1]
	global_store_dwordx4 v[96:97], v[80:83], off offset:528
	global_store_dwordx4 v[96:97], v[88:91], off offset:16
	s_nop 0
	v_add_u32_e32 v80, s11, v190
	v_lshlrev_b32_e32 v88, 16, v218
	v_and_b32_e32 v89, 0xffff0000, v218
	v_lshlrev_b32_e32 v90, 16, v219
	v_and_b32_e32 v91, 0xffff0000, v219
	v_ashrrev_i32_e32 v81, 31, v80
	v_pk_fma_f32 v[86:87], v[86:87], v[98:99], v[90:91] op_sel_hi:[1,0,1]
	v_pk_fma_f32 v[84:85], v[84:85], v[98:99], v[88:89] op_sel_hi:[1,0,1]
	v_lshlrev_b64 v[80:81], 12, v[80:81]
	global_store_dwordx4 v[96:97], v[84:87], off offset:512
	v_lshl_add_u64 v[80:81], s[26:27], 0, v[80:81]
	v_lshlrev_b32_e32 v82, 16, v222
	v_and_b32_e32 v83, 0xffff0000, v222
	v_lshlrev_b32_e32 v84, 16, v223
	v_and_b32_e32 v85, 0xffff0000, v223
	v_mov_b32_e32 v90, v99
	v_lshl_add_u64 v[80:81], v[80:81], 0, v[176:177]
	v_pk_fma_f32 v[78:79], v[78:79], v[90:91], v[84:85] op_sel_hi:[1,0,1]
	v_pk_fma_f32 v[76:77], v[76:77], v[90:91], v[82:83] op_sel_hi:[1,0,1]
	global_store_dwordx4 v[80:81], v[76:79], off
	v_lshlrev_b32_e32 v86, 16, v224
	v_and_b32_e32 v87, 0xffff0000, v224
	v_lshlrev_b32_e32 v76, 16, v228
	v_and_b32_e32 v77, 0xffff0000, v228
	v_lshlrev_b32_e32 v78, 16, v229
	v_and_b32_e32 v79, 0xffff0000, v229
	v_pk_fma_f32 v[66:67], v[66:67], v[90:91], v[78:79] op_sel_hi:[1,0,1]
	v_pk_fma_f32 v[64:65], v[64:65], v[90:91], v[76:77] op_sel_hi:[1,0,1]
	v_lshlrev_b32_e32 v88, 16, v225
	v_and_b32_e32 v89, 0xffff0000, v225
	global_store_dwordx4 v[80:81], v[64:67], off offset:528
	ds_read2_b32 v[66:67], v196 offset0:128 offset1:144
	v_pk_fma_f32 v[74:75], v[74:75], v[90:91], v[88:89] op_sel_hi:[1,0,1]
	v_pk_fma_f32 v[72:73], v[72:73], v[90:91], v[86:87] op_sel_hi:[1,0,1]
	global_store_dwordx4 v[80:81], v[72:75], off offset:16
	v_lshlrev_b64 v[64:65], 12, v[184:185]
	v_lshl_add_u64 v[64:65], s[26:27], 0, v[64:65]
	v_lshlrev_b32_e32 v72, 16, v226
	v_and_b32_e32 v73, 0xffff0000, v226
	v_lshlrev_b32_e32 v74, 16, v227
	v_and_b32_e32 v75, 0xffff0000, v227
	v_pk_fma_f32 v[70:71], v[70:71], v[90:91], v[74:75] op_sel_hi:[1,0,1]
	v_pk_fma_f32 v[68:69], v[68:69], v[90:91], v[72:73] op_sel_hi:[1,0,1]
	global_store_dwordx4 v[80:81], v[68:71], off offset:512
	v_lshl_add_u64 v[64:65], v[64:65], 0, v[176:177]
	v_lshlrev_b32_e32 v72, 16, v158
	v_lshlrev_b32_e32 v68, 16, v156
	v_and_b32_e32 v69, 0xffff0000, v156
	v_lshlrev_b32_e32 v70, 16, v157
	v_and_b32_e32 v71, 0xffff0000, v157
	v_and_b32_e32 v73, 0xffff0000, v158
	v_lshlrev_b32_e32 v74, 16, v159
	v_and_b32_e32 v75, 0xffff0000, v159
	s_waitcnt lgkmcnt(0)
; __device__ __forceinline__ float bf_lo(unsigned w) { return __uint_as_float(w << 16); }
; __device__ __forceinline__ float bf_hi(unsigned w) { return __uint_as_float(w & 0xffff0000u); }
; #define PG8_WAIT_V(n) asm volatile("s_waitcnt vmcnt(" #n ")" ::: "memory")
; #define PG8_BAR __builtin_amdgcn_s_barrier()
; template <class Epi, class Ptrs>
; __device__ __forceinline__ void gemm_phase(LAS unsigned char* lds, const int K, const StaticOrder& S, const Ptrs& P, const Epi& E) {
;     ...
;     PG8_WAIT_V(0);
;     if (wr == 0) PG8_BAR;
;     __device__ __forceinline__ void operator()(const f32x4 (&acc)[2][2][4][2], const Unit& u, int ui, int wr, int wc, int fr, int fq) const {
;     ...
;             for (int m = 0; m < 4; ++m) { const int rl = rl0 + ai * 128 + m * 16; float* rowp = out + (size_t)(u.pm * 256 + rl) * DM + col0;
;                 const float r2 = tab[ui * 256 + rl];
; #pragma unroll
;                 for (int bj = 0; bj < 2; ++bj) { const u32x4 x = xv[ai][m][bj];
;                     const f32x4 x0 = {bf_lo(x.x), bf_hi(x.x), bf_lo(x.y), bf_hi(x.y)}, x1 = {bf_lo(x.z), bf_hi(x.z), bf_lo(x.w), bf_hi(x.w)};
;                     *(f32x4*)(rowp + bj * 128) = acc[ai][bj][m][0] * r2 + x0; *(f32x4*)(rowp + bj * 128 + 4) = acc[ai][bj][m][1] * r2 + x1; } }
	v_pk_fma_f32 v[62:63], v[62:63], v[66:67], v[70:71] op_sel_hi:[1,0,1]
	v_pk_fma_f32 v[60:61], v[60:61], v[66:67], v[68:69] op_sel_hi:[1,0,1]
	global_store_dwordx4 v[64:65], v[60:63], off
	v_pk_fma_f32 v[58:59], v[58:59], v[66:67], v[74:75] op_sel_hi:[1,0,1]
	v_pk_fma_f32 v[56:57], v[56:57], v[66:67], v[72:73] op_sel_hi:[1,0,1]
	v_lshlrev_b32_e32 v60, 16, v154
	v_and_b32_e32 v61, 0xffff0000, v154
	v_lshlrev_b32_e32 v62, 16, v155
	v_and_b32_e32 v63, 0xffff0000, v155
	global_store_dwordx4 v[64:65], v[56:59], off offset:16
	v_pk_fma_f32 v[46:47], v[46:47], v[66:67], v[62:63] op_sel_hi:[1,0,1]
	v_pk_fma_f32 v[44:45], v[44:45], v[66:67], v[60:61] op_sel_hi:[1,0,1]
	v_lshlrev_b32_e32 v56, 16, v152
	v_and_b32_e32 v57, 0xffff0000, v152
	v_lshlrev_b32_e32 v58, 16, v153
	v_and_b32_e32 v59, 0xffff0000, v153
	v_pk_fma_f32 v[54:55], v[54:55], v[66:67], v[58:59] op_sel_hi:[1,0,1]
	v_pk_fma_f32 v[52:53], v[52:53], v[66:67], v[56:57] op_sel_hi:[1,0,1]
	global_store_dwordx4 v[64:65], v[44:47], off offset:528
	global_store_dwordx4 v[64:65], v[52:55], off offset:512
	v_lshlrev_b32_e32 v56, 16, v151
	v_lshlrev_b64 v[44:45], 12, v[182:183]
	v_lshl_add_u64 v[44:45], s[26:27], 0, v[44:45]
	v_lshlrev_b32_e32 v54, 16, v150
	v_and_b32_e32 v55, 0xffff0000, v150
	v_and_b32_e32 v57, 0xffff0000, v151
	v_mov_b32_e32 v58, v67
	v_lshl_add_u64 v[52:53], v[44:45], 0, v[176:177]
	v_pk_fma_f32 v[42:43], v[42:43], v[58:59], v[56:57] op_sel_hi:[1,0,1]
	v_pk_fma_f32 v[40:41], v[40:41], v[58:59], v[54:55] op_sel_hi:[1,0,1]
	v_lshlrev_b32_e32 v44, 16, v148
	v_and_b32_e32 v45, 0xffff0000, v148
	v_lshlrev_b32_e32 v46, 16, v149
	v_and_b32_e32 v47, 0xffff0000, v149
	global_store_dwordx4 v[52:53], v[40:43], off offset:16
	v_pk_fma_f32 v[46:47], v[50:51], v[58:59], v[46:47] op_sel_hi:[1,0,1]
	v_pk_fma_f32 v[44:45], v[48:49], v[58:59], v[44:45] op_sel_hi:[1,0,1]
	v_lshlrev_b32_e32 v40, 16, v144
	v_and_b32_e32 v41, 0xffff0000, v144
	v_lshlrev_b32_e32 v42, 16, v145
	v_and_b32_e32 v43, 0xffff0000, v145
	v_pk_fma_f32 v[38:39], v[38:39], v[58:59], v[42:43] op_sel_hi:[1,0,1]
	v_pk_fma_f32 v[36:37], v[36:37], v[58:59], v[40:41] op_sel_hi:[1,0,1]
	global_store_dwordx4 v[52:53], v[44:47], off
	global_store_dwordx4 v[52:53], v[36:39], off offset:512
	ds_read2_b32 v[38:39], v196 offset0:160 offset1:176
	v_lshlrev_b32_e32 v44, 16, v146
	v_and_b32_e32 v45, 0xffff0000, v146
	v_lshlrev_b32_e32 v46, 16, v147
	v_and_b32_e32 v47, 0xffff0000, v147
	v_pk_fma_f32 v[30:31], v[30:31], v[58:59], v[46:47] op_sel_hi:[1,0,1]
	v_pk_fma_f32 v[28:29], v[28:29], v[58:59], v[44:45] op_sel_hi:[1,0,1]
	global_store_dwordx4 v[52:53], v[28:31], off offset:528
	v_lshlrev_b32_e32 v40, 16, v142
	v_and_b32_e32 v41, 0xffff0000, v142
	v_lshlrev_b64 v[28:29], 12, v[180:181]
	v_lshl_add_u64 v[28:29], s[26:27], 0, v[28:29]
	v_lshl_add_u64 v[36:37], v[28:29], 0, v[176:177]
	v_lshlrev_b32_e32 v28, 16, v140
	v_and_b32_e32 v29, 0xffff0000, v140
	v_lshlrev_b32_e32 v30, 16, v141
	v_and_b32_e32 v31, 0xffff0000, v141
	s_waitcnt lgkmcnt(0)
	v_pk_fma_f32 v[30:31], v[34:35], v[38:39], v[30:31] op_sel_hi:[1,0,1]
	v_pk_fma_f32 v[28:29], v[32:33], v[38:39], v[28:29] op_sel_hi:[1,0,1]
	v_lshlrev_b32_e32 v42, 16, v143
	v_and_b32_e32 v43, 0xffff0000, v143
	global_store_dwordx4 v[36:37], v[28:31], off
	v_pk_fma_f32 v[26:27], v[26:27], v[38:39], v[42:43] op_sel_hi:[1,0,1]
	v_pk_fma_f32 v[24:25], v[24:25], v[38:39], v[40:41] op_sel_hi:[1,0,1]
	v_lshlrev_b32_e32 v28, 16, v138
	v_and_b32_e32 v29, 0xffff0000, v138
	v_lshlrev_b32_e32 v30, 16, v139
	v_and_b32_e32 v31, 0xffff0000, v139
	v_pk_fma_f32 v[14:15], v[14:15], v[38:39], v[30:31] op_sel_hi:[1,0,1]
	v_pk_fma_f32 v[12:13], v[12:13], v[38:39], v[28:29] op_sel_hi:[1,0,1]
	global_store_dwordx4 v[36:37], v[24:27], off offset:16
	global_store_dwordx4 v[36:37], v[12:15], off offset:528
	s_nop 0
	v_lshlrev_b32_e32 v24, 16, v136
	v_and_b32_e32 v25, 0xffff0000, v136
	v_lshlrev_b32_e32 v26, 16, v137
	v_and_b32_e32 v27, 0xffff0000, v137
	v_lshlrev_b64 v[12:13], 12, v[178:179]
	v_pk_fma_f32 v[22:23], v[22:23], v[38:39], v[26:27] op_sel_hi:[1,0,1]
	v_pk_fma_f32 v[20:21], v[20:21], v[38:39], v[24:25] op_sel_hi:[1,0,1]
	v_lshl_add_u64 v[12:13], s[26:27], 0, v[12:13]
	global_store_dwordx4 v[36:37], v[20:23], off offset:512
	v_lshlrev_b32_e32 v14, 16, v133
	v_and_b32_e32 v15, 0xffff0000, v133
	v_lshl_add_u64 v[20:21], v[12:13], 0, v[176:177]
	v_lshlrev_b32_e32 v12, 16, v132
	v_and_b32_e32 v13, 0xffff0000, v132
	v_lshlrev_b32_e32 v22, 16, v134
	v_and_b32_e32 v23, 0xffff0000, v134
	v_lshlrev_b32_e32 v24, 16, v135
	v_and_b32_e32 v25, 0xffff0000, v135
	v_mov_b32_e32 v26, v39
	v_pk_fma_f32 v[14:15], v[18:19], v[26:27], v[14:15] op_sel_hi:[1,0,1]
	v_pk_fma_f32 v[12:13], v[16:17], v[26:27], v[12:13] op_sel_hi:[1,0,1]
	v_pk_fma_f32 v[10:11], v[10:11], v[26:27], v[24:25] op_sel_hi:[1,0,1]
	v_pk_fma_f32 v[8:9], v[8:9], v[26:27], v[22:23] op_sel_hi:[1,0,1]
	global_store_dwordx4 v[20:21], v[12:15], off
	global_store_dwordx4 v[20:21], v[8:11], off offset:16
	s_nop 0
	v_lshlrev_b32_e32 v12, 16, v130
	v_lshlrev_b32_e32 v8, 16, v128
	v_and_b32_e32 v9, 0xffff0000, v128
	v_lshlrev_b32_e32 v10, 16, v129
	v_and_b32_e32 v11, 0xffff0000, v129
	v_and_b32_e32 v13, 0xffff0000, v130
	v_lshlrev_b32_e32 v14, 16, v131
	v_and_b32_e32 v15, 0xffff0000, v131
	v_pk_fma_f32 v[6:7], v[6:7], v[26:27], v[10:11] op_sel_hi:[1,0,1]
	v_pk_fma_f32 v[4:5], v[4:5], v[26:27], v[8:9] op_sel_hi:[1,0,1]
	v_pk_fma_f32 v[2:3], v[2:3], v[26:27], v[14:15] op_sel_hi:[1,0,1]
	v_pk_fma_f32 v[0:1], v[0:1], v[26:27], v[12:13] op_sel_hi:[1,0,1]
	global_store_dwordx4 v[20:21], v[4:7], off offset:512
	global_store_dwordx4 v[20:21], v[0:3], off offset:528
	s_cbranch_vccz .LBB0_517
	s_waitcnt vmcnt(0)
	s_setprio 0
	s_cmpk_gt_u32 s33, 0xff
	s_cbranch_scc1 .LBB0_526
	s_barrier
